# NSA sel/window softmax: running-max reference folded into the preloaded bias regs during the QK MFMAs (16 v_sub per half-tile removed from the issue stream; rescale test/rare path adjusted), on top of
# speedup vs baseline: 1.0042x; 1.0042x over previous
; #define NSA_RESET()                                                                         \
;   _Pragma("unroll") for (int r = 0; r < 2; ++r) { asm volatile("v_mov_b32 %0, 0xf149f2ca" : "=v"(m[r])); l[r] = 0.f; }               \
;   _Pragma("unroll") for (int df = 0; df < 4; ++df) _Pragma("unroll") for (int r = 0; r < 2; ++r) O[df][r] = zero4();
; __device__ __forceinline__ void nsa_item(const Params& P, int b, int g, int c, const bf16_t* z, const bf16_t* kcv, bf16_t* y, char* lds) {
;     ...
;     NSA_RESET();
;     int zg;
;     if (br == 0) {
;       nsa_branch<2>(0, 0, U, z + tokb * LDZ + ZC_KS + g * 64, z + tokb * LDZ + ZC_VS + g * 64, LDZ, t, hp * 2, mymask, Qf, O, m, l, inv, impw, lds);
;       zg = ZC_GS;
;     } else {
;       const int kt0 = c > 8 ? c - 8 : 0;
;       nsa_branch<3>(kt0, c - kt0 + 1, 0ull, z + tokb * LDZ + ZC_KW + g * 64, z + tokb * LDZ + ZC_VW + g * 64, LDZ, t, hp * 2, 0ull, Qf, O, m, l, inv, impw, lds);
.LBB0_348:
	s_xor_b64 s[0:1], s[0:1], -1
	s_and_b64 vcc, exec, s[0:1]
	s_mov_b64 s[30:31], -1
	v_mov_b32 v188, 0xf149f2ca
	v_mov_b32 v189, 0xf149f2ca
	v_mov_b32_e32 v230, 0
	v_mov_b32_e32 v231, 0
	v_mov_b32 v16, 0
	v_mov_b32 v17, 0
	v_mov_b32 v18, 0
	v_mov_b32 v19, 0
	v_mov_b32 v20, 0
	v_mov_b32 v21, 0
	v_mov_b32 v22, 0
	v_mov_b32 v23, 0
	v_mov_b32 v24, 0
	v_mov_b32 v25, 0
	v_mov_b32 v26, 0
	v_mov_b32 v27, 0
	v_mov_b32 v28, 0
	v_mov_b32 v29, 0
	v_mov_b32 v30, 0
	v_mov_b32 v31, 0
	v_mov_b32 v32, 0
	v_mov_b32 v33, 0
	v_mov_b32 v34, 0
	v_mov_b32 v35, 0
	v_mov_b32 v36, 0
	v_mov_b32 v37, 0
	v_mov_b32 v38, 0
	v_mov_b32 v39, 0
	v_mov_b32 v40, 0
	v_mov_b32 v41, 0
	v_mov_b32 v42, 0
	v_mov_b32 v43, 0
	v_mov_b32 v44, 0
	v_mov_b32 v45, 0
	v_mov_b32 v46, 0
	v_mov_b32 v47, 0
	s_cbranch_vccz .LBB0_424
	v_cndmask_b32_e64 v48, 0, 1, s[38:39]
	v_cmp_ne_u32_e64 s[36:37], 1, v48
	s_andn2_b64 vcc, exec, s[38:39]
	s_cbranch_vccnz .LBB0_351
	v_readlane_b32 s16, v255, 12
	v_readlane_b32 s17, v255, 13
	v_mov_b32 v50, v179
	s_nop 0
	v_ashrrev_i32_e32 v52, 3, v50
	v_mov_b64_e32 v[48:49], s[16:17]
	v_mad_i64_i32 v[48:49], s[16:17], v52, s61, v[48:49]
	v_readlane_b32 s16, v255, 14
	v_lshlrev_b32_e32 v50, 4, v50
	v_readlane_b32 s17, v255, 15
	v_and_b32_e32 v176, 0x70, v50
	v_lshl_add_u64 v[48:49], v[48:49], 0, v[176:177]
	v_mov_b64_e32 v[50:51], s[16:17]
	v_mad_i64_i32 v[50:51], s[16:17], v52, s61, v[50:51]
	v_lshl_add_u64 v[52:53], v[50:51], 0, v[176:177]
	global_load_dwordx4 v[48:51], v[48:49], off
	s_nop 0
	global_load_dwordx4 v[52:55], v[52:53], off

; template <int MODE>
; __device__ __forceinline__ void nsa_compute(int cur, int buf, int t, int hl, u64 mymask, const bf16x8 (&Qf)[2][2], f32x4 (&O)[4][2], float (&m)[2], float (&l)[2],
;                                             const float (&inv)[2], float* impw, char* lds) {
;     ...
;   for (int s2 = 0; s2 < 2; ++s2) {
;     f32x4 S[2][2] = {};
;     bf16x8 kfr[2][2];
; #pragma unroll
;     for (int ks = 0; ks < 2; ++ks)
; #pragma unroll
;       for (int kk = 0; kk < 2; ++kk) kfr[ks][kk] = *(const bf16x8*)(kt + (32 * s2 + 16 * kk + fr) * 128 + (((ks * 4 + fq) ^ (fr & 7)) << 4));
;     __builtin_amdgcn_s_setprio(1);
; #pragma unroll
;     for (int ks = 0; ks < 2; ++ks)
; #pragma unroll
;       for (int kk = 0; kk < 2; ++kk)
; #pragma unroll
;         for (int r = 0; r < 2; ++r) S[kk][r] = mfma16(kfr[ks][kk], Qf[r][ks], S[kk][r]);
;     __builtin_amdgcn_s_setprio(0);
;     bf16x8 Pf[2];
;     float g1s[2] = {0.f, 0.f}, p3s[2] = {0.f, 0.f};
; #pragma unroll
;     for (int r = 0; r < 2; ++r) {
;       float sv[2][4];
; #pragma unroll
;       for (int kk = 0; kk < 2; ++kk)
; #pragma unroll
;         for (int e = 0; e < 4; ++e) {
;           const int off = 32 * s2 + 16 * kk + e;
;           int idx;
;           if (MODE <= 1) { idx = base - 16 * off; idx = idx > 0 ? idx : 0; } else idx = base - off;
;           sv[kk][e] = S[kk][r][e] * (0.125f * LOG2E) + tb[r * TS + idx];
;         }
;       float pv[2][4];
;       if (MODE == 1) {
; #pragma unroll
;         for (int kk = 0; kk < 2; ++kk)
; #pragma unroll
;           for (int e = 0; e < 4; ++e) pv[kk][e] = __builtin_amdgcn_exp2f(sv[kk][e] - m[r]) * inv[r];
; #pragma unroll
;         for (int kk = 0; kk < 2; ++kk) { g1s[kk] += pv[kk][0] + pv[kk][1] + pv[kk][2] + 0.5f * pv[kk][3]; p3s[kk] += 0.5f * pv[kk][3]; }
;       } else {
;         const float mxa = fmaxf(fmaxf(sv[0][0], sv[0][1]), sv[0][2]), mxb = fmaxf(fmaxf(sv[0][3], sv[1][0]), sv[1][1]);
;         float mx = fmaxf(fmaxf(fmaxf(sv[1][2], sv[1][3]), mxa), mxb);
;         if (MODE == 2) mx = selok ? mx : -__builtin_inff();
;         if (__any(mx > m[r] + 8.0f)) {
;           mx = fmaxf(mx, __shfl_xor(mx, 16)); mx = fmaxf(mx, __shfl_xor(mx, 32));
;           const float mn = fmaxf(m[r], mx), al = __builtin_amdgcn_exp2f(m[r] - mn);
;           m[r] = mn; l[r] *= al;
;           if (MODE != 0) {
; #pragma unroll
.LBB0_361:
	v_mov_b32 v72, v179
	s_lshl_b32 s64, s46, 13
	v_lshrrev_b32_e32 v73, 4, v72
	v_bfe_u32 v80, v72, 4, 2
	v_and_b32_e32 v81, 7, v72
	v_and_b32_e32 v92, 15, v72
	v_lshlrev_b32_e32 v93, 2, v80
	v_bitop3_b32 v72, v73, v81, 3 bitop3:0x6c
	v_bitop3_b32 v80, v80, v81, 4 bitop3:0x36
	v_lshlrev_b32_e32 v90, 7, v92
	v_lshl_or_b32 v91, v72, 4, s64
	v_lshl_or_b32 v100, v80, 4, s64
	v_or_b32_e32 v76, v91, v90
	v_or_b32_e32 v84, v100, v90
	ds_read_b128 v[72:75], v76
	ds_read_b128 v[76:79], v76 offset:2048
	ds_read_b128 v[80:83], v84
	ds_read_b128 v[84:87], v84 offset:2048
	s_mov_b32 s17, s74
	s_mov_b32 s74, s73
	v_sub_u32_e32 v251, v180, v93
	v_lshl_add_u32 v251, v251, 2, v235
	s_lshl_b32 s17, s17, 8
	v_subrev_u32_e32 v250, s17, v251
	v_add_u32_e32 v249, 0xa00, v250
	ds_read2_b32 v[98:99], v250 offset0:63 offset1:64
	ds_read2_b32 v[102:103], v250 offset0:61 offset1:62
	ds_read2_b32 v[168:169], v250 offset0:47 offset1:48
	ds_read2_b32 v[170:171], v250 offset0:45 offset1:46
	ds_read2_b32 v[172:173], v249 offset0:63 offset1:64
	ds_read2_b32 v[174:175], v249 offset0:61 offset1:62
	ds_read2_b32 v[194:195], v249 offset0:47 offset1:48
	ds_read2_b32 v[198:199], v249 offset0:45 offset1:46
	s_setprio 1
	s_waitcnt lgkmcnt(11)
	v_mfma_f32_16x16x32_bf16 v[94:97], v[72:75], v[0:3], 0
	v_mfma_f32_16x16x32_bf16 v[72:75], v[72:75], v[8:11], 0
	s_waitcnt lgkmcnt(10)
	v_mfma_f32_16x16x32_bf16 v[140:143], v[76:79], v[8:11], 0
	v_mfma_f32_16x16x32_bf16 v[136:139], v[76:79], v[0:3], 0
	s_waitcnt lgkmcnt(9)
	v_mfma_f32_16x16x32_bf16 v[94:97], v[80:83], v[4:7], v[94:97]
	v_mfma_f32_16x16x32_bf16 v[76:79], v[80:83], v[12:15], v[72:75]
	s_waitcnt lgkmcnt(8)
	v_mfma_f32_16x16x32_bf16 v[72:75], v[84:87], v[12:15], v[140:143]
	v_mfma_f32_16x16x32_bf16 v[144:147], v[84:87], v[4:7], v[136:139]
	s_setprio 0
	s_waitcnt lgkmcnt(4)
	v_sub_f32_e32 v99, v99, v230
	v_sub_f32_e32 v98, v98, v230
	v_sub_f32_e32 v103, v103, v230
	v_sub_f32_e32 v102, v102, v230
	v_sub_f32_e32 v169, v169, v230
	v_sub_f32_e32 v168, v168, v230
	v_sub_f32_e32 v171, v171, v230
	v_sub_f32_e32 v170, v170, v230
	s_waitcnt lgkmcnt(0)
	v_sub_f32_e32 v173, v173, v231
	v_sub_f32_e32 v172, v172, v231
	v_sub_f32_e32 v175, v175, v231
	v_sub_f32_e32 v174, v174, v231
	v_sub_f32_e32 v195, v195, v231
	v_sub_f32_e32 v194, v194, v231
	v_sub_f32_e32 v199, v199, v231
	v_sub_f32_e32 v198, v198, v231
	v_sub_u32_e32 v80, v180, v93
	v_lshl_add_u32 v80, v80, 2, v235
	v_subrev_u32_e32 v136, s17, v80
	s_waitcnt lgkmcnt(7)
	v_fmamk_f32 v94, v94, 0x3e38aa3b, v99
	v_fmamk_f32 v86, v95, 0x3e38aa3b, v98
	s_waitcnt lgkmcnt(6)
	v_fmamk_f32 v87, v96, 0x3e38aa3b, v103
	v_fmamk_f32 v84, v97, 0x3e38aa3b, v102
	s_waitcnt lgkmcnt(5)
	v_fmamk_f32 v81, v144, 0x3e38aa3b, v169
	v_fmamk_f32 v80, v145, 0x3e38aa3b, v168
	s_waitcnt lgkmcnt(4)
	v_fmamk_f32 v83, v146, 0x3e38aa3b, v171
	v_fmamk_f32 v82, v147, 0x3e38aa3b, v170
	v_max3_f32 v85, v94, v86, v87
	v_max3_f32 v88, v84, v81, v80
	v_max_f32_e32 v89, v83, v82
	v_max3_f32 v85, v89, v85, v88
	v_sub_f32_e32 v88, v192, v230
	v_add_f32_e32 v88, 0x41000000, v88
	v_cmp_gt_f32_e32 vcc, v85, v88
	s_cbranch_vccz .LBB0_363
	v_add_f32_e32 v85, v85, v230
	ds_bpermute_b32 v88, v233, v85
	v_max_f32_e32 v85, v85, v85
	v_mov_b32_e32 v89, v193
	s_waitcnt lgkmcnt(0)
	v_max_f32_e32 v88, v88, v88
	v_max_f32_e32 v85, v85, v88
	ds_bpermute_b32 v88, v234, v85
	s_waitcnt lgkmcnt(0)
	v_max3_f32 v88, v192, v85, v88
	v_sub_f32_e32 v85, v192, v88
	v_exp_f32_e32 v96, v85
	v_mov_b64_e32 v[192:193], v[88:89]
	v_mul_f32_e32 v190, v190, v96
	v_pk_mul_f32 v[118:119], v[118:119], v[96:97] op_sel_hi:[1,0]
	v_pk_mul_f32 v[116:117], v[116:117], v[96:97] op_sel_hi:[1,0]
	v_pk_mul_f32 v[126:127], v[126:127], v[96:97] op_sel_hi:[1,0]
	v_pk_mul_f32 v[124:125], v[124:125], v[96:97] op_sel_hi:[1,0]
	v_pk_mul_f32 v[130:131], v[130:131], v[96:97] op_sel_hi:[1,0]
	v_pk_mul_f32 v[128:129], v[128:129], v[96:97] op_sel_hi:[1,0]
	v_pk_mul_f32 v[134:135], v[134:135], v[96:97] op_sel_hi:[1,0]
	v_pk_mul_f32 v[132:133], v[132:133], v[96:97] op_sel_hi:[1,0]
	v_cmp_lt_f32_e32 vcc, 0xefa18f08, v88
	s_nop 1
	v_cndmask_b32_e32 v232, 0, v88, vcc
	v_sub_f32_e32 v230, v232, v230
	v_sub_f32_e32 v94, v94, v230
	v_sub_f32_e32 v86, v86, v230
	v_sub_f32_e32 v87, v87, v230
	v_sub_f32_e32 v84, v84, v230
	v_sub_f32_e32 v81, v81, v230
	v_sub_f32_e32 v80, v80, v230
	v_sub_f32_e32 v83, v83, v230
	v_sub_f32_e32 v82, v82, v230
	v_mov_b32_e32 v230, v232
	s_branch .LBB0_364
.LBB0_363:
.LBB0_364:
	v_exp_f32_e32 v85, v94
	v_exp_f32_e32 v86, v86
	v_exp_f32_e32 v87, v87
	v_exp_f32_e32 v84, v84
	v_add_f32_e32 v89, 0, v85
	v_add_f32_e32 v89, v86, v89
	v_add_f32_e32 v89, v87, v89
	v_add_f32_e32 v94, v84, v89
	v_exp_f32_e32 v89, v81
	s_nop 0
	v_add_f32_e32 v81, v89, v94
	v_exp_f32_e32 v94, v80
	s_nop 0
	v_add_f32_e32 v80, v94, v81
	v_exp_f32_e32 v95, v83
	v_exp_f32_e32 v88, v82
	v_add_f32_e32 v80, v95, v80
	v_add_f32_e32 v80, v88, v80
	v_add_f32_e32 v190, v190, v80
	s_waitcnt lgkmcnt(3)
	v_fmamk_f32 v81, v76, 0x3e38aa3b, v173
	v_fmamk_f32 v80, v77, 0x3e38aa3b, v172
	s_waitcnt lgkmcnt(2)
	v_fmamk_f32 v78, v78, 0x3e38aa3b, v175
	v_fmamk_f32 v82, v79, 0x3e38aa3b, v174
	s_waitcnt lgkmcnt(1)
	v_fmamk_f32 v77, v72, 0x3e38aa3b, v195
	v_fmamk_f32 v76, v73, 0x3e38aa3b, v194
	s_waitcnt lgkmcnt(0)
	v_fmamk_f32 v73, v74, 0x3e38aa3b, v199
	v_fmamk_f32 v72, v75, 0x3e38aa3b, v198
	v_max3_f32 v74, v81, v80, v78
	v_max3_f32 v75, v82, v77, v76
	v_max_f32_e32 v79, v73, v72
	v_max3_f32 v74, v79, v74, v75
	v_sub_f32_e32 v75, v193, v231
	v_add_f32_e32 v75, 0x41000000, v75
	v_cmp_gt_f32_e32 vcc, v74, v75
	s_cbranch_vccz .LBB0_366
	v_add_f32_e32 v74, v74, v231
	ds_bpermute_b32 v75, v233, v74
	v_max_f32_e32 v74, v74, v74
	s_waitcnt lgkmcnt(0)
	v_max_f32_e32 v75, v75, v75
	v_max_f32_e32 v74, v74, v75
	ds_bpermute_b32 v75, v234, v74
	s_waitcnt lgkmcnt(0)
	v_max3_f32 v74, v193, v74, v75
	v_sub_f32_e32 v75, v193, v74
	v_exp_f32_e32 v96, v75
	v_mov_b32_e32 v193, v74
	v_mul_f32_e32 v191, v191, v96
	v_pk_mul_f32 v[106:107], v[106:107], v[96:97] op_sel_hi:[1,0]
	v_pk_mul_f32 v[104:105], v[104:105], v[96:97] op_sel_hi:[1,0]
	v_pk_mul_f32 v[110:111], v[110:111], v[96:97] op_sel_hi:[1,0]
	v_pk_mul_f32 v[108:109], v[108:109], v[96:97] op_sel_hi:[1,0]
	v_pk_mul_f32 v[114:115], v[114:115], v[96:97] op_sel_hi:[1,0]
	v_pk_mul_f32 v[112:113], v[112:113], v[96:97] op_sel_hi:[1,0]
	v_pk_mul_f32 v[122:123], v[122:123], v[96:97] op_sel_hi:[1,0]
	v_pk_mul_f32 v[120:121], v[120:121], v[96:97] op_sel_hi:[1,0]
	v_cmp_lt_f32_e32 vcc, 0xefa18f08, v74
	s_nop 1
	v_cndmask_b32_e32 v232, 0, v74, vcc
	v_sub_f32_e32 v231, v232, v231
	v_sub_f32_e32 v81, v81, v231
	v_sub_f32_e32 v80, v80, v231
	v_sub_f32_e32 v78, v78, v231
	v_sub_f32_e32 v82, v82, v231
	v_sub_f32_e32 v77, v77, v231
	v_sub_f32_e32 v76, v76, v231
	v_sub_f32_e32 v73, v73, v231
	v_sub_f32_e32 v72, v72, v231
	v_mov_b32_e32 v231, v232
	s_branch .LBB0_367
; template <int MODE>
; __device__ __forceinline__ void nsa_compute(int cur, int buf, int t, int hl, u64 mymask, const bf16x8 (&Qf)[2][2], f32x4 (&O)[4][2], float (&m)[2], float (&l)[2],
;                                             const float (&inv)[2], float* impw, char* lds) {
;     ...
; #pragma unroll
;     for (int ks = 0; ks < 2; ++ks)
; #pragma unroll
;       for (int kk = 0; kk < 2; ++kk) kfr[ks][kk] = *(const bf16x8*)(kt + (32 * s2 + 16 * kk + fr) * 128 + (((ks * 4 + fq) ^ (fr & 7)) << 4));
;     __builtin_amdgcn_s_setprio(1);
; #pragma unroll
;     for (int ks = 0; ks < 2; ++ks)
; #pragma unroll
;       for (int kk = 0; kk < 2; ++kk)
; #pragma unroll
;         for (int r = 0; r < 2; ++r) S[kk][r] = mfma16(kfr[ks][kk], Qf[r][ks], S[kk][r]);
;     __builtin_amdgcn_s_setprio(0);
;     bf16x8 Pf[2];
;     float g1s[2] = {0.f, 0.f}, p3s[2] = {0.f, 0.f};
; #pragma unroll
;     for (int r = 0; r < 2; ++r) {
;       float sv[2][4];
; #pragma unroll
;       for (int kk = 0; kk < 2; ++kk)
; #pragma unroll
;         for (int e = 0; e < 4; ++e) {
;     ...
;         const float me = (MODE == 2) ? (selok ? m[r] : __builtin_inff()) : m[r];
;         float ps = 0.f;
; #pragma unroll
;         for (int kk = 0; kk < 2; ++kk)
; #pragma unroll
;           for (int e = 0; e < 4; ++e) { pv[kk][e] = __builtin_amdgcn_exp2f(sv[kk][e] - me); ps += pv[kk][e]; }
;         l[r] += ps;
;       }
;       if (MODE != 0) {
;         const unsigned w0 = pk2(pv[0][0], pv[0][1]), w1 = pk2(pv[0][2], pv[0][3]), w2 = pk2(pv[1][0], pv[1][1]), w3 = pk2(pv[1][2], pv[1][3]);
;         u32x4 pw; pw.x = w0; pw.y = w1; pw.z = w2; pw.w = w3;
;         Pf[r] = __builtin_bit_cast(bf16x8, pw);
;       }
;     }
;     if (MODE != 0) {
;       bf16x8 vfr[4];
; #pragma unroll
;       for (int df = 0; df < 4; ++df) {
;         const bf16x4 va = *(const bf16x4*)(vt + (df * 16 + fr) * 68 + 32 * s2 + 4 * fq);
;         const bf16x4 vb = *(const bf16x4*)(vt + (df * 16 + fr) * 68 + 32 * s2 + 16 + 4 * fq);
;         bf16x8 vf; vf[0] = va[0]; vf[1] = va[1]; vf[2] = va[2]; vf[3] = va[3]; vf[4] = vb[0]; vf[5] = vb[1]; vf[6] = vb[2]; vf[7] = vb[3];
;         vfr[df] = vf;
;       }
;       __builtin_amdgcn_s_setprio(1);
; #pragma unroll
;       for (int df = 0; df < 4; ++df)
; #pragma unroll
;         for (int r = 0; r < 2; ++r) O[df][r] = mfma16(vfr[df], Pf[r], O[df][r]);
;       __builtin_amdgcn_s_setprio(0);
.LBB0_366:
.LBB0_367:
	v_exp_f32_e32 v75, v81
	v_exp_f32_e32 v80, v80
	v_exp_f32_e32 v78, v78
	v_exp_f32_e32 v81, v82
	v_add_f32_e32 v79, 0, v75
	v_exp_f32_e32 v77, v77
	v_add_f32_e32 v79, v80, v79
	v_exp_f32_e32 v76, v76
	v_add_f32_e32 v79, v78, v79
	v_exp_f32_e32 v73, v73
	v_add_f32_e32 v79, v81, v79
	v_exp_f32_e32 v72, v72
	v_add_f32_e32 v79, v77, v79
	v_add_f32_e32 v79, v76, v79
	v_add_f32_e32 v79, v73, v79
	s_lshl_b32 s17, s46, 9
	v_add_f32_e32 v74, v72, v79
	v_cvt_pk_bf16_f32 v149, v73, v72
	v_mul_u32_u24_e32 v72, 0x44, v92
	s_add_i32 s43, s64, s17
	v_lshlrev_b32_e32 v72, 1, v72
	v_lshlrev_b32_e32 v73, 1, v93
	v_cvt_pk_bf16_f32 v146, v75, v80
	v_add3_u32 v80, s43, v72, v73
	v_add_u32_e32 v137, 0x4000, v80
	v_add_u32_e32 v138, 0x4800, v80
	v_add_f32_e32 v191, v191, v74
	v_cvt_pk_bf16_f32 v147, v78, v81
	v_cvt_pk_bf16_f32 v148, v77, v76
	ds_read2_b64 v[72:75], v137 offset1:4
	ds_read2_b64 v[76:79], v138 offset0:16 offset1:20
	v_add_u32_e32 v139, 0x5000, v80
	v_add_u32_e32 v140, 0x5800, v80
	ds_read2_b64 v[150:153], v139 offset0:32 offset1:36
	ds_read2_b64 v[154:157], v140 offset0:48 offset1:52
	v_cvt_pk_bf16_f32 v142, v85, v86
	v_cvt_pk_bf16_f32 v143, v87, v84
	v_cvt_pk_bf16_f32 v144, v89, v94
	v_cvt_pk_bf16_f32 v145, v95, v88
	s_setprio 1
	s_waitcnt lgkmcnt(3)
	v_mfma_f32_16x16x32_bf16 v[84:87], v[72:75], v[142:145], v[116:119]
	v_mfma_f32_16x16x32_bf16 v[96:99], v[72:75], v[146:149], v[104:107]
	s_waitcnt lgkmcnt(2)
	v_mfma_f32_16x16x32_bf16 v[80:83], v[76:79], v[142:145], v[124:127]
	v_mfma_f32_16x16x32_bf16 v[92:95], v[76:79], v[146:149], v[108:111]
	s_waitcnt lgkmcnt(1)
	v_mfma_f32_16x16x32_bf16 v[76:79], v[150:153], v[142:145], v[128:131]
	v_mfma_f32_16x16x32_bf16 v[108:111], v[150:153], v[146:149], v[112:115]
	s_waitcnt lgkmcnt(0)
	v_mfma_f32_16x16x32_bf16 v[72:75], v[154:157], v[142:145], v[132:135]
	v_mfma_f32_16x16x32_bf16 v[104:107], v[154:157], v[146:149], v[120:123]
	s_setprio 0
	v_add_u32_e32 v88, v91, v90
	v_add_u32_e32 v100, v100, v90
	ds_read_b128 v[112:115], v88 offset:4096
	ds_read_b128 v[116:119], v88 offset:6144
	ds_read_b128 v[88:91], v100 offset:4096
	ds_read_b128 v[120:123], v100 offset:6144
	v_add_u32_e32 v251, 0xa00, v136
	ds_read2_b32 v[168:169], v136 offset0:31 offset1:32
	ds_read2_b32 v[170:171], v136 offset0:29 offset1:30
	ds_read2_b32 v[172:173], v136 offset0:15 offset1:16
	ds_read2_b32 v[174:175], v136 offset0:13 offset1:14
	ds_read2_b32 v[198:199], v251 offset0:31 offset1:32
	ds_read2_b32 v[200:201], v251 offset0:29 offset1:30
	ds_read2_b32 v[202:203], v251 offset0:15 offset1:16
	ds_read2_b32 v[204:205], v251 offset0:13 offset1:14
	s_setprio 1
	s_waitcnt lgkmcnt(11)
	v_mfma_f32_16x16x32_bf16 v[100:103], v[112:115], v[0:3], 0
	v_mfma_f32_16x16x32_bf16 v[112:115], v[112:115], v[8:11], 0
	s_waitcnt lgkmcnt(10)
	v_mfma_f32_16x16x32_bf16 v[124:127], v[116:119], v[0:3], 0
	v_mfma_f32_16x16x32_bf16 v[116:119], v[116:119], v[8:11], 0
	s_waitcnt lgkmcnt(9)
	v_mfma_f32_16x16x32_bf16 v[128:131], v[88:91], v[4:7], v[100:103]
	v_mfma_f32_16x16x32_bf16 v[100:103], v[88:91], v[12:15], v[112:115]
	s_waitcnt lgkmcnt(8)
	v_mfma_f32_16x16x32_bf16 v[88:91], v[120:123], v[12:15], v[116:119]
	v_mfma_f32_16x16x32_bf16 v[124:127], v[120:123], v[4:7], v[124:127]
	s_setprio 0
	s_waitcnt lgkmcnt(4)
	v_sub_f32_e32 v169, v169, v230
	v_sub_f32_e32 v168, v168, v230
	v_sub_f32_e32 v171, v171, v230
	v_sub_f32_e32 v170, v170, v230
	v_sub_f32_e32 v173, v173, v230
	v_sub_f32_e32 v172, v172, v230
	v_sub_f32_e32 v175, v175, v230
	v_sub_f32_e32 v174, v174, v230
	s_waitcnt lgkmcnt(0)
	v_sub_f32_e32 v199, v199, v231
	v_sub_f32_e32 v198, v198, v231
	v_sub_f32_e32 v201, v201, v231
	v_sub_f32_e32 v200, v200, v231
	v_sub_f32_e32 v203, v203, v231
	v_sub_f32_e32 v202, v202, v231
	v_sub_f32_e32 v205, v205, v231
	v_sub_f32_e32 v204, v204, v231
	s_nop 0
	s_waitcnt lgkmcnt(7)
	s_nop 0
	v_fmamk_f32 v123, v128, 0x3e38aa3b, v169
	v_fmamk_f32 v118, v129, 0x3e38aa3b, v168
	s_waitcnt lgkmcnt(6)
	v_fmamk_f32 v122, v130, 0x3e38aa3b, v171
	v_fmamk_f32 v116, v131, 0x3e38aa3b, v170
	s_waitcnt lgkmcnt(5)
	v_fmamk_f32 v119, v124, 0x3e38aa3b, v173
	v_fmamk_f32 v114, v125, 0x3e38aa3b, v172
	s_waitcnt lgkmcnt(4)
	v_fmamk_f32 v113, v126, 0x3e38aa3b, v175
	v_fmamk_f32 v112, v127, 0x3e38aa3b, v174
	v_max3_f32 v115, v123, v118, v122
	v_max3_f32 v117, v116, v119, v114
	v_max_f32_e32 v120, v113, v112
	v_max3_f32 v115, v120, v115, v117
	v_sub_f32_e32 v117, v192, v230
	v_add_f32_e32 v117, 0x41000000, v117
	v_cmp_gt_f32_e32 vcc, v115, v117
	s_cbranch_vccz .LBB0_369
	v_add_f32_e32 v115, v115, v230
	ds_bpermute_b32 v117, v233, v115
	v_max_f32_e32 v115, v115, v115
	v_mov_b32_e32 v121, v193
	s_waitcnt lgkmcnt(0)
	v_max_f32_e32 v117, v117, v117
	v_max_f32_e32 v115, v115, v117
	ds_bpermute_b32 v117, v234, v115
	s_waitcnt lgkmcnt(0)
	v_max3_f32 v120, v192, v115, v117
	v_sub_f32_e32 v115, v192, v120
	v_exp_f32_e32 v124, v115
	v_mov_b64_e32 v[192:193], v[120:121]
	v_mul_f32_e32 v190, v190, v124
	v_pk_mul_f32 v[86:87], v[86:87], v[124:125] op_sel_hi:[1,0]
	v_pk_mul_f32 v[84:85], v[84:85], v[124:125] op_sel_hi:[1,0]
	v_pk_mul_f32 v[82:83], v[82:83], v[124:125] op_sel_hi:[1,0]
	v_pk_mul_f32 v[80:81], v[80:81], v[124:125] op_sel_hi:[1,0]
	v_pk_mul_f32 v[78:79], v[78:79], v[124:125] op_sel_hi:[1,0]
	v_pk_mul_f32 v[76:77], v[76:77], v[124:125] op_sel_hi:[1,0]
	v_pk_mul_f32 v[74:75], v[74:75], v[124:125] op_sel_hi:[1,0]
	v_pk_mul_f32 v[72:73], v[72:73], v[124:125] op_sel_hi:[1,0]
	v_cmp_lt_f32_e32 vcc, 0xefa18f08, v120
	s_nop 1
	v_cndmask_b32_e32 v232, 0, v120, vcc
	v_sub_f32_e32 v230, v232, v230
	v_sub_f32_e32 v123, v123, v230
	v_sub_f32_e32 v118, v118, v230
	v_sub_f32_e32 v122, v122, v230
	v_sub_f32_e32 v116, v116, v230
	v_sub_f32_e32 v119, v119, v230
	v_sub_f32_e32 v114, v114, v230
	v_sub_f32_e32 v113, v113, v230
	v_sub_f32_e32 v112, v112, v230
	v_mov_b32_e32 v230, v232
	s_branch .LBB0_370
; template <int MODE>
; __device__ __forceinline__ void nsa_compute(int cur, int buf, int t, int hl, u64 mymask, const bf16x8 (&Qf)[2][2], f32x4 (&O)[4][2], float (&m)[2], float (&l)[2],
;                                             const float (&inv)[2], float* impw, char* lds) {
;     ...
;         const float mxa = fmaxf(fmaxf(sv[0][0], sv[0][1]), sv[0][2]), mxb = fmaxf(fmaxf(sv[0][3], sv[1][0]), sv[1][1]);
;         float mx = fmaxf(fmaxf(fmaxf(sv[1][2], sv[1][3]), mxa), mxb);
;         if (MODE == 2) mx = selok ? mx : -__builtin_inff();
;         if (__any(mx > m[r] + 8.0f)) {
;           mx = fmaxf(mx, __shfl_xor(mx, 16)); mx = fmaxf(mx, __shfl_xor(mx, 32));
;           const float mn = fmaxf(m[r], mx), al = __builtin_amdgcn_exp2f(m[r] - mn);
;           m[r] = mn; l[r] *= al;
;           if (MODE != 0) {
; #pragma unroll
;             for (int df = 0; df < 4; ++df) O[df][r] *= al;
;           }
;         }
;         const float me = (MODE == 2) ? (selok ? m[r] : __builtin_inff()) : m[r];
;         float ps = 0.f;
; #pragma unroll
;         for (int kk = 0; kk < 2; ++kk)
; #pragma unroll
;           for (int e = 0; e < 4; ++e) { pv[kk][e] = __builtin_amdgcn_exp2f(sv[kk][e] - me); ps += pv[kk][e]; }
;         l[r] += ps;
.LBB0_369:
.LBB0_370:
	v_exp_f32_e32 v115, v123
	v_exp_f32_e32 v117, v118
	v_exp_f32_e32 v118, v122
	v_exp_f32_e32 v116, v116
	v_add_f32_e32 v121, 0, v115
	v_exp_f32_e32 v119, v119
	v_add_f32_e32 v121, v117, v121
	v_exp_f32_e32 v114, v114
	v_add_f32_e32 v121, v118, v121
	v_add_f32_e32 v121, v116, v121
	v_add_f32_e32 v121, v119, v121
	v_add_f32_e32 v122, v114, v121
	v_exp_f32_e32 v121, v113
	v_exp_f32_e32 v120, v112
	v_add_f32_e32 v113, v121, v122
	v_add_f32_e32 v112, v120, v113
	v_add_f32_e32 v190, v190, v112
	s_waitcnt lgkmcnt(3)
	v_fmamk_f32 v113, v100, 0x3e38aa3b, v199
	v_fmamk_f32 v112, v101, 0x3e38aa3b, v198
	s_waitcnt lgkmcnt(2)
	v_fmamk_f32 v101, v102, 0x3e38aa3b, v201
	v_fmamk_f32 v100, v103, 0x3e38aa3b, v200
	s_waitcnt lgkmcnt(1)
	v_fmamk_f32 v103, v88, 0x3e38aa3b, v203
	v_fmamk_f32 v102, v89, 0x3e38aa3b, v202
	s_waitcnt lgkmcnt(0)
	v_fmamk_f32 v89, v90, 0x3e38aa3b, v205
	v_fmamk_f32 v88, v91, 0x3e38aa3b, v204
	v_max3_f32 v90, v113, v112, v101
	v_max3_f32 v91, v100, v103, v102
	v_max_f32_e32 v122, v89, v88
	v_max3_f32 v90, v122, v90, v91
	v_sub_f32_e32 v91, v193, v231
	v_add_f32_e32 v91, 0x41000000, v91
	v_cmp_gt_f32_e32 vcc, v90, v91
	s_cbranch_vccz .LBB0_372
	v_add_f32_e32 v90, v90, v231
	ds_bpermute_b32 v91, v233, v90
	v_max_f32_e32 v90, v90, v90
	s_waitcnt lgkmcnt(0)
	v_max_f32_e32 v91, v91, v91
	v_max_f32_e32 v90, v90, v91
	ds_bpermute_b32 v91, v234, v90
	s_waitcnt lgkmcnt(0)
	v_max3_f32 v90, v193, v90, v91
	v_sub_f32_e32 v91, v193, v90
	v_exp_f32_e32 v122, v91
	v_mov_b32_e32 v193, v90
	v_mul_f32_e32 v191, v191, v122
	v_pk_mul_f32 v[98:99], v[98:99], v[122:123] op_sel_hi:[1,0]
	v_pk_mul_f32 v[96:97], v[96:97], v[122:123] op_sel_hi:[1,0]
	v_pk_mul_f32 v[94:95], v[94:95], v[122:123] op_sel_hi:[1,0]
	v_pk_mul_f32 v[92:93], v[92:93], v[122:123] op_sel_hi:[1,0]
	v_pk_mul_f32 v[110:111], v[110:111], v[122:123] op_sel_hi:[1,0]
	v_pk_mul_f32 v[108:109], v[108:109], v[122:123] op_sel_hi:[1,0]
	v_pk_mul_f32 v[106:107], v[106:107], v[122:123] op_sel_hi:[1,0]
	v_pk_mul_f32 v[104:105], v[104:105], v[122:123] op_sel_hi:[1,0]
	v_mov_b64_e32 v[194:195], v[190:191]
	v_cmp_lt_f32_e32 vcc, 0xefa18f08, v90
	s_nop 1
	v_cndmask_b32_e32 v232, 0, v90, vcc
	v_sub_f32_e32 v231, v232, v231
	v_sub_f32_e32 v113, v113, v231
	v_sub_f32_e32 v112, v112, v231
	v_sub_f32_e32 v101, v101, v231
	v_sub_f32_e32 v100, v100, v231
	v_sub_f32_e32 v103, v103, v231
	v_sub_f32_e32 v102, v102, v231
	v_sub_f32_e32 v89, v89, v231
	v_sub_f32_e32 v88, v88, v231
	v_mov_b32_e32 v231, v232
	s_branch .LBB0_373

; #define TIDX opaque_tid()
; __device__ __forceinline__ unsigned pk2(float lo, float hi) { const f32x2v v = {lo, hi}; const bf16x2v r = __builtin_convertvector(v, bf16x2v); return __builtin_bit_cast(unsigned, r); }
; __device__ __forceinline__ void kv_lwrite(const KVRegs& r, char* lds, int buf) {
;   const int tid = TIDX, row = tid >> 3, cq = tid & 7;
;   char* kt = lds + NSA_KT + buf * 8192 + row * 128;
;   *(u32x4*)(kt + ((cq ^ (row & 7)) << 4)) = r.k0;
;   bf16_t* vt = (bf16_t*)(lds + NSA_VT + buf * 8704) + (cq * 8) * 68 + row;
; #pragma unroll
;   for (int i = 0; i < 4; ++i) { vt[(2 * i) * 68] = (bf16_t)(r.v0[i] & 0xffffu); vt[(2 * i + 1) * 68] = (bf16_t)(r.v0[i] >> 16); }
; }
; template <int MODE>
; __device__ __forceinline__ void nsa_compute(int cur, int buf, int t, int hl, u64 mymask, const bf16x8 (&Qf)[2][2], f32x4 (&O)[4][2], float (&m)[2], float (&l)[2],
;                                             const float (&inv)[2], float* impw, char* lds) {
;     ...
;         const float me = (MODE == 2) ? (selok ? m[r] : __builtin_inff()) : m[r];
;         float ps = 0.f;
; #pragma unroll
;         for (int kk = 0; kk < 2; ++kk)
; #pragma unroll
;           for (int e = 0; e < 4; ++e) { pv[kk][e] = __builtin_amdgcn_exp2f(sv[kk][e] - me); ps += pv[kk][e]; }
;         l[r] += ps;
;       }
;       if (MODE != 0) {
;         const unsigned w0 = pk2(pv[0][0], pv[0][1]), w1 = pk2(pv[0][2], pv[0][3]), w2 = pk2(pv[1][0], pv[1][1]), w3 = pk2(pv[1][2], pv[1][3]);
;         u32x4 pw; pw.x = w0; pw.y = w1; pw.z = w2; pw.w = w3;
;         Pf[r] = __builtin_bit_cast(bf16x8, pw);
;       }
;     }
;     if (MODE != 0) {
;       bf16x8 vfr[4];
; #pragma unroll
;       for (int df = 0; df < 4; ++df) {
;         const bf16x4 va = *(const bf16x4*)(vt + (df * 16 + fr) * 68 + 32 * s2 + 4 * fq);
;         const bf16x4 vb = *(const bf16x4*)(vt + (df * 16 + fr) * 68 + 32 * s2 + 16 + 4 * fq);
;         bf16x8 vf; vf[0] = va[0]; vf[1] = va[1]; vf[2] = va[2]; vf[3] = va[3]; vf[4] = vb[0]; vf[5] = vb[1]; vf[6] = vb[2]; vf[7] = vb[3];
;         vfr[df] = vf;
;       }
;       __builtin_amdgcn_s_setprio(1);
; #pragma unroll
;       for (int df = 0; df < 4; ++df)
; #pragma unroll
;         for (int r = 0; r < 2; ++r) O[df][r] = mfma16(vfr[df], Pf[r], O[df][r]);
;       __builtin_amdgcn_s_setprio(0);
.LBB0_373:
	v_exp_f32_e32 v113, v113
	v_exp_f32_e32 v112, v112
	v_cvt_pk_bf16_f32 v124, v119, v114
	v_exp_f32_e32 v114, v101
	v_cvt_pk_bf16_f32 v122, v115, v117
	v_exp_f32_e32 v115, v100
	v_cvt_pk_bf16_f32 v123, v118, v116
	v_exp_f32_e32 v116, v103
	v_mov_b32_e32 v91, v102
	ds_read2_b64 v[100:103], v137 offset0:8 offset1:12
	ds_read2_b64 v[126:129], v138 offset0:24 offset1:28
	ds_read2_b64 v[130:133], v139 offset0:40 offset1:44
	ds_read2_b64 v[134:137], v140 offset0:56 offset1:60
	v_exp_f32_e32 v117, v91
	v_exp_f32_e32 v118, v89
	v_exp_f32_e32 v119, v88
	v_cvt_pk_bf16_f32 v125, v121, v120
	v_cvt_pk_bf16_f32 v138, v113, v112
	v_cvt_pk_bf16_f32 v139, v114, v115
	v_cvt_pk_bf16_f32 v140, v116, v117
	v_cvt_pk_bf16_f32 v141, v118, v119
	s_setprio 1
	s_waitcnt lgkmcnt(3)
	v_mfma_f32_16x16x32_bf16 v[88:91], v[100:103], v[122:125], v[84:87]
	v_mfma_f32_16x16x32_bf16 v[96:99], v[100:103], v[138:141], v[96:99]
	s_waitcnt lgkmcnt(2)
	v_mfma_f32_16x16x32_bf16 v[100:103], v[126:129], v[122:125], v[80:83]
	v_mfma_f32_16x16x32_bf16 v[84:87], v[126:129], v[138:141], v[92:95]
	s_waitcnt lgkmcnt(1)
	v_mfma_f32_16x16x32_bf16 v[92:95], v[130:133], v[122:125], v[76:79]
	v_mfma_f32_16x16x32_bf16 v[76:79], v[130:133], v[138:141], v[108:111]
	s_waitcnt lgkmcnt(0)
	v_mfma_f32_16x16x32_bf16 v[80:83], v[134:137], v[122:125], v[72:75]
	v_mfma_f32_16x16x32_bf16 v[72:75], v[134:137], v[138:141], v[104:107]
	s_setprio 0
	s_xor_b32 s46, s46, 1
	s_cmp_lt_i32 s16, 0
	s_cbranch_scc1 .LBB0_375
	v_mov_b32 v104, v179
	s_lshl_b32 s17, s46, 13
	v_ashrrev_i32_e32 v105, 3, v104
	v_xor_b32_e32 v107, v105, v104
	v_lshl_add_u32 v106, v105, 7, s17
	v_lshlrev_b32_e32 v107, 4, v107
	s_movk_i32 s30, 0x70
	v_lshlrev_b32_e32 v104, 3, v104
	v_and_or_b32 v106, v107, s30, v106
	s_lshl_b32 s30, s46, 9
	v_and_b32_e32 v104, 56, v104
	s_add_i32 s17, s17, s30
	v_mul_u32_u24_e32 v104, 0x88, v104
	v_lshlrev_b32_e32 v105, 1, v105
	v_add3_u32 v104, s17, v104, v105
	s_waitcnt vmcnt(1)
	ds_write_b128 v106, v[56:59]
	s_waitcnt vmcnt(0)
	ds_write_b16 v104, v60 offset:16384
	ds_write_b16_d16_hi v104, v60 offset:16520
	ds_write_b16 v104, v61 offset:16656
	ds_write_b16_d16_hi v104, v61 offset:16792
	ds_write_b16 v104, v62 offset:16928
	ds_write_b16_d16_hi v104, v62 offset:17064
	ds_write_b16 v104, v63 offset:17200
	ds_write_b16_d16_hi v104, v63 offset:17336

; template <int MODE>
; __device__ __forceinline__ void nsa_compute(int cur, int buf, int t, int hl, u64 mymask, const bf16x8 (&Qf)[2][2], f32x4 (&O)[4][2], float (&m)[2], float (&l)[2],
;                                             const float (&inv)[2], float* impw, char* lds) {
;     ...
; #pragma unroll
;   for (int s2 = 0; s2 < 2; ++s2) {
;     f32x4 S[2][2] = {};
;     bf16x8 kfr[2][2];
; #pragma unroll
;     for (int ks = 0; ks < 2; ++ks)
; #pragma unroll
;       for (int kk = 0; kk < 2; ++kk) kfr[ks][kk] = *(const bf16x8*)(kt + (32 * s2 + 16 * kk + fr) * 128 + (((ks * 4 + fq) ^ (fr & 7)) << 4));
;     __builtin_amdgcn_s_setprio(1);
; #pragma unroll
;     for (int ks = 0; ks < 2; ++ks)
; #pragma unroll
;       for (int kk = 0; kk < 2; ++kk)
; #pragma unroll
;         for (int r = 0; r < 2; ++r) S[kk][r] = mfma16(kfr[ks][kk], Qf[r][ks], S[kk][r]);
;     __builtin_amdgcn_s_setprio(0);
;     bf16x8 Pf[2];
;     float g1s[2] = {0.f, 0.f}, p3s[2] = {0.f, 0.f};
; #pragma unroll
;     for (int r = 0; r < 2; ++r) {
;       float sv[2][4];
; #pragma unroll
;       for (int kk = 0; kk < 2; ++kk)
; #pragma unroll
;         for (int e = 0; e < 4; ++e) {
;           const int off = 32 * s2 + 16 * kk + e;
;           int idx;
;           if (MODE <= 1) { idx = base - 16 * off; idx = idx > 0 ? idx : 0; } else idx = base - off;
;           sv[kk][e] = S[kk][r][e] * (0.125f * LOG2E) + tb[r * TS + idx];
;         }
;       float pv[2][4];
;       if (MODE == 1) {
; #pragma unroll
;         for (int kk = 0; kk < 2; ++kk)
; #pragma unroll
;           for (int e = 0; e < 4; ++e) pv[kk][e] = __builtin_amdgcn_exp2f(sv[kk][e] - m[r]) * inv[r];
; #pragma unroll
;         for (int kk = 0; kk < 2; ++kk) { g1s[kk] += pv[kk][0] + pv[kk][1] + pv[kk][2] + 0.5f * pv[kk][3]; p3s[kk] += 0.5f * pv[kk][3]; }
;       } else {
;         const float mxa = fmaxf(fmaxf(sv[0][0], sv[0][1]), sv[0][2]), mxb = fmaxf(fmaxf(sv[0][3], sv[1][0]), sv[1][1]);
;         float mx = fmaxf(fmaxf(fmaxf(sv[1][2], sv[1][3]), mxa), mxb);
;         if (MODE == 2) mx = selok ? mx : -__builtin_inff();
;         if (__any(mx > m[r] + 8.0f)) {
;           mx = fmaxf(mx, __shfl_xor(mx, 16)); mx = fmaxf(mx, __shfl_xor(mx, 32));
;           const float mn = fmaxf(m[r], mx), al = __builtin_amdgcn_exp2f(m[r] - mn);
;           m[r] = mn; l[r] *= al;
;           if (MODE != 0) {
; #pragma unroll
.LBB0_377:
	v_add_f32_e32 v104, 0, v113
	v_add_f32_e32 v104, v112, v104
	v_add_f32_e32 v104, v114, v104
	v_add_f32_e32 v104, v115, v104
	v_add_f32_e32 v104, v116, v104
	v_add_f32_e32 v104, v117, v104
	v_add_f32_e32 v104, v118, v104
	v_add_f32_e32 v104, v119, v104
	s_cmp_lt_i32 s16, 0
	v_add_f32_e32 v195, v195, v104
	s_cbranch_scc1 .LBB0_380
	v_mov_b32 v104, v179
	s_lshl_b32 s71, s46, 13
	v_lshrrev_b32_e32 v105, 4, v104
	v_bfe_u32 v120, v104, 4, 2
	v_and_b32_e32 v112, 7, v104
	v_and_b32_e32 v149, 15, v104
	v_bitop3_b32 v104, v105, v112, 3 bitop3:0x6c
	v_bitop3_b32 v112, v120, v112, 4 bitop3:0x36
	v_lshlrev_b32_e32 v146, 7, v149
	v_lshl_or_b32 v147, v104, 4, s71
	v_lshl_or_b32 v148, v112, 4, s71
	v_or_b32_e32 v108, v147, v146
	v_or_b32_e32 v116, v148, v146
	ds_read_b128 v[104:107], v108
	ds_read_b128 v[108:111], v108 offset:2048
	ds_read_b128 v[112:115], v116
	ds_read_b128 v[116:119], v116 offset:2048
	v_lshlrev_b32_e32 v150, 2, v120
	v_sub_u32_e32 v251, v180, v150
	v_lshl_add_u32 v251, v251, 2, v235
	s_lshl_b32 s16, s16, 8
	v_subrev_u32_e32 v250, s16, v251
	v_add_u32_e32 v249, 0xa00, v250
	ds_read2_b32 v[198:199], v250 offset0:63 offset1:64
	ds_read2_b32 v[200:201], v250 offset0:61 offset1:62
	ds_read2_b32 v[202:203], v250 offset0:47 offset1:48
	ds_read2_b32 v[204:205], v250 offset0:45 offset1:46
	ds_read2_b32 v[206:207], v249 offset0:63 offset1:64
	ds_read2_b32 v[208:209], v249 offset0:61 offset1:62
	ds_read2_b32 v[210:211], v249 offset0:47 offset1:48
	ds_read2_b32 v[236:237], v249 offset0:45 offset1:46
	s_setprio 1
	s_waitcnt lgkmcnt(11)
	v_mfma_f32_16x16x32_bf16 v[120:123], v[104:107], v[0:3], 0
	v_mfma_f32_16x16x32_bf16 v[104:107], v[104:107], v[8:11], 0
	s_waitcnt lgkmcnt(10)
	v_mfma_f32_16x16x32_bf16 v[128:131], v[108:111], v[0:3], 0
	v_mfma_f32_16x16x32_bf16 v[108:111], v[108:111], v[8:11], 0
	s_waitcnt lgkmcnt(9)
	v_mfma_f32_16x16x32_bf16 v[124:127], v[112:115], v[12:15], v[104:107]
	s_waitcnt lgkmcnt(8)
	v_mfma_f32_16x16x32_bf16 v[104:107], v[116:119], v[4:7], v[128:131]
	v_mfma_f32_16x16x32_bf16 v[116:119], v[116:119], v[12:15], v[108:111]
	v_mfma_f32_16x16x32_bf16 v[120:123], v[112:115], v[4:7], v[120:123]
	s_setprio 0
	s_waitcnt lgkmcnt(4)
	v_sub_f32_e32 v199, v199, v230
	v_sub_f32_e32 v198, v198, v230
	v_sub_f32_e32 v201, v201, v230
	v_sub_f32_e32 v200, v200, v230
	v_sub_f32_e32 v203, v203, v230
	v_sub_f32_e32 v202, v202, v230
	v_sub_f32_e32 v205, v205, v230
	v_sub_f32_e32 v204, v204, v230
	s_waitcnt lgkmcnt(0)
	v_sub_f32_e32 v207, v207, v231
	v_sub_f32_e32 v206, v206, v231
	v_sub_f32_e32 v209, v209, v231
	v_sub_f32_e32 v208, v208, v231
	v_sub_f32_e32 v211, v211, v231
	v_sub_f32_e32 v210, v210, v231
	v_sub_f32_e32 v237, v237, v231
	v_sub_f32_e32 v236, v236, v231
	s_nop 0
	v_sub_u32_e32 v108, v180, v150
	v_lshl_add_u32 v108, v108, 2, v235
	v_subrev_u32_e32 v154, s16, v108
	s_waitcnt lgkmcnt(7)
	s_nop 1
	v_fmamk_f32 v135, v120, 0x3e38aa3b, v199
	v_fmamk_f32 v134, v121, 0x3e38aa3b, v198
	s_waitcnt lgkmcnt(6)
	v_fmamk_f32 v133, v122, 0x3e38aa3b, v201
	v_fmamk_f32 v132, v123, 0x3e38aa3b, v200
	s_waitcnt lgkmcnt(5)
	v_fmamk_f32 v129, v104, 0x3e38aa3b, v203
	v_fmamk_f32 v128, v105, 0x3e38aa3b, v202
	s_waitcnt lgkmcnt(4)
	v_fmamk_f32 v131, v106, 0x3e38aa3b, v205
	v_fmamk_f32 v130, v107, 0x3e38aa3b, v204
	v_max3_f32 v104, v135, v134, v133
	v_max3_f32 v105, v132, v129, v128
	v_max_f32_e32 v106, v131, v130
	v_max3_f32 v104, v106, v104, v105
	v_sub_f32_e32 v105, v192, v230
	v_add_f32_e32 v105, 0x41000000, v105
	v_cmp_gt_f32_e32 vcc, v104, v105
	s_cbranch_vccz .LBB0_381
	v_add_f32_e32 v104, v104, v230
	ds_bpermute_b32 v105, v233, v104
	v_max_f32_e32 v104, v104, v104
	v_mov_b32_e32 v137, v193
	v_mov_b32_e32 v197, v195
	s_waitcnt lgkmcnt(0)
	v_max_f32_e32 v105, v105, v105
	v_max_f32_e32 v104, v104, v105
	ds_bpermute_b32 v105, v234, v104
	s_waitcnt lgkmcnt(0)
	v_max3_f32 v136, v192, v104, v105
	v_sub_f32_e32 v104, v192, v136
	v_exp_f32_e32 v120, v104
	v_mov_b64_e32 v[192:193], v[136:137]
	v_mul_f32_e32 v196, v194, v120
	v_pk_mul_f32 v[114:115], v[90:91], v[120:121] op_sel_hi:[1,0]
	v_pk_mul_f32 v[112:113], v[88:89], v[120:121] op_sel_hi:[1,0]
	v_pk_mul_f32 v[106:107], v[102:103], v[120:121] op_sel_hi:[1,0]
	v_pk_mul_f32 v[104:105], v[100:101], v[120:121] op_sel_hi:[1,0]
	v_pk_mul_f32 v[110:111], v[94:95], v[120:121] op_sel_hi:[1,0]
	v_pk_mul_f32 v[108:109], v[92:93], v[120:121] op_sel_hi:[1,0]
	v_pk_mul_f32 v[122:123], v[82:83], v[120:121] op_sel_hi:[1,0]
	v_pk_mul_f32 v[120:121], v[80:81], v[120:121] op_sel_hi:[1,0]
	v_cmp_lt_f32_e32 vcc, 0xefa18f08, v136
	s_nop 1
	v_cndmask_b32_e32 v232, 0, v136, vcc
	v_sub_f32_e32 v230, v232, v230
	v_sub_f32_e32 v135, v135, v230
	v_sub_f32_e32 v134, v134, v230
	v_sub_f32_e32 v133, v133, v230
	v_sub_f32_e32 v132, v132, v230
	v_sub_f32_e32 v129, v129, v230
	v_sub_f32_e32 v128, v128, v230
	v_sub_f32_e32 v131, v131, v230
	v_sub_f32_e32 v130, v130, v230
	v_mov_b32_e32 v230, v232
	s_branch .LBB0_382

; template <int MODE>
; __device__ __forceinline__ void nsa_compute(int cur, int buf, int t, int hl, u64 mymask, const bf16x8 (&Qf)[2][2], f32x4 (&O)[4][2], float (&m)[2], float (&l)[2],
;                                             const float (&inv)[2], float* impw, char* lds) {
;     ...
;         const float mxa = fmaxf(fmaxf(sv[0][0], sv[0][1]), sv[0][2]), mxb = fmaxf(fmaxf(sv[0][3], sv[1][0]), sv[1][1]);
;         float mx = fmaxf(fmaxf(fmaxf(sv[1][2], sv[1][3]), mxa), mxb);
;         if (MODE == 2) mx = selok ? mx : -__builtin_inff();
;         if (__any(mx > m[r] + 8.0f)) {
;           mx = fmaxf(mx, __shfl_xor(mx, 16)); mx = fmaxf(mx, __shfl_xor(mx, 32));
;           const float mn = fmaxf(m[r], mx), al = __builtin_amdgcn_exp2f(m[r] - mn);
;           m[r] = mn; l[r] *= al;
;           if (MODE != 0) {
; #pragma unroll
;             for (int df = 0; df < 4; ++df) O[df][r] *= al;
;           }
;         }
;         const float me = (MODE == 2) ? (selok ? m[r] : __builtin_inff()) : m[r];
;         float ps = 0.f;
; #pragma unroll
;         for (int kk = 0; kk < 2; ++kk)
; #pragma unroll
;           for (int e = 0; e < 4; ++e) { pv[kk][e] = __builtin_amdgcn_exp2f(sv[kk][e] - me); ps += pv[kk][e]; }
;         l[r] += ps;
.LBB0_382:
	v_exp_f32_e32 v151, v135
	v_exp_f32_e32 v152, v134
	v_exp_f32_e32 v153, v133
	v_exp_f32_e32 v155, v132
	v_add_f32_e32 v135, 0, v151
	v_exp_f32_e32 v156, v129
	v_add_f32_e32 v134, v152, v135
	v_exp_f32_e32 v157, v128
	v_add_f32_e32 v133, v153, v134
	v_add_f32_e32 v132, v155, v133
	v_add_f32_e32 v129, v156, v132
	v_add_f32_e32 v128, v157, v129
	v_exp_f32_e32 v158, v131
	v_exp_f32_e32 v159, v130
	v_add_f32_e32 v128, v158, v128
	v_add_f32_e32 v128, v159, v128
	v_add_f32_e32 v196, v196, v128
	s_waitcnt lgkmcnt(3)
	v_fmamk_f32 v135, v124, 0x3e38aa3b, v207
	v_fmamk_f32 v134, v125, 0x3e38aa3b, v206
	s_waitcnt lgkmcnt(2)
	v_fmamk_f32 v145, v126, 0x3e38aa3b, v209
	v_fmamk_f32 v144, v127, 0x3e38aa3b, v208
	s_waitcnt lgkmcnt(1)
	v_fmamk_f32 v133, v116, 0x3e38aa3b, v211
	v_fmamk_f32 v132, v117, 0x3e38aa3b, v210
	s_waitcnt lgkmcnt(0)
	v_fmamk_f32 v117, v118, 0x3e38aa3b, v237
	v_fmamk_f32 v116, v119, 0x3e38aa3b, v236
	v_max3_f32 v118, v135, v134, v145
	v_max3_f32 v119, v144, v133, v132
	v_max_f32_e32 v124, v117, v116
	v_max3_f32 v118, v124, v118, v119
	v_sub_f32_e32 v119, v193, v231
	v_add_f32_e32 v119, 0x41000000, v119
	v_cmp_gt_f32_e32 vcc, v118, v119
	s_cbranch_vccz .LBB0_384
	v_add_f32_e32 v118, v118, v231
	ds_bpermute_b32 v119, v233, v118
	v_max_f32_e32 v118, v118, v118
	s_waitcnt lgkmcnt(0)
	v_max_f32_e32 v119, v119, v119
	v_max_f32_e32 v118, v118, v119
	ds_bpermute_b32 v119, v234, v118
	s_waitcnt lgkmcnt(0)
	v_max3_f32 v118, v193, v118, v119
	v_sub_f32_e32 v119, v193, v118
	v_exp_f32_e32 v140, v119
	v_mov_b32_e32 v193, v118
	v_mul_f32_e32 v197, v197, v140
	v_pk_mul_f32 v[126:127], v[98:99], v[140:141] op_sel_hi:[1,0]
	v_pk_mul_f32 v[124:125], v[96:97], v[140:141] op_sel_hi:[1,0]
	v_pk_mul_f32 v[130:131], v[86:87], v[140:141] op_sel_hi:[1,0]
	v_pk_mul_f32 v[128:129], v[84:85], v[140:141] op_sel_hi:[1,0]
	v_pk_mul_f32 v[138:139], v[78:79], v[140:141] op_sel_hi:[1,0]
	v_pk_mul_f32 v[136:137], v[76:77], v[140:141] op_sel_hi:[1,0]
	v_pk_mul_f32 v[142:143], v[74:75], v[140:141] op_sel_hi:[1,0]
	v_pk_mul_f32 v[140:141], v[72:73], v[140:141] op_sel_hi:[1,0]
	v_cmp_lt_f32_e32 vcc, 0xefa18f08, v118
	s_nop 1
	v_cndmask_b32_e32 v232, 0, v118, vcc
	v_sub_f32_e32 v231, v232, v231
	v_sub_f32_e32 v135, v135, v231
	v_sub_f32_e32 v134, v134, v231
	v_sub_f32_e32 v145, v145, v231
	v_sub_f32_e32 v144, v144, v231
	v_sub_f32_e32 v133, v133, v231
	v_sub_f32_e32 v132, v132, v231
	v_sub_f32_e32 v117, v117, v231
	v_sub_f32_e32 v116, v116, v231
	v_mov_b32_e32 v231, v232
	s_branch .LBB0_385

; template <int MODE>
; __device__ __forceinline__ void nsa_compute(int cur, int buf, int t, int hl, u64 mymask, const bf16x8 (&Qf)[2][2], f32x4 (&O)[4][2], float (&m)[2], float (&l)[2],
;                                             const float (&inv)[2], float* impw, char* lds) {
;     ...
; #pragma unroll
;     for (int ks = 0; ks < 2; ++ks)
; #pragma unroll
;       for (int kk = 0; kk < 2; ++kk) kfr[ks][kk] = *(const bf16x8*)(kt + (32 * s2 + 16 * kk + fr) * 128 + (((ks * 4 + fq) ^ (fr & 7)) << 4));
;     __builtin_amdgcn_s_setprio(1);
; #pragma unroll
;     for (int ks = 0; ks < 2; ++ks)
; #pragma unroll
;       for (int kk = 0; kk < 2; ++kk)
; #pragma unroll
;         for (int r = 0; r < 2; ++r) S[kk][r] = mfma16(kfr[ks][kk], Qf[r][ks], S[kk][r]);
;     __builtin_amdgcn_s_setprio(0);
;     bf16x8 Pf[2];
;     float g1s[2] = {0.f, 0.f}, p3s[2] = {0.f, 0.f};
; #pragma unroll
;     for (int r = 0; r < 2; ++r) {
;       float sv[2][4];
; #pragma unroll
;       for (int kk = 0; kk < 2; ++kk)
; #pragma unroll
;         for (int e = 0; e < 4; ++e) {
;     ...
;         const float me = (MODE == 2) ? (selok ? m[r] : __builtin_inff()) : m[r];
;         float ps = 0.f;
; #pragma unroll
;         for (int kk = 0; kk < 2; ++kk)
; #pragma unroll
;           for (int e = 0; e < 4; ++e) { pv[kk][e] = __builtin_amdgcn_exp2f(sv[kk][e] - me); ps += pv[kk][e]; }
;         l[r] += ps;
;       }
;       if (MODE != 0) {
;         const unsigned w0 = pk2(pv[0][0], pv[0][1]), w1 = pk2(pv[0][2], pv[0][3]), w2 = pk2(pv[1][0], pv[1][1]), w3 = pk2(pv[1][2], pv[1][3]);
;         u32x4 pw; pw.x = w0; pw.y = w1; pw.z = w2; pw.w = w3;
;         Pf[r] = __builtin_bit_cast(bf16x8, pw);
;       }
;     }
;     if (MODE != 0) {
;       bf16x8 vfr[4];
; #pragma unroll
;       for (int df = 0; df < 4; ++df) {
;         const bf16x4 va = *(const bf16x4*)(vt + (df * 16 + fr) * 68 + 32 * s2 + 4 * fq);
;         const bf16x4 vb = *(const bf16x4*)(vt + (df * 16 + fr) * 68 + 32 * s2 + 16 + 4 * fq);
;         bf16x8 vf; vf[0] = va[0]; vf[1] = va[1]; vf[2] = va[2]; vf[3] = va[3]; vf[4] = vb[0]; vf[5] = vb[1]; vf[6] = vb[2]; vf[7] = vb[3];
;         vfr[df] = vf;
;       }
;       __builtin_amdgcn_s_setprio(1);
; #pragma unroll
;       for (int df = 0; df < 4; ++df)
; #pragma unroll
;         for (int r = 0; r < 2; ++r) O[df][r] = mfma16(vfr[df], Pf[r], O[df][r]);
;       __builtin_amdgcn_s_setprio(0);
.LBB0_385:
	v_exp_f32_e32 v119, v135
	v_exp_f32_e32 v134, v134
	v_exp_f32_e32 v145, v145
	v_exp_f32_e32 v144, v144
	v_add_f32_e32 v135, 0, v119
	v_exp_f32_e32 v133, v133
	v_add_f32_e32 v135, v134, v135
	v_exp_f32_e32 v132, v132
	v_add_f32_e32 v135, v145, v135
	v_exp_f32_e32 v117, v117
	v_add_f32_e32 v135, v144, v135
	v_exp_f32_e32 v116, v116
	v_add_f32_e32 v135, v133, v135
	v_add_f32_e32 v135, v132, v135
	v_add_f32_e32 v135, v117, v135
	s_lshl_b32 s16, s46, 9
	v_add_f32_e32 v118, v116, v135
	v_cvt_pk_bf16_f32 v167, v117, v116
	v_mul_u32_u24_e32 v116, 0x44, v149
	s_add_i32 s72, s71, s16
	v_lshlrev_b32_e32 v116, 1, v116
	v_lshlrev_b32_e32 v117, 1, v150
	v_add3_u32 v116, s72, v116, v117
	v_cvt_pk_bf16_f32 v161, v153, v155
	v_cvt_pk_bf16_f32 v162, v156, v157
	v_add_u32_e32 v155, 0x4000, v116
	v_add_u32_e32 v156, 0x4800, v116
	v_cvt_pk_bf16_f32 v160, v151, v152
	v_cvt_pk_bf16_f32 v163, v158, v159
	v_cvt_pk_bf16_f32 v164, v119, v134
	v_cvt_pk_bf16_f32 v166, v133, v132
	ds_read2_b64 v[132:135], v155 offset1:4
	ds_read2_b64 v[150:153], v156 offset0:16 offset1:20
	v_add_u32_e32 v157, 0x5000, v116
	v_add_u32_e32 v158, 0x5800, v116
	ds_read2_b64 v[168:171], v157 offset0:32 offset1:36
	ds_read2_b64 v[172:175], v158 offset0:48 offset1:52
	v_add_f32_e32 v197, v197, v118
	v_cvt_pk_bf16_f32 v165, v145, v144
	s_setprio 1
	s_waitcnt lgkmcnt(3)
	v_mfma_f32_16x16x32_bf16 v[116:119], v[132:135], v[160:163], v[112:115]
	v_mfma_f32_16x16x32_bf16 v[132:135], v[132:135], v[164:167], v[124:127]
	s_waitcnt lgkmcnt(2)
	v_mfma_f32_16x16x32_bf16 v[112:115], v[150:153], v[160:163], v[104:107]
	v_mfma_f32_16x16x32_bf16 v[128:131], v[150:153], v[164:167], v[128:131]
	s_waitcnt lgkmcnt(1)
	v_mfma_f32_16x16x32_bf16 v[108:111], v[168:171], v[160:163], v[108:111]
	v_mfma_f32_16x16x32_bf16 v[124:127], v[168:171], v[164:167], v[136:139]
	s_waitcnt lgkmcnt(0)
	v_mfma_f32_16x16x32_bf16 v[104:107], v[172:175], v[160:163], v[120:123]
	v_mfma_f32_16x16x32_bf16 v[120:123], v[172:175], v[164:167], v[140:143]
	s_setprio 0
	s_nop 1
	v_add_u32_e32 v140, v147, v146
	v_add_u32_e32 v148, v148, v146
	ds_read_b128 v[136:139], v140 offset:4096
	ds_read_b128 v[140:143], v140 offset:6144
	ds_read_b128 v[144:147], v148 offset:4096
	ds_read_b128 v[148:151], v148 offset:6144
	v_add_u32_e32 v251, 0xa00, v154
	ds_read2_b32 v[202:203], v154 offset0:31 offset1:32
	ds_read2_b32 v[204:205], v154 offset0:29 offset1:30
	ds_read2_b32 v[206:207], v154 offset0:15 offset1:16
	ds_read2_b32 v[208:209], v154 offset0:13 offset1:14
	ds_read2_b32 v[210:211], v251 offset0:31 offset1:32
	ds_read2_b32 v[236:237], v251 offset0:29 offset1:30
	ds_read2_b32 v[238:239], v251 offset0:15 offset1:16
	ds_read2_b32 v[240:241], v251 offset0:13 offset1:14
	s_setprio 1
	s_waitcnt lgkmcnt(11)
	v_mfma_f32_16x16x32_bf16 v[160:163], v[136:139], v[0:3], 0
	v_mfma_f32_16x16x32_bf16 v[136:139], v[136:139], v[8:11], 0
	s_waitcnt lgkmcnt(10)
	v_mfma_f32_16x16x32_bf16 v[168:171], v[140:143], v[8:11], 0
	v_mfma_f32_16x16x32_bf16 v[164:167], v[140:143], v[0:3], 0
	s_waitcnt lgkmcnt(9)
	v_mfma_f32_16x16x32_bf16 v[160:163], v[144:147], v[4:7], v[160:163]
	v_mfma_f32_16x16x32_bf16 v[140:143], v[144:147], v[12:15], v[136:139]
	s_waitcnt lgkmcnt(8)
	v_mfma_f32_16x16x32_bf16 v[136:139], v[148:151], v[12:15], v[168:171]
	v_mfma_f32_16x16x32_bf16 v[164:167], v[148:151], v[4:7], v[164:167]
	s_setprio 0
	s_waitcnt lgkmcnt(4)
	v_sub_f32_e32 v203, v203, v230
	v_sub_f32_e32 v202, v202, v230
	v_sub_f32_e32 v205, v205, v230
	v_sub_f32_e32 v204, v204, v230
	v_sub_f32_e32 v207, v207, v230
	v_sub_f32_e32 v206, v206, v230
	v_sub_f32_e32 v209, v209, v230
	v_sub_f32_e32 v208, v208, v230
	s_waitcnt lgkmcnt(0)
	v_sub_f32_e32 v211, v211, v231
	v_sub_f32_e32 v210, v210, v231
	v_sub_f32_e32 v237, v237, v231
	v_sub_f32_e32 v236, v236, v231
	v_sub_f32_e32 v239, v239, v231
	v_sub_f32_e32 v238, v238, v231
	v_sub_f32_e32 v241, v241, v231
	v_sub_f32_e32 v240, v240, v231
	s_waitcnt lgkmcnt(7)
	s_nop 1
	v_fmamk_f32 v160, v160, 0x3e38aa3b, v203
	v_fmamk_f32 v150, v161, 0x3e38aa3b, v202
	s_waitcnt lgkmcnt(6)
	v_fmamk_f32 v159, v162, 0x3e38aa3b, v205
	v_fmamk_f32 v148, v163, 0x3e38aa3b, v204
	s_waitcnt lgkmcnt(5)
	v_fmamk_f32 v151, v164, 0x3e38aa3b, v207
	v_fmamk_f32 v146, v165, 0x3e38aa3b, v206
	s_waitcnt lgkmcnt(4)
	v_fmamk_f32 v145, v166, 0x3e38aa3b, v209
	v_fmamk_f32 v144, v167, 0x3e38aa3b, v208
	v_max3_f32 v147, v160, v150, v159
	v_max3_f32 v149, v148, v151, v146
	v_max_f32_e32 v152, v145, v144
	v_max3_f32 v147, v152, v147, v149
	v_sub_f32_e32 v149, v192, v230
	v_add_f32_e32 v149, 0x41000000, v149
	v_cmp_gt_f32_e32 vcc, v147, v149
	s_cbranch_vccz .LBB0_387
	v_add_f32_e32 v147, v147, v230
	ds_bpermute_b32 v149, v233, v147
	v_max_f32_e32 v147, v147, v147
	v_mov_b32_e32 v153, v193
	s_waitcnt lgkmcnt(0)
	v_max_f32_e32 v149, v149, v149
	v_max_f32_e32 v147, v147, v149
	ds_bpermute_b32 v149, v234, v147
	s_waitcnt lgkmcnt(0)
	v_max3_f32 v152, v192, v147, v149
	v_sub_f32_e32 v147, v192, v152
	v_exp_f32_e32 v162, v147
	v_mov_b64_e32 v[192:193], v[152:153]
	v_mul_f32_e32 v196, v196, v162
	v_pk_mul_f32 v[118:119], v[118:119], v[162:163] op_sel_hi:[1,0]
	v_pk_mul_f32 v[116:117], v[116:117], v[162:163] op_sel_hi:[1,0]
	v_pk_mul_f32 v[114:115], v[114:115], v[162:163] op_sel_hi:[1,0]
	v_pk_mul_f32 v[112:113], v[112:113], v[162:163] op_sel_hi:[1,0]
	v_pk_mul_f32 v[110:111], v[110:111], v[162:163] op_sel_hi:[1,0]
	v_pk_mul_f32 v[108:109], v[108:109], v[162:163] op_sel_hi:[1,0]
	v_pk_mul_f32 v[106:107], v[106:107], v[162:163] op_sel_hi:[1,0]
	v_pk_mul_f32 v[104:105], v[104:105], v[162:163] op_sel_hi:[1,0]
	v_cmp_lt_f32_e32 vcc, 0xefa18f08, v152
	s_nop 1
	v_cndmask_b32_e32 v232, 0, v152, vcc
	v_sub_f32_e32 v230, v232, v230
	v_sub_f32_e32 v160, v160, v230
	v_sub_f32_e32 v150, v150, v230
	v_sub_f32_e32 v159, v159, v230
	v_sub_f32_e32 v148, v148, v230
	v_sub_f32_e32 v151, v151, v230
	v_sub_f32_e32 v146, v146, v230
	v_sub_f32_e32 v145, v145, v230
	v_sub_f32_e32 v144, v144, v230
	v_mov_b32_e32 v230, v232
	s_branch .LBB0_388
; __device__ __forceinline__ void kv_lwrite(const KVRegs& r, char* lds, int buf) {
;   const int tid = TIDX, row = tid >> 3, cq = tid & 7;
; template <int MODE>
; __device__ __forceinline__ void nsa_compute(int cur, int buf, int t, int hl, u64 mymask, const bf16x8 (&Qf)[2][2], f32x4 (&O)[4][2], float (&m)[2], float (&l)[2],
;                                             const float (&inv)[2], float* impw, char* lds) {
;     ...
;         const float mxa = fmaxf(fmaxf(sv[0][0], sv[0][1]), sv[0][2]), mxb = fmaxf(fmaxf(sv[0][3], sv[1][0]), sv[1][1]);
;         float mx = fmaxf(fmaxf(fmaxf(sv[1][2], sv[1][3]), mxa), mxb);
;         if (MODE == 2) mx = selok ? mx : -__builtin_inff();
;         if (__any(mx > m[r] + 8.0f)) {
;           mx = fmaxf(mx, __shfl_xor(mx, 16)); mx = fmaxf(mx, __shfl_xor(mx, 32));
;           const float mn = fmaxf(m[r], mx), al = __builtin_amdgcn_exp2f(m[r] - mn);
;           m[r] = mn; l[r] *= al;
;           if (MODE != 0) {
; #pragma unroll
;             for (int df = 0; df < 4; ++df) O[df][r] *= al;
;           }
;         }
;         const float me = (MODE == 2) ? (selok ? m[r] : __builtin_inff()) : m[r];
;         float ps = 0.f;
; #pragma unroll
;         for (int kk = 0; kk < 2; ++kk)
; #pragma unroll
;           for (int e = 0; e < 4; ++e) { pv[kk][e] = __builtin_amdgcn_exp2f(sv[kk][e] - me); ps += pv[kk][e]; }
;         l[r] += ps;
;       }
;       if (MODE != 0) {
;         const unsigned w0 = pk2(pv[0][0], pv[0][1]), w1 = pk2(pv[0][2], pv[0][3]), w2 = pk2(pv[1][0], pv[1][1]), w3 = pk2(pv[1][2], pv[1][3]);
;         u32x4 pw; pw.x = w0; pw.y = w1; pw.z = w2; pw.w = w3;
;         Pf[r] = __builtin_bit_cast(bf16x8, pw);
;       }
;     }
;     if (MODE != 0) {
;       bf16x8 vfr[4];
; #pragma unroll
;       for (int df = 0; df < 4; ++df) {
;         const bf16x4 va = *(const bf16x4*)(vt + (df * 16 + fr) * 68 + 32 * s2 + 4 * fq);
;         const bf16x4 vb = *(const bf16x4*)(vt + (df * 16 + fr) * 68 + 32 * s2 + 16 + 4 * fq);
;         bf16x8 vf; vf[0] = va[0]; vf[1] = va[1]; vf[2] = va[2]; vf[3] = va[3]; vf[4] = vb[0]; vf[5] = vb[1]; vf[6] = vb[2]; vf[7] = vb[3];
;         vfr[df] = vf;
;       }
;       __builtin_amdgcn_s_setprio(1);
; #pragma unroll
;       for (int df = 0; df < 4; ++df)
; #pragma unroll
;         for (int r = 0; r < 2; ++r) O[df][r] = mfma16(vfr[df], Pf[r], O[df][r]);
;       __builtin_amdgcn_s_setprio(0);
.LBB0_387:
.LBB0_388:
	v_exp_f32_e32 v147, v160
	v_exp_f32_e32 v149, v150
	v_exp_f32_e32 v150, v159
	v_exp_f32_e32 v148, v148
	v_add_f32_e32 v153, 0, v147
	v_exp_f32_e32 v151, v151
	v_add_f32_e32 v153, v149, v153
	v_exp_f32_e32 v146, v146
	v_add_f32_e32 v153, v150, v153
	v_add_f32_e32 v153, v148, v153
	v_add_f32_e32 v153, v151, v153
	v_add_f32_e32 v159, v146, v153
	v_exp_f32_e32 v153, v145
	v_exp_f32_e32 v152, v144
	v_add_f32_e32 v145, v153, v159
	v_add_f32_e32 v144, v152, v145
	v_add_f32_e32 v196, v196, v144
	s_waitcnt lgkmcnt(3)
	v_fmamk_f32 v145, v140, 0x3e38aa3b, v211
	v_fmamk_f32 v144, v141, 0x3e38aa3b, v210
	s_waitcnt lgkmcnt(2)
	v_fmamk_f32 v141, v142, 0x3e38aa3b, v237
	v_fmamk_f32 v140, v143, 0x3e38aa3b, v236
	s_waitcnt lgkmcnt(1)
	v_fmamk_f32 v143, v136, 0x3e38aa3b, v239
	v_fmamk_f32 v142, v137, 0x3e38aa3b, v238
	s_waitcnt lgkmcnt(0)
	v_fmamk_f32 v137, v138, 0x3e38aa3b, v241
	v_fmamk_f32 v136, v139, 0x3e38aa3b, v240
	v_max3_f32 v138, v145, v144, v141
	v_max3_f32 v139, v140, v143, v142
	v_max_f32_e32 v154, v137, v136
	v_max3_f32 v138, v154, v138, v139
	v_sub_f32_e32 v139, v193, v231
	v_add_f32_e32 v139, 0x41000000, v139
	v_cmp_gt_f32_e32 vcc, v138, v139
	s_cbranch_vccz .LBB0_390
	v_add_f32_e32 v138, v138, v231
	ds_bpermute_b32 v139, v233, v138
	v_max_f32_e32 v138, v138, v138
	s_waitcnt lgkmcnt(0)
	v_max_f32_e32 v139, v139, v139
	v_max_f32_e32 v138, v138, v139
	ds_bpermute_b32 v139, v234, v138
	s_waitcnt lgkmcnt(0)
	v_max3_f32 v138, v193, v138, v139
	v_sub_f32_e32 v139, v193, v138
	v_exp_f32_e32 v154, v139
	v_mov_b32_e32 v193, v138
	v_mul_f32_e32 v197, v197, v154
	v_pk_mul_f32 v[134:135], v[134:135], v[154:155] op_sel_hi:[1,0]
	v_pk_mul_f32 v[132:133], v[132:133], v[154:155] op_sel_hi:[1,0]
	v_pk_mul_f32 v[130:131], v[130:131], v[154:155] op_sel_hi:[1,0]
	v_pk_mul_f32 v[128:129], v[128:129], v[154:155] op_sel_hi:[1,0]
	v_pk_mul_f32 v[126:127], v[126:127], v[154:155] op_sel_hi:[1,0]
	v_pk_mul_f32 v[124:125], v[124:125], v[154:155] op_sel_hi:[1,0]
	v_pk_mul_f32 v[122:123], v[122:123], v[154:155] op_sel_hi:[1,0]
	v_pk_mul_f32 v[120:121], v[120:121], v[154:155] op_sel_hi:[1,0]
	v_cmp_lt_f32_e32 vcc, 0xefa18f08, v138
	s_nop 1
	v_cndmask_b32_e32 v232, 0, v138, vcc
	v_sub_f32_e32 v231, v232, v231
	v_sub_f32_e32 v145, v145, v231
	v_sub_f32_e32 v144, v144, v231
	v_sub_f32_e32 v141, v141, v231
	v_sub_f32_e32 v140, v140, v231
	v_sub_f32_e32 v143, v143, v231
	v_sub_f32_e32 v142, v142, v231
	v_sub_f32_e32 v137, v137, v231
	v_sub_f32_e32 v136, v136, v231
	v_mov_b32_e32 v231, v232
	s_branch .LBB0_391
.LBB0_390:
.LBB0_391:
	v_exp_f32_e32 v168, v145
	v_exp_f32_e32 v169, v144
	v_exp_f32_e32 v170, v141
	v_exp_f32_e32 v171, v140
	v_cvt_pk_bf16_f32 v164, v147, v149
	v_cvt_pk_bf16_f32 v165, v150, v148
	v_cvt_pk_bf16_f32 v166, v151, v146
	v_cvt_pk_bf16_f32 v167, v153, v152
	v_exp_f32_e32 v172, v143
	v_mov_b32_e32 v139, v142
	ds_read2_b64 v[140:143], v155 offset0:8 offset1:12
	ds_read2_b64 v[144:147], v156 offset0:24 offset1:28
	ds_read2_b64 v[148:151], v157 offset0:40 offset1:44
	ds_read2_b64 v[152:155], v158 offset0:56 offset1:60
	v_exp_f32_e32 v173, v139
	v_exp_f32_e32 v174, v137
	v_exp_f32_e32 v175, v136
	v_cvt_pk_bf16_f32 v198, v168, v169
	v_cvt_pk_bf16_f32 v199, v170, v171
	v_cvt_pk_bf16_f32 v200, v172, v173
	v_cvt_pk_bf16_f32 v201, v174, v175
	s_setprio 1
	s_waitcnt lgkmcnt(3)
	v_mfma_f32_16x16x32_bf16 v[136:139], v[140:143], v[164:167], v[116:119]
	v_mfma_f32_16x16x32_bf16 v[140:143], v[140:143], v[198:201], v[132:135]
	s_waitcnt lgkmcnt(2)
	v_mfma_f32_16x16x32_bf16 v[156:159], v[144:147], v[164:167], v[112:115]
	v_mfma_f32_16x16x32_bf16 v[144:147], v[144:147], v[198:201], v[128:131]
	s_waitcnt lgkmcnt(1)
	v_mfma_f32_16x16x32_bf16 v[160:163], v[148:151], v[164:167], v[108:111]
	v_mfma_f32_16x16x32_bf16 v[148:151], v[148:151], v[198:201], v[124:127]
	s_waitcnt lgkmcnt(0)
	v_mfma_f32_16x16x32_bf16 v[164:167], v[152:155], v[164:167], v[104:107]
	v_mfma_f32_16x16x32_bf16 v[152:155], v[152:155], v[198:201], v[120:123]
	s_setprio 0
	s_cmp_lt_i32 s42, 0
	s_cbranch_scc1 .LBB0_393
	v_mov_b32 v104, v179
	s_nop 0
	v_ashrrev_i32_e32 v105, 3, v104
	v_xor_b32_e32 v107, v105, v104
	v_lshlrev_b32_e32 v104, 3, v104
	v_lshlrev_b32_e32 v107, 4, v107
	v_and_b32_e32 v104, 56, v104
	v_lshlrev_b32_e32 v106, 7, v105
	v_and_b32_e32 v107, 0x70, v107
	v_mul_u32_u24_e32 v104, 0x88, v104
	v_lshlrev_b32_e32 v105, 1, v105
	v_add3_u32 v106, s64, v106, v107
	v_add3_u32 v104, s43, v104, v105
	s_waitcnt vmcnt(1)
	ds_write_b128 v106, v[64:67]
	s_waitcnt vmcnt(0)
	ds_write_b16 v104, v68 offset:16384
	ds_write_b16_d16_hi v104, v68 offset:16520
	ds_write_b16 v104, v69 offset:16656
	ds_write_b16_d16_hi v104, v69 offset:16792
	ds_write_b16 v104, v70 offset:16928
	ds_write_b16_d16_hi v104, v70 offset:17064
	ds_write_b16 v104, v71 offset:17200
	ds_write_b16_d16_hi v104, v71 offset:17336

; template <int MODE>
; __device__ __forceinline__ void nsa_compute(int cur, int buf, int t, int hl, u64 mymask, const bf16x8 (&Qf)[2][2], f32x4 (&O)[4][2], float (&m)[2], float (&l)[2],
;                                             const float (&inv)[2], float* impw, char* lds) {
;     ...
; #pragma unroll
;   for (int s2 = 0; s2 < 2; ++s2) {
;     f32x4 S[2][2] = {};
;     bf16x8 kfr[2][2];
; #pragma unroll
;     for (int ks = 0; ks < 2; ++ks)
; #pragma unroll
;       for (int kk = 0; kk < 2; ++kk) kfr[ks][kk] = *(const bf16x8*)(kt + (32 * s2 + 16 * kk + fr) * 128 + (((ks * 4 + fq) ^ (fr & 7)) << 4));
;     __builtin_amdgcn_s_setprio(1);
; #pragma unroll
;     for (int ks = 0; ks < 2; ++ks)
; #pragma unroll
;       for (int kk = 0; kk < 2; ++kk)
; #pragma unroll
;         for (int r = 0; r < 2; ++r) S[kk][r] = mfma16(kfr[ks][kk], Qf[r][ks], S[kk][r]);
;     __builtin_amdgcn_s_setprio(0);
;     bf16x8 Pf[2];
;     float g1s[2] = {0.f, 0.f}, p3s[2] = {0.f, 0.f};
; #pragma unroll
;     for (int r = 0; r < 2; ++r) {
;       float sv[2][4];
; #pragma unroll
;       for (int kk = 0; kk < 2; ++kk)
; #pragma unroll
;         for (int e = 0; e < 4; ++e) {
;           const int off = 32 * s2 + 16 * kk + e;
;           int idx;
;           if (MODE <= 1) { idx = base - 16 * off; idx = idx > 0 ? idx : 0; } else idx = base - off;
;           sv[kk][e] = S[kk][r][e] * (0.125f * LOG2E) + tb[r * TS + idx];
;         }
;       float pv[2][4];
;       if (MODE == 1) {
; #pragma unroll
;         for (int kk = 0; kk < 2; ++kk)
; #pragma unroll
;           for (int e = 0; e < 4; ++e) pv[kk][e] = __builtin_amdgcn_exp2f(sv[kk][e] - m[r]) * inv[r];
; #pragma unroll
;         for (int kk = 0; kk < 2; ++kk) { g1s[kk] += pv[kk][0] + pv[kk][1] + pv[kk][2] + 0.5f * pv[kk][3]; p3s[kk] += 0.5f * pv[kk][3]; }
;       } else {
;         const float mxa = fmaxf(fmaxf(sv[0][0], sv[0][1]), sv[0][2]), mxb = fmaxf(fmaxf(sv[0][3], sv[1][0]), sv[1][1]);
;         float mx = fmaxf(fmaxf(fmaxf(sv[1][2], sv[1][3]), mxa), mxb);
;         if (MODE == 2) mx = selok ? mx : -__builtin_inff();
;         if (__any(mx > m[r] + 8.0f)) {
;           mx = fmaxf(mx, __shfl_xor(mx, 16)); mx = fmaxf(mx, __shfl_xor(mx, 32));
;           const float mn = fmaxf(m[r], mx), al = __builtin_amdgcn_exp2f(m[r] - mn);
;           m[r] = mn; l[r] *= al;
;           if (MODE != 0) {
; #pragma unroll
.LBB0_395:
	v_add_f32_e32 v104, 0, v168
	v_add_f32_e32 v104, v169, v104
	v_add_f32_e32 v104, v170, v104
	v_add_f32_e32 v104, v171, v104
	v_add_f32_e32 v104, v172, v104
	v_add_f32_e32 v104, v173, v104
	v_add_f32_e32 v104, v174, v104
	v_add_f32_e32 v104, v175, v104
	v_add_f32_e32 v197, v197, v104
	s_mov_b64 s[30:31], -1
	s_cmp_lt_i32 s42, 0
	s_mov_b64 s[36:37], -1
	s_cbranch_scc1 .LBB0_413
	v_mov_b32 v104, v179
	s_nop 0
	v_lshrrev_b32_e32 v105, 4, v104
	v_bfe_u32 v112, v104, 4, 2
	v_and_b32_e32 v113, 7, v104
	v_and_b32_e32 v200, 15, v104
	v_lshlrev_b32_e32 v201, 2, v112
	v_bitop3_b32 v104, v105, v113, 3 bitop3:0x6c
	v_bitop3_b32 v112, v112, v113, 4 bitop3:0x36
	v_lshlrev_b32_e32 v114, 7, v200
	v_lshl_add_u32 v104, v104, 4, s64
	v_lshl_add_u32 v112, v112, 4, s64
	v_add_u32_e32 v198, v104, v114
	v_add_u32_e32 v199, v112, v114
	ds_read_b128 v[104:107], v198
	ds_read_b128 v[108:111], v198 offset:2048
	ds_read_b128 v[112:115], v199
	ds_read_b128 v[116:119], v199 offset:2048
	s_setprio 1
	s_waitcnt lgkmcnt(3)
	v_mfma_f32_16x16x32_bf16 v[120:123], v[104:107], v[0:3], 0
	v_mfma_f32_16x16x32_bf16 v[104:107], v[104:107], v[8:11], 0
	s_waitcnt lgkmcnt(2)
	v_mfma_f32_16x16x32_bf16 v[128:131], v[108:111], v[0:3], 0
	v_mfma_f32_16x16x32_bf16 v[108:111], v[108:111], v[8:11], 0
	s_waitcnt lgkmcnt(1)
	v_mfma_f32_16x16x32_bf16 v[168:171], v[112:115], v[4:7], v[120:123]
	v_mfma_f32_16x16x32_bf16 v[124:127], v[112:115], v[12:15], v[104:107]
	s_waitcnt lgkmcnt(0)
	v_mfma_f32_16x16x32_bf16 v[104:107], v[116:119], v[4:7], v[128:131]
	v_mfma_f32_16x16x32_bf16 v[120:123], v[116:119], v[12:15], v[108:111]
	s_setprio 0
	s_nop 1
	v_sub_u32_e32 v108, v180, v201
	v_lshl_add_u32 v108, v108, 2, v235
	s_lshl_b32 s30, s42, 8
	v_subrev_u32_e32 v176, s30, v108
	ds_read2_b32 v[134:135], v176 offset0:63 offset1:64
	ds_read2_b32 v[132:133], v176 offset0:61 offset1:62
	ds_read2_b32 v[128:129], v176 offset0:47 offset1:48
	ds_read2_b32 v[130:131], v176 offset0:45 offset1:46
	s_waitcnt lgkmcnt(3)
	v_fmamk_f32 v135, v168, 0x3e38aa3b, v135
	v_fmac_f32_e32 v134, 0x3e38aa3b, v169
	s_waitcnt lgkmcnt(2)
	v_fmamk_f32 v133, v170, 0x3e38aa3b, v133
	v_fmac_f32_e32 v132, 0x3e38aa3b, v171
	s_waitcnt lgkmcnt(1)
	v_fmamk_f32 v129, v104, 0x3e38aa3b, v129
	v_fmac_f32_e32 v128, 0x3e38aa3b, v105
	s_waitcnt lgkmcnt(0)
	v_fmamk_f32 v131, v106, 0x3e38aa3b, v131
	v_fmac_f32_e32 v130, 0x3e38aa3b, v107
	v_max3_f32 v104, v135, v134, v133
	v_max3_f32 v105, v132, v129, v128
	v_max_f32_e32 v106, v131, v130
	v_max3_f32 v104, v106, v104, v105
	v_add_f32_e32 v105, 0x41000000, v192
	v_cmp_gt_f32_e32 vcc, v104, v105
	s_cbranch_vccz .LBB0_398
	ds_bpermute_b32 v105, v233, v104
	v_max_f32_e32 v104, v104, v104
	v_mov_b32_e32 v169, v193
	v_mov_b32_e32 v191, v197
	s_waitcnt lgkmcnt(0)
	v_max_f32_e32 v105, v105, v105
	v_max_f32_e32 v104, v104, v105
	ds_bpermute_b32 v105, v234, v104
	s_waitcnt lgkmcnt(0)
	v_max3_f32 v168, v192, v104, v105
	v_sub_f32_e32 v104, v192, v168
	v_exp_f32_e32 v116, v104
	v_mov_b64_e32 v[192:193], v[168:169]
	v_mul_f32_e32 v190, v196, v116
	v_pk_mul_f32 v[106:107], v[138:139], v[116:117] op_sel_hi:[1,0]
	v_pk_mul_f32 v[104:105], v[136:137], v[116:117] op_sel_hi:[1,0]
	v_pk_mul_f32 v[110:111], v[158:159], v[116:117] op_sel_hi:[1,0]
	v_pk_mul_f32 v[108:109], v[156:157], v[116:117] op_sel_hi:[1,0]
	v_pk_mul_f32 v[114:115], v[162:163], v[116:117] op_sel_hi:[1,0]
	v_pk_mul_f32 v[112:113], v[160:161], v[116:117] op_sel_hi:[1,0]
	v_pk_mul_f32 v[118:119], v[166:167], v[116:117] op_sel_hi:[1,0]
	v_pk_mul_f32 v[116:117], v[164:165], v[116:117] op_sel_hi:[1,0]
	v_cmp_lt_f32_e32 vcc, 0xefa18f08, v168
	s_nop 1
	v_cndmask_b32_e32 v230, 0, v168, vcc
	s_branch .LBB0_399

; template <int MODE>
; __device__ __forceinline__ void nsa_compute(int cur, int buf, int t, int hl, u64 mymask, const bf16x8 (&Qf)[2][2], f32x4 (&O)[4][2], float (&m)[2], float (&l)[2],
;                                             const float (&inv)[2], float* impw, char* lds) {
;     ...
;         const float mxa = fmaxf(fmaxf(sv[0][0], sv[0][1]), sv[0][2]), mxb = fmaxf(fmaxf(sv[0][3], sv[1][0]), sv[1][1]);
;         float mx = fmaxf(fmaxf(fmaxf(sv[1][2], sv[1][3]), mxa), mxb);
;         if (MODE == 2) mx = selok ? mx : -__builtin_inff();
;         if (__any(mx > m[r] + 8.0f)) {
;           mx = fmaxf(mx, __shfl_xor(mx, 16)); mx = fmaxf(mx, __shfl_xor(mx, 32));
;           const float mn = fmaxf(m[r], mx), al = __builtin_amdgcn_exp2f(m[r] - mn);
;           m[r] = mn; l[r] *= al;
;           if (MODE != 0) {
; #pragma unroll
;             for (int df = 0; df < 4; ++df) O[df][r] *= al;
;           }
;         }
;         const float me = (MODE == 2) ? (selok ? m[r] : __builtin_inff()) : m[r];
;         float ps = 0.f;
; #pragma unroll
;         for (int kk = 0; kk < 2; ++kk)
; #pragma unroll
;           for (int e = 0; e < 4; ++e) { pv[kk][e] = __builtin_amdgcn_exp2f(sv[kk][e] - me); ps += pv[kk][e]; }
;         l[r] += ps;
.LBB0_399:
	v_sub_f32_e32 v135, v135, v168
	v_exp_f32_e32 v202, v135
	v_sub_f32_e32 v134, v134, v168
	v_exp_f32_e32 v203, v134
	v_sub_f32_e32 v133, v133, v168
	v_exp_f32_e32 v204, v133
	v_sub_f32_e32 v132, v132, v168
	v_exp_f32_e32 v205, v132
	v_sub_f32_e32 v129, v129, v168
	v_add_f32_e32 v135, 0, v202
	v_exp_f32_e32 v206, v129
	v_sub_f32_e32 v128, v128, v168
	v_add_f32_e32 v134, v203, v135
	v_exp_f32_e32 v207, v128
	v_add_f32_e32 v133, v204, v134
	v_add_f32_e32 v132, v205, v133
	v_add_f32_e32 v129, v206, v132
	v_add_f32_e32 v128, v207, v129
	v_sub_f32_e32 v129, v131, v168
	v_exp_f32_e32 v236, v129
	v_sub_f32_e32 v129, v130, v168
	v_exp_f32_e32 v237, v129
	v_add_f32_e32 v128, v236, v128
	v_add_f32_e32 v128, v237, v128
	v_add_f32_e32 v190, v190, v128
	v_add_u32_e32 v128, 0xafc, v176
	ds_read2_b32 v[172:173], v128 offset1:1
	s_waitcnt lgkmcnt(0)
	v_fmamk_f32 v173, v124, 0x3e38aa3b, v173
	v_add_u32_e32 v124, 0xaf4, v176
	ds_read2_b32 v[174:175], v124 offset1:1
	v_add_u32_e32 v124, 0xabc, v176
	v_fmac_f32_e32 v172, 0x3e38aa3b, v125
	ds_read2_b32 v[124:125], v124 offset1:1
	s_waitcnt lgkmcnt(1)
	v_fmamk_f32 v175, v126, 0x3e38aa3b, v175
	v_fmac_f32_e32 v174, 0x3e38aa3b, v127
	s_waitcnt lgkmcnt(0)
	v_fmamk_f32 v125, v120, 0x3e38aa3b, v125
	v_add_u32_e32 v120, 0xab4, v176
	ds_read2_b32 v[126:127], v120 offset1:1
	v_fmac_f32_e32 v124, 0x3e38aa3b, v121
	v_max3_f32 v120, v173, v172, v175
	v_max3_f32 v121, v174, v125, v124
	s_waitcnt lgkmcnt(0)
	v_fmamk_f32 v127, v122, 0x3e38aa3b, v127
	v_fmac_f32_e32 v126, 0x3e38aa3b, v123
	v_max_f32_e32 v122, v127, v126
	v_max3_f32 v120, v122, v120, v121
	v_add_f32_e32 v121, 0x41000000, v193
	v_cmp_gt_f32_e32 vcc, v120, v121
	s_cbranch_vccz .LBB0_401
	ds_bpermute_b32 v121, v233, v120
	v_max_f32_e32 v120, v120, v120
	s_waitcnt lgkmcnt(0)
	v_max_f32_e32 v121, v121, v121
	v_max_f32_e32 v120, v120, v121
	ds_bpermute_b32 v121, v234, v120
	s_waitcnt lgkmcnt(0)
	v_max3_f32 v238, v193, v120, v121
	v_sub_f32_e32 v120, v193, v238
	v_exp_f32_e32 v168, v120
	v_mov_b32_e32 v193, v238
	v_mul_f32_e32 v191, v191, v168
	v_pk_mul_f32 v[122:123], v[142:143], v[168:169] op_sel_hi:[1,0]
	v_pk_mul_f32 v[120:121], v[140:141], v[168:169] op_sel_hi:[1,0]
	v_pk_mul_f32 v[130:131], v[146:147], v[168:169] op_sel_hi:[1,0]
	v_pk_mul_f32 v[128:129], v[144:145], v[168:169] op_sel_hi:[1,0]
	v_pk_mul_f32 v[134:135], v[150:151], v[168:169] op_sel_hi:[1,0]
	v_pk_mul_f32 v[132:133], v[148:149], v[168:169] op_sel_hi:[1,0]
	v_pk_mul_f32 v[170:171], v[154:155], v[168:169] op_sel_hi:[1,0]
	v_pk_mul_f32 v[168:169], v[152:153], v[168:169] op_sel_hi:[1,0]
	v_cmp_lt_f32_e32 vcc, 0xefa18f08, v238
	s_nop 1
	v_cndmask_b32_e32 v231, 0, v238, vcc
	s_branch .LBB0_402

; template <int MODE>
; __device__ __forceinline__ void nsa_compute(int cur, int buf, int t, int hl, u64 mymask, const bf16x8 (&Qf)[2][2], f32x4 (&O)[4][2], float (&m)[2], float (&l)[2],
;                                             const float (&inv)[2], float* impw, char* lds) {
;     ...
; #pragma unroll
;     for (int ks = 0; ks < 2; ++ks)
; #pragma unroll
;       for (int kk = 0; kk < 2; ++kk) kfr[ks][kk] = *(const bf16x8*)(kt + (32 * s2 + 16 * kk + fr) * 128 + (((ks * 4 + fq) ^ (fr & 7)) << 4));
;     __builtin_amdgcn_s_setprio(1);
; #pragma unroll
;     for (int ks = 0; ks < 2; ++ks)
; #pragma unroll
;       for (int kk = 0; kk < 2; ++kk)
; #pragma unroll
;         for (int r = 0; r < 2; ++r) S[kk][r] = mfma16(kfr[ks][kk], Qf[r][ks], S[kk][r]);
;     __builtin_amdgcn_s_setprio(0);
;     bf16x8 Pf[2];
;     float g1s[2] = {0.f, 0.f}, p3s[2] = {0.f, 0.f};
; #pragma unroll
;     for (int r = 0; r < 2; ++r) {
;       float sv[2][4];
; #pragma unroll
;       for (int kk = 0; kk < 2; ++kk)
; #pragma unroll
;         for (int e = 0; e < 4; ++e) {
;     ...
;         const float me = (MODE == 2) ? (selok ? m[r] : __builtin_inff()) : m[r];
;         float ps = 0.f;
; #pragma unroll
;         for (int kk = 0; kk < 2; ++kk)
; #pragma unroll
;           for (int e = 0; e < 4; ++e) { pv[kk][e] = __builtin_amdgcn_exp2f(sv[kk][e] - me); ps += pv[kk][e]; }
;         l[r] += ps;
;       }
;       if (MODE != 0) {
;         const unsigned w0 = pk2(pv[0][0], pv[0][1]), w1 = pk2(pv[0][2], pv[0][3]), w2 = pk2(pv[1][0], pv[1][1]), w3 = pk2(pv[1][2], pv[1][3]);
;         u32x4 pw; pw.x = w0; pw.y = w1; pw.z = w2; pw.w = w3;
;         Pf[r] = __builtin_bit_cast(bf16x8, pw);
;       }
;     }
;     if (MODE != 0) {
;       bf16x8 vfr[4];
; #pragma unroll
;       for (int df = 0; df < 4; ++df) {
;         const bf16x4 va = *(const bf16x4*)(vt + (df * 16 + fr) * 68 + 32 * s2 + 4 * fq);
;         const bf16x4 vb = *(const bf16x4*)(vt + (df * 16 + fr) * 68 + 32 * s2 + 16 + 4 * fq);
;         bf16x8 vf; vf[0] = va[0]; vf[1] = va[1]; vf[2] = va[2]; vf[3] = va[3]; vf[4] = vb[0]; vf[5] = vb[1]; vf[6] = vb[2]; vf[7] = vb[3];
;         vfr[df] = vf;
;       }
;       __builtin_amdgcn_s_setprio(1);
; #pragma unroll
;       for (int df = 0; df < 4; ++df)
; #pragma unroll
;         for (int r = 0; r < 2; ++r) O[df][r] = mfma16(vfr[df], Pf[r], O[df][r]);
;       __builtin_amdgcn_s_setprio(0);
.LBB0_402:
	v_sub_f32_e32 v173, v173, v238
	v_exp_f32_e32 v173, v173
	v_sub_f32_e32 v172, v172, v238
	v_exp_f32_e32 v172, v172
	v_sub_f32_e32 v175, v175, v238
	v_exp_f32_e32 v175, v175
	v_sub_f32_e32 v174, v174, v238
	v_exp_f32_e32 v174, v174
	v_sub_f32_e32 v125, v125, v238
	v_cvt_pk_bf16_f32 v202, v202, v203
	v_cvt_pk_bf16_f32 v203, v204, v205
	v_cvt_pk_bf16_f32 v204, v206, v207
	v_add_f32_e32 v206, 0, v173
	v_exp_f32_e32 v125, v125
	v_sub_f32_e32 v124, v124, v238
	v_add_f32_e32 v206, v172, v206
	v_exp_f32_e32 v124, v124
	v_add_f32_e32 v206, v175, v206
	v_add_f32_e32 v206, v174, v206
	v_sub_f32_e32 v127, v127, v238
	v_add_f32_e32 v206, v125, v206
	v_exp_f32_e32 v127, v127
	v_sub_f32_e32 v126, v126, v238
	v_add_f32_e32 v206, v124, v206
	v_exp_f32_e32 v126, v126
	v_cvt_pk_bf16_f32 v172, v173, v172
	v_cvt_pk_bf16_f32 v173, v175, v174
	v_cvt_pk_bf16_f32 v174, v125, v124
	v_mul_u32_u24_e32 v124, 0x44, v200
	v_lshlrev_b32_e32 v124, 1, v124
	v_lshlrev_b32_e32 v125, 1, v201
	v_add3_u32 v200, s43, v124, v125
	v_cvt_pk_bf16_f32 v205, v236, v237
	v_add_f32_e32 v206, v127, v206
	v_add_u32_e32 v236, 0x4000, v200
	v_add_u32_e32 v237, 0x4800, v200
	v_add_f32_e32 v206, v126, v206
	v_cvt_pk_bf16_f32 v175, v127, v126
	ds_read2_b64 v[124:127], v236 offset1:4
	ds_read2_b64 v[240:243], v237 offset0:16 offset1:20
	v_add_u32_e32 v238, 0x5000, v200
	v_add_u32_e32 v239, 0x5800, v200
	ds_read2_b64 v[244:247], v238 offset0:32 offset1:36
	ds_read2_b64 v[248:251], v239 offset0:48 offset1:52
	v_add_f32_e32 v191, v191, v206
	s_setprio 1
	s_waitcnt lgkmcnt(3)
	v_mfma_f32_16x16x32_bf16 v[104:107], v[124:127], v[202:205], v[104:107]
	v_mfma_f32_16x16x32_bf16 v[124:127], v[124:127], v[172:175], v[120:123]
	s_waitcnt lgkmcnt(2)
	v_mfma_f32_16x16x32_bf16 v[108:111], v[240:243], v[202:205], v[108:111]
	v_mfma_f32_16x16x32_bf16 v[128:131], v[240:243], v[172:175], v[128:131]
	s_waitcnt lgkmcnt(1)
	v_mfma_f32_16x16x32_bf16 v[112:115], v[244:247], v[202:205], v[112:115]
	v_mfma_f32_16x16x32_bf16 v[132:135], v[244:247], v[172:175], v[132:135]
	s_waitcnt lgkmcnt(0)
	v_mfma_f32_16x16x32_bf16 v[120:123], v[248:251], v[202:205], v[116:119]
	v_mfma_f32_16x16x32_bf16 v[168:171], v[248:251], v[172:175], v[168:171]
	s_setprio 0
	s_nop 0
	ds_read_b128 v[116:119], v198 offset:4096
	ds_read_b128 v[172:175], v198 offset:6144
	ds_read_b128 v[200:203], v199 offset:4096
	ds_read_b128 v[204:207], v199 offset:6144
	s_setprio 1
	s_waitcnt lgkmcnt(3)
	v_mfma_f32_16x16x32_bf16 v[240:243], v[116:119], v[0:3], 0
	v_mfma_f32_16x16x32_bf16 v[116:119], v[116:119], v[8:11], 0
	s_waitcnt lgkmcnt(2)
	v_mfma_f32_16x16x32_bf16 v[248:251], v[172:175], v[8:11], 0
	v_mfma_f32_16x16x32_bf16 v[244:247], v[172:175], v[0:3], 0
	s_waitcnt lgkmcnt(1)
	v_mfma_f32_16x16x32_bf16 v[172:175], v[200:203], v[12:15], v[116:119]
	s_waitcnt lgkmcnt(0)
	v_mfma_f32_16x16x32_bf16 v[116:119], v[204:207], v[12:15], v[248:251]
	v_mfma_f32_16x16x32_bf16 v[208:211], v[200:203], v[4:7], v[240:243]
	v_mfma_f32_16x16x32_bf16 v[242:245], v[204:207], v[4:7], v[244:247]
	s_setprio 0
	ds_read2_b32 v[204:205], v176 offset0:31 offset1:32
	ds_read2_b32 v[202:203], v176 offset0:29 offset1:30
	ds_read2_b32 v[200:201], v176 offset0:15 offset1:16
	ds_read2_b32 v[198:199], v176 offset0:13 offset1:14
	s_waitcnt lgkmcnt(3)
	s_nop 0
	v_fmamk_f32 v241, v208, 0x3e38aa3b, v205
	v_fmac_f32_e32 v204, 0x3e38aa3b, v209
	s_waitcnt lgkmcnt(2)
	v_fmamk_f32 v240, v210, 0x3e38aa3b, v203
	v_fmac_f32_e32 v202, 0x3e38aa3b, v211
	s_waitcnt lgkmcnt(1)
	v_fmamk_f32 v205, v242, 0x3e38aa3b, v201
	v_fmac_f32_e32 v200, 0x3e38aa3b, v243
	s_waitcnt lgkmcnt(0)
	v_fmamk_f32 v199, v244, 0x3e38aa3b, v199
	v_fmac_f32_e32 v198, 0x3e38aa3b, v245
	v_max3_f32 v201, v241, v204, v240
	v_max3_f32 v203, v202, v205, v200
	v_max_f32_e32 v206, v199, v198
	v_max3_f32 v201, v206, v201, v203
	v_add_f32_e32 v203, 0x41000000, v192
	v_cmp_gt_f32_e32 vcc, v201, v203
	s_cbranch_vccz .LBB0_404
	ds_bpermute_b32 v203, v233, v201
	v_max_f32_e32 v201, v201, v201
	v_mov_b32_e32 v207, v193
	s_waitcnt lgkmcnt(0)
	v_max_f32_e32 v203, v203, v203
	v_max_f32_e32 v201, v201, v203
	ds_bpermute_b32 v203, v234, v201
	s_waitcnt lgkmcnt(0)
	v_max3_f32 v206, v192, v201, v203
	v_sub_f32_e32 v192, v192, v206
	v_exp_f32_e32 v192, v192
	s_nop 0
	v_mul_f32_e32 v190, v190, v192
	v_pk_mul_f32 v[106:107], v[106:107], v[192:193] op_sel_hi:[1,0]
	v_pk_mul_f32 v[104:105], v[104:105], v[192:193] op_sel_hi:[1,0]
	v_pk_mul_f32 v[110:111], v[110:111], v[192:193] op_sel_hi:[1,0]
	v_pk_mul_f32 v[108:109], v[108:109], v[192:193] op_sel_hi:[1,0]
	v_pk_mul_f32 v[114:115], v[114:115], v[192:193] op_sel_hi:[1,0]
	v_pk_mul_f32 v[112:113], v[112:113], v[192:193] op_sel_hi:[1,0]
	v_pk_mul_f32 v[122:123], v[122:123], v[192:193] op_sel_hi:[1,0]
	v_pk_mul_f32 v[120:121], v[120:121], v[192:193] op_sel_hi:[1,0]
	v_mov_b64_e32 v[192:193], v[206:207]
	v_cmp_lt_f32_e32 vcc, 0xefa18f08, v206
	s_nop 1
	v_cndmask_b32_e32 v230, 0, v206, vcc
	s_branch .LBB0_405

; template <int MODE>
; __device__ __forceinline__ void nsa_compute(int cur, int buf, int t, int hl, u64 mymask, const bf16x8 (&Qf)[2][2], f32x4 (&O)[4][2], float (&m)[2], float (&l)[2],
;                                             const float (&inv)[2], float* impw, char* lds) {
;     ...
;         const float mxa = fmaxf(fmaxf(sv[0][0], sv[0][1]), sv[0][2]), mxb = fmaxf(fmaxf(sv[0][3], sv[1][0]), sv[1][1]);
;         float mx = fmaxf(fmaxf(fmaxf(sv[1][2], sv[1][3]), mxa), mxb);
;         if (MODE == 2) mx = selok ? mx : -__builtin_inff();
;         if (__any(mx > m[r] + 8.0f)) {
;           mx = fmaxf(mx, __shfl_xor(mx, 16)); mx = fmaxf(mx, __shfl_xor(mx, 32));
;           const float mn = fmaxf(m[r], mx), al = __builtin_amdgcn_exp2f(m[r] - mn);
;           m[r] = mn; l[r] *= al;
;           if (MODE != 0) {
; #pragma unroll
;             for (int df = 0; df < 4; ++df) O[df][r] *= al;
;           }
;         }
;         const float me = (MODE == 2) ? (selok ? m[r] : __builtin_inff()) : m[r];
;         float ps = 0.f;
; #pragma unroll
;         for (int kk = 0; kk < 2; ++kk)
; #pragma unroll
;           for (int e = 0; e < 4; ++e) { pv[kk][e] = __builtin_amdgcn_exp2f(sv[kk][e] - me); ps += pv[kk][e]; }
;         l[r] += ps;
.LBB0_405:
	v_sub_f32_e32 v201, v241, v206
	v_exp_f32_e32 v201, v201
	v_sub_f32_e32 v203, v204, v206
	v_exp_f32_e32 v203, v203
	v_sub_f32_e32 v204, v240, v206
	v_exp_f32_e32 v204, v204
	v_sub_f32_e32 v202, v202, v206
	v_exp_f32_e32 v202, v202
	v_sub_f32_e32 v205, v205, v206
	v_add_f32_e32 v207, 0, v201
	v_exp_f32_e32 v205, v205
	v_sub_f32_e32 v200, v200, v206
	v_add_f32_e32 v207, v203, v207
	v_exp_f32_e32 v200, v200
	v_add_f32_e32 v207, v204, v207
	v_add_f32_e32 v207, v202, v207
	v_add_f32_e32 v207, v205, v207
	v_sub_f32_e32 v199, v199, v206
	v_add_f32_e32 v208, v200, v207
	v_exp_f32_e32 v207, v199
	v_sub_f32_e32 v198, v198, v206
	v_exp_f32_e32 v206, v198
	v_add_f32_e32 v199, v207, v208
	v_add_f32_e32 v198, v206, v199
	v_add_f32_e32 v190, v190, v198
	v_add_u32_e32 v198, 0xa7c, v176
	ds_read2_b32 v[198:199], v198 offset1:1
	s_waitcnt lgkmcnt(0)
	v_fmamk_f32 v199, v172, 0x3e38aa3b, v199
	v_add_u32_e32 v172, 0xa74, v176
	v_fmac_f32_e32 v198, 0x3e38aa3b, v173
	ds_read2_b32 v[172:173], v172 offset1:1
	s_waitcnt lgkmcnt(0)
	v_fmamk_f32 v173, v174, 0x3e38aa3b, v173
	v_add_u32_e32 v174, 0xa3c, v176
	v_fmac_f32_e32 v172, 0x3e38aa3b, v175
	ds_read2_b32 v[174:175], v174 offset1:1
	s_waitcnt lgkmcnt(0)
	v_fmamk_f32 v240, v116, 0x3e38aa3b, v175
	v_add_u32_e32 v116, 0xa34, v176
	v_fmac_f32_e32 v174, 0x3e38aa3b, v117
	ds_read2_b32 v[116:117], v116 offset1:1
	s_waitcnt lgkmcnt(0)
	v_fmamk_f32 v117, v118, 0x3e38aa3b, v117
	v_fmac_f32_e32 v116, 0x3e38aa3b, v119
	v_max3_f32 v118, v199, v198, v173
	v_max3_f32 v119, v172, v240, v174
	v_max_f32_e32 v175, v117, v116
	v_max3_f32 v118, v175, v118, v119
	v_add_f32_e32 v119, 0x41000000, v193
	v_cmp_gt_f32_e32 vcc, v118, v119
	s_cbranch_vccz .LBB0_407
	ds_bpermute_b32 v119, v233, v118
	v_max_f32_e32 v118, v118, v118
	s_waitcnt lgkmcnt(0)
	v_max_f32_e32 v119, v119, v119
	v_max_f32_e32 v118, v118, v119
	ds_bpermute_b32 v119, v234, v118
	s_waitcnt lgkmcnt(0)
	v_max3_f32 v118, v193, v118, v119
	v_sub_f32_e32 v119, v193, v118
	v_exp_f32_e32 v176, v119
	v_mov_b32_e32 v193, v118
	v_mul_f32_e32 v191, v191, v176
	v_pk_mul_f32 v[126:127], v[126:127], v[176:177] op_sel_hi:[1,0]
	v_pk_mul_f32 v[124:125], v[124:125], v[176:177] op_sel_hi:[1,0]
	v_pk_mul_f32 v[130:131], v[130:131], v[176:177] op_sel_hi:[1,0]
	v_pk_mul_f32 v[128:129], v[128:129], v[176:177] op_sel_hi:[1,0]
	v_pk_mul_f32 v[134:135], v[134:135], v[176:177] op_sel_hi:[1,0]
	v_pk_mul_f32 v[132:133], v[132:133], v[176:177] op_sel_hi:[1,0]
	v_pk_mul_f32 v[170:171], v[170:171], v[176:177] op_sel_hi:[1,0]
	v_pk_mul_f32 v[168:169], v[168:169], v[176:177] op_sel_hi:[1,0]
	v_cmp_lt_f32_e32 vcc, 0xefa18f08, v118
	s_nop 1
	v_cndmask_b32_e32 v231, 0, v118, vcc
	s_branch .LBB0_408

; template <int MODE>
; __device__ __forceinline__ void nsa_compute(int cur, int buf, int t, int hl, u64 mymask, const bf16x8 (&Qf)[2][2], f32x4 (&O)[4][2], float (&m)[2], float (&l)[2],
;                                             const float (&inv)[2], float* impw, char* lds) {
;     ...
;   const bool selok = (MODE == 2) ? (((mymask >> cur) & 1ull) != 0ull) : true;
;   const float* tb = (MODE == 3) ? (const float*)(lds + NSA_TW) + hl * 640 : (const float*)(lds + NSA_T) + hl * 4160;
;   constexpr int TS = (MODE == 3) ? 640 : 4160;
;   const int base = (MODE <= 1) ? (t - 31 - 16 * (cur * 64 + 4 * fq) + 64) : (t - cur * 64 - 4 * fq + 64);
; #pragma unroll
;   for (int s2 = 0; s2 < 2; ++s2) {
;     f32x4 S[2][2] = {};
;     bf16x8 kfr[2][2];
; #pragma unroll
;     for (int ks = 0; ks < 2; ++ks)
; #pragma unroll
;       for (int kk = 0; kk < 2; ++kk) kfr[ks][kk] = *(const bf16x8*)(kt + (32 * s2 + 16 * kk + fr) * 128 + (((ks * 4 + fq) ^ (fr & 7)) << 4));
;     __builtin_amdgcn_s_setprio(1);
; #pragma unroll
;     for (int ks = 0; ks < 2; ++ks)
; #pragma unroll
;       for (int kk = 0; kk < 2; ++kk)
; #pragma unroll
;         for (int r = 0; r < 2; ++r) S[kk][r] = mfma16(kfr[ks][kk], Qf[r][ks], S[kk][r]);
;     __builtin_amdgcn_s_setprio(0);
;     bf16x8 Pf[2];
;     float g1s[2] = {0.f, 0.f}, p3s[2] = {0.f, 0.f};
; #pragma unroll
;     for (int r = 0; r < 2; ++r) {
;       float sv[2][4];
; #pragma unroll
;       for (int kk = 0; kk < 2; ++kk)
; #pragma unroll
;         for (int e = 0; e < 4; ++e) {
;           const int off = 32 * s2 + 16 * kk + e;
;           int idx;
;           if (MODE <= 1) { idx = base - 16 * off; idx = idx > 0 ? idx : 0; } else idx = base - off;
;           sv[kk][e] = S[kk][r][e] * (0.125f * LOG2E) + tb[r * TS + idx];
;         }
;       float pv[2][4];
;       if (MODE == 1) {
; #pragma unroll
;         for (int kk = 0; kk < 2; ++kk)
; #pragma unroll
;           for (int e = 0; e < 4; ++e) pv[kk][e] = __builtin_amdgcn_exp2f(sv[kk][e] - m[r]) * inv[r];
; #pragma unroll
;         for (int kk = 0; kk < 2; ++kk) { g1s[kk] += pv[kk][0] + pv[kk][1] + pv[kk][2] + 0.5f * pv[kk][3]; p3s[kk] += 0.5f * pv[kk][3]; }
;       } else {
;         const float mxa = fmaxf(fmaxf(sv[0][0], sv[0][1]), sv[0][2]), mxb = fmaxf(fmaxf(sv[0][3], sv[1][0]), sv[1][1]);
;         float mx = fmaxf(fmaxf(fmaxf(sv[1][2], sv[1][3]), mxa), mxb);
.LBB0_436:
	s_mov_b32 s17, s75
	s_lshl_b64 s[30:31], 1, s17
	v_mov_b32 v74, v179
	v_and_b32_e32 v73, s31, v187
	v_lshrrev_b32_e32 v75, 4, v74
	v_bfe_u32 v80, v74, 4, 2
	v_and_b32_e32 v72, s30, v186
	v_and_b32_e32 v81, 7, v74
	v_and_b32_e32 v94, 15, v74
	s_lshl_b32 s63, s74, 13
	v_cmp_eq_u64_e64 s[36:37], 0, v[72:73]
	v_lshlrev_b32_e32 v95, 2, v80
	v_bitop3_b32 v72, v75, v81, 3 bitop3:0x6c
	v_bitop3_b32 v80, v80, v81, 4 bitop3:0x36
	v_lshlrev_b32_e32 v91, 7, v94
	v_lshl_or_b32 v92, v72, 4, s63
	v_lshl_or_b32 v93, v80, 4, s63
	v_or_b32_e32 v76, v92, v91
	v_or_b32_e32 v84, v93, v91
	ds_read_b128 v[72:75], v76
	ds_read_b128 v[76:79], v76 offset:2048
	ds_read_b128 v[80:83], v84
	ds_read_b128 v[84:87], v84 offset:2048
	s_mov_b32 s75, s46
	v_sub_u32_e32 v251, v180, v95
	v_lshl_add_u32 v251, v251, 2, v181
	s_lshl_b32 s17, s17, 8
	v_subrev_u32_e32 v250, s17, v251
	v_add_u32_e32 v249, 0x8400, v250
	v_add_u32_e32 v248, 0xc500, v250
	ds_read2_b32 v[114:115], v249 offset0:63 offset1:64
	ds_read2_b32 v[116:117], v249 offset0:61 offset1:62
	ds_read2_b32 v[118:119], v249 offset0:47 offset1:48
	ds_read2_b32 v[138:139], v249 offset0:45 offset1:46
	ds_read2_b32 v[140:141], v248 offset0:63 offset1:64
	ds_read2_b32 v[142:143], v248 offset0:61 offset1:62
	ds_read2_b32 v[144:145], v248 offset0:47 offset1:48
	ds_read2_b32 v[148:149], v248 offset0:45 offset1:46
	s_setprio 1
	s_waitcnt lgkmcnt(11)
	v_mfma_f32_16x16x32_bf16 v[96:99], v[72:75], v[0:3], 0
	v_mfma_f32_16x16x32_bf16 v[72:75], v[72:75], v[8:11], 0
	s_waitcnt lgkmcnt(10)
	v_mfma_f32_16x16x32_bf16 v[104:107], v[76:79], v[8:11], 0
	v_mfma_f32_16x16x32_bf16 v[100:103], v[76:79], v[0:3], 0
	s_waitcnt lgkmcnt(9)
	v_mfma_f32_16x16x32_bf16 v[96:99], v[80:83], v[4:7], v[96:99]
	v_mfma_f32_16x16x32_bf16 v[76:79], v[80:83], v[12:15], v[72:75]
	s_waitcnt lgkmcnt(8)
	v_mfma_f32_16x16x32_bf16 v[72:75], v[84:87], v[12:15], v[104:107]
	v_mfma_f32_16x16x32_bf16 v[100:103], v[84:87], v[4:7], v[100:103]
	s_setprio 0
	v_cndmask_b32_e64 v232, v230, v228, s[36:37]
	s_waitcnt lgkmcnt(4)
	v_sub_f32_e32 v115, v115, v232
	v_sub_f32_e32 v114, v114, v232
	v_sub_f32_e32 v117, v117, v232
	v_sub_f32_e32 v116, v116, v232
	v_sub_f32_e32 v119, v119, v232
	v_sub_f32_e32 v118, v118, v232
	v_sub_f32_e32 v139, v139, v232
	v_sub_f32_e32 v138, v138, v232
	v_cndmask_b32_e64 v232, v231, v228, s[36:37]
	s_waitcnt lgkmcnt(0)
	v_sub_f32_e32 v141, v141, v232
	v_sub_f32_e32 v140, v140, v232
	v_sub_f32_e32 v143, v143, v232
	v_sub_f32_e32 v142, v142, v232
	v_sub_f32_e32 v145, v145, v232
	v_sub_f32_e32 v144, v144, v232
	v_sub_f32_e32 v149, v149, v232
	v_sub_f32_e32 v148, v148, v232
	v_sub_u32_e32 v80, v180, v95
	v_lshl_add_u32 v80, v80, 2, v181
	v_subrev_u32_e32 v90, s17, v80
	s_waitcnt lgkmcnt(7)
	v_fmamk_f32 v87, v96, 0x3e38aa3b, v115
	v_fmamk_f32 v86, v97, 0x3e38aa3b, v114
	s_waitcnt lgkmcnt(6)
	v_fmamk_f32 v83, v98, 0x3e38aa3b, v117
	v_fmamk_f32 v82, v99, 0x3e38aa3b, v116
	s_waitcnt lgkmcnt(5)
	v_fmamk_f32 v81, v100, 0x3e38aa3b, v119
	v_fmamk_f32 v80, v101, 0x3e38aa3b, v118
	s_waitcnt lgkmcnt(4)
	v_fmamk_f32 v97, v102, 0x3e38aa3b, v139
	v_fmamk_f32 v84, v103, 0x3e38aa3b, v138
	v_max3_f32 v85, v87, v86, v83
	v_max3_f32 v88, v82, v81, v80
	v_max_f32_e32 v89, v97, v84
	v_max3_f32 v85, v89, v85, v88
	v_cndmask_b32_e64 v85, v85, v225, s[36:37]
	v_sub_f32_e32 v88, v188, v230
	v_add_f32_e32 v88, 0x41000000, v88
	v_cmp_gt_f32_e32 vcc, v85, v88
	s_cbranch_vccz .LBB0_438
	v_add_f32_e32 v85, v85, v230
	ds_bpermute_b32 v88, v233, v85
	v_max_f32_e32 v85, v85, v85
	v_mov_b32_e32 v89, v189
	s_waitcnt lgkmcnt(0)
	v_max_f32_e32 v88, v88, v88
	v_max_f32_e32 v85, v85, v88
	ds_bpermute_b32 v88, v234, v85
	s_waitcnt lgkmcnt(0)
	v_max3_f32 v88, v188, v85, v88
	v_sub_f32_e32 v85, v188, v88
	v_exp_f32_e32 v96, v85
	v_mov_b64_e32 v[188:189], v[88:89]
	v_mul_f32_e32 v190, v190, v96
	v_pk_mul_f32 v[18:19], v[18:19], v[96:97] op_sel_hi:[1,0]
	v_pk_mul_f32 v[16:17], v[16:17], v[96:97] op_sel_hi:[1,0]
	v_pk_mul_f32 v[26:27], v[26:27], v[96:97] op_sel_hi:[1,0]
	v_pk_mul_f32 v[24:25], v[24:25], v[96:97] op_sel_hi:[1,0]
	v_pk_mul_f32 v[34:35], v[34:35], v[96:97] op_sel_hi:[1,0]
	v_pk_mul_f32 v[32:33], v[32:33], v[96:97] op_sel_hi:[1,0]
	v_pk_mul_f32 v[42:43], v[42:43], v[96:97] op_sel_hi:[1,0]
	v_pk_mul_f32 v[40:41], v[40:41], v[96:97] op_sel_hi:[1,0]
	v_cmp_lt_f32_e32 vcc, 0xefa18f08, v88
	s_nop 1
	v_cndmask_b32_e32 v232, 0, v88, vcc
	v_sub_f32_e32 v230, v232, v230
	v_sub_f32_e32 v87, v87, v230
	v_sub_f32_e32 v86, v86, v230
	v_sub_f32_e32 v83, v83, v230
	v_sub_f32_e32 v82, v82, v230
	v_sub_f32_e32 v81, v81, v230
	v_sub_f32_e32 v80, v80, v230
	v_sub_f32_e32 v97, v97, v230
	v_sub_f32_e32 v84, v84, v230
	v_mov_b32_e32 v230, v232
	s_branch .LBB0_439
; template <int MODE>
; __device__ __forceinline__ void nsa_compute(int cur, int buf, int t, int hl, u64 mymask, const bf16x8 (&Qf)[2][2], f32x4 (&O)[4][2], float (&m)[2], float (&l)[2],
;                                             const float (&inv)[2], float* impw, char* lds) {
;     ...
; #pragma unroll
;     for (int ks = 0; ks < 2; ++ks)
; #pragma unroll
;       for (int kk = 0; kk < 2; ++kk) kfr[ks][kk] = *(const bf16x8*)(kt + (32 * s2 + 16 * kk + fr) * 128 + (((ks * 4 + fq) ^ (fr & 7)) << 4));
;     __builtin_amdgcn_s_setprio(1);
; #pragma unroll
;     for (int ks = 0; ks < 2; ++ks)
; #pragma unroll
;       for (int kk = 0; kk < 2; ++kk)
; #pragma unroll
;         for (int r = 0; r < 2; ++r) S[kk][r] = mfma16(kfr[ks][kk], Qf[r][ks], S[kk][r]);
;     __builtin_amdgcn_s_setprio(0);
;     bf16x8 Pf[2];
;     float g1s[2] = {0.f, 0.f}, p3s[2] = {0.f, 0.f};
; #pragma unroll
;     for (int r = 0; r < 2; ++r) {
;       float sv[2][4];
; #pragma unroll
;       for (int kk = 0; kk < 2; ++kk)
; #pragma unroll
;         for (int e = 0; e < 4; ++e) {
;     ...
;         const float me = (MODE == 2) ? (selok ? m[r] : __builtin_inff()) : m[r];
;         float ps = 0.f;
; #pragma unroll
;         for (int kk = 0; kk < 2; ++kk)
; #pragma unroll
;           for (int e = 0; e < 4; ++e) { pv[kk][e] = __builtin_amdgcn_exp2f(sv[kk][e] - me); ps += pv[kk][e]; }
;         l[r] += ps;
;       }
;       if (MODE != 0) {
;         const unsigned w0 = pk2(pv[0][0], pv[0][1]), w1 = pk2(pv[0][2], pv[0][3]), w2 = pk2(pv[1][0], pv[1][1]), w3 = pk2(pv[1][2], pv[1][3]);
;         u32x4 pw; pw.x = w0; pw.y = w1; pw.z = w2; pw.w = w3;
;         Pf[r] = __builtin_bit_cast(bf16x8, pw);
;       }
;     }
;     if (MODE != 0) {
;       bf16x8 vfr[4];
; #pragma unroll
;       for (int df = 0; df < 4; ++df) {
;         const bf16x4 va = *(const bf16x4*)(vt + (df * 16 + fr) * 68 + 32 * s2 + 4 * fq);
;         const bf16x4 vb = *(const bf16x4*)(vt + (df * 16 + fr) * 68 + 32 * s2 + 16 + 4 * fq);
;         bf16x8 vf; vf[0] = va[0]; vf[1] = va[1]; vf[2] = va[2]; vf[3] = va[3]; vf[4] = vb[0]; vf[5] = vb[1]; vf[6] = vb[2]; vf[7] = vb[3];
;         vfr[df] = vf;
;       }
;       __builtin_amdgcn_s_setprio(1);
; #pragma unroll
;       for (int df = 0; df < 4; ++df)
; #pragma unroll
;         for (int r = 0; r < 2; ++r) O[df][r] = mfma16(vfr[df], Pf[r], O[df][r]);
;       __builtin_amdgcn_s_setprio(0);
.LBB0_438:
.LBB0_439:
	v_exp_f32_e32 v85, v87
	v_exp_f32_e32 v86, v86
	v_add_f32_e32 v87, 0, v85
	v_add_f32_e32 v88, v86, v87
	v_exp_f32_e32 v87, v83
	v_exp_f32_e32 v89, v81
	v_add_f32_e32 v83, v87, v88
	v_exp_f32_e32 v88, v82
	v_exp_f32_e32 v96, v80
	v_add_f32_e32 v82, v88, v83
	v_add_f32_e32 v81, v89, v82
	v_add_f32_e32 v80, v96, v81
	v_exp_f32_e32 v97, v97
	v_exp_f32_e32 v84, v84
	v_add_f32_e32 v80, v97, v80
	v_add_f32_e32 v80, v84, v80
	v_add_f32_e32 v190, v190, v80
	s_waitcnt lgkmcnt(3)
	v_fmamk_f32 v81, v76, 0x3e38aa3b, v141
	v_fmamk_f32 v80, v77, 0x3e38aa3b, v140
	s_waitcnt lgkmcnt(2)
	v_fmamk_f32 v78, v78, 0x3e38aa3b, v143
	v_fmamk_f32 v82, v79, 0x3e38aa3b, v142
	s_waitcnt lgkmcnt(1)
	v_fmamk_f32 v77, v72, 0x3e38aa3b, v145
	v_fmamk_f32 v76, v73, 0x3e38aa3b, v144
	s_waitcnt lgkmcnt(0)
	v_fmamk_f32 v73, v74, 0x3e38aa3b, v149
	v_fmamk_f32 v72, v75, 0x3e38aa3b, v148
	v_max3_f32 v74, v81, v80, v78
	v_max3_f32 v75, v82, v77, v76
	v_max_f32_e32 v79, v73, v72
	v_max3_f32 v74, v79, v74, v75
	v_cndmask_b32_e64 v74, v74, v225, s[36:37]
	v_sub_f32_e32 v75, v189, v231
	v_add_f32_e32 v75, 0x41000000, v75
	v_cmp_gt_f32_e32 vcc, v74, v75
	s_cbranch_vccz .LBB0_441
	v_add_f32_e32 v74, v74, v231
	ds_bpermute_b32 v75, v233, v74
	v_max_f32_e32 v74, v74, v74
	s_waitcnt lgkmcnt(0)
	v_max_f32_e32 v75, v75, v75
	v_max_f32_e32 v74, v74, v75
	ds_bpermute_b32 v75, v234, v74
	s_waitcnt lgkmcnt(0)
	v_max3_f32 v74, v189, v74, v75
	v_sub_f32_e32 v75, v189, v74
	v_exp_f32_e32 v98, v75
	v_mov_b32_e32 v189, v74
	v_mul_f32_e32 v191, v191, v98
	v_pk_mul_f32 v[22:23], v[22:23], v[98:99] op_sel_hi:[1,0]
	v_pk_mul_f32 v[20:21], v[20:21], v[98:99] op_sel_hi:[1,0]
	v_pk_mul_f32 v[30:31], v[30:31], v[98:99] op_sel_hi:[1,0]
	v_pk_mul_f32 v[28:29], v[28:29], v[98:99] op_sel_hi:[1,0]
	v_pk_mul_f32 v[38:39], v[38:39], v[98:99] op_sel_hi:[1,0]
	v_pk_mul_f32 v[36:37], v[36:37], v[98:99] op_sel_hi:[1,0]
	v_pk_mul_f32 v[46:47], v[46:47], v[98:99] op_sel_hi:[1,0]
	v_pk_mul_f32 v[44:45], v[44:45], v[98:99] op_sel_hi:[1,0]
	v_cmp_lt_f32_e32 vcc, 0xefa18f08, v74
	s_nop 1
	v_cndmask_b32_e32 v232, 0, v74, vcc
	v_sub_f32_e32 v231, v232, v231
	v_sub_f32_e32 v81, v81, v231
	v_sub_f32_e32 v80, v80, v231
	v_sub_f32_e32 v78, v78, v231
	v_sub_f32_e32 v82, v82, v231
	v_sub_f32_e32 v77, v77, v231
	v_sub_f32_e32 v76, v76, v231
	v_sub_f32_e32 v73, v73, v231
	v_sub_f32_e32 v72, v72, v231
	v_mov_b32_e32 v231, v232
	s_branch .LBB0_442
.LBB0_441:
.LBB0_442:
	v_exp_f32_e32 v75, v81
	v_exp_f32_e32 v80, v80
	v_exp_f32_e32 v78, v78
	v_exp_f32_e32 v81, v82
	v_add_f32_e32 v79, 0, v75
	v_exp_f32_e32 v77, v77
	v_add_f32_e32 v79, v80, v79
	v_exp_f32_e32 v76, v76
	v_add_f32_e32 v79, v78, v79
	v_exp_f32_e32 v73, v73
	v_add_f32_e32 v79, v81, v79
	v_exp_f32_e32 v72, v72
	v_add_f32_e32 v79, v77, v79
	v_add_f32_e32 v79, v76, v79
	v_add_f32_e32 v79, v73, v79
	s_lshl_b32 s17, s74, 9
	v_add_f32_e32 v74, v72, v79
	v_cvt_pk_bf16_f32 v101, v73, v72
	v_mul_u32_u24_e32 v72, 0x44, v94
	s_add_i32 s71, s63, s17
	v_lshlrev_b32_e32 v72, 1, v72
	v_lshlrev_b32_e32 v73, 1, v95
	v_add3_u32 v72, s71, v72, v73
	v_add_u32_e32 v94, 0x4000, v72
	v_cvt_pk_bf16_f32 v87, v87, v88
	v_cvt_pk_bf16_f32 v88, v89, v96
	v_cvt_pk_bf16_f32 v89, v97, v84
	v_cvt_pk_bf16_f32 v99, v78, v81
	v_cvt_pk_bf16_f32 v100, v77, v76
	ds_read2_b64 v[76:79], v94 offset1:4
	v_add_u32_e32 v95, 0x4800, v72
	v_add_u32_e32 v96, 0x5000, v72
	v_add_u32_e32 v97, 0x5800, v72
	ds_read2_b64 v[102:105], v95 offset0:16 offset1:20
	ds_read2_b64 v[106:109], v96 offset0:32 offset1:36
	ds_read2_b64 v[110:113], v97 offset0:48 offset1:52
	v_cvt_pk_bf16_f32 v86, v85, v86
	v_add_f32_e32 v191, v191, v74
	v_cvt_pk_bf16_f32 v98, v75, v80
	s_setprio 1
	s_waitcnt lgkmcnt(3)
	v_mfma_f32_16x16x32_bf16 v[72:75], v[76:79], v[86:89], v[16:19]
	v_mfma_f32_16x16x32_bf16 v[80:83], v[76:79], v[98:101], v[20:23]
	s_waitcnt lgkmcnt(2)
	v_mfma_f32_16x16x32_bf16 v[24:27], v[102:105], v[86:89], v[24:27]
	v_mfma_f32_16x16x32_bf16 v[76:79], v[102:105], v[98:101], v[28:31]
	s_waitcnt lgkmcnt(1)
	v_mfma_f32_16x16x32_bf16 v[20:23], v[106:109], v[86:89], v[32:35]
	v_mfma_f32_16x16x32_bf16 v[32:35], v[106:109], v[98:101], v[36:39]
	s_waitcnt lgkmcnt(0)
	v_mfma_f32_16x16x32_bf16 v[16:19], v[110:113], v[86:89], v[40:43]
	v_mfma_f32_16x16x32_bf16 v[28:31], v[110:113], v[98:101], v[44:47]
	s_setprio 0
	s_nop 0
	v_add_u32_e32 v40, v92, v91
	v_add_u32_e32 v84, v93, v91
	ds_read_b128 v[36:39], v40 offset:4096
	ds_read_b128 v[40:43], v40 offset:6144
	ds_read_b128 v[44:47], v84 offset:4096
	ds_read_b128 v[84:87], v84 offset:6144
	v_add_u32_e32 v251, 0x8400, v90
	v_add_u32_e32 v250, 0xc500, v90
	ds_read2_b32 v[138:139], v251 offset0:31 offset1:32
	ds_read2_b32 v[140:141], v251 offset0:29 offset1:30
	ds_read2_b32 v[142:143], v251 offset0:15 offset1:16
	ds_read2_b32 v[148:149], v251 offset0:13 offset1:14
	ds_read2_b32 v[150:151], v250 offset0:31 offset1:32
	ds_read2_b32 v[152:153], v250 offset0:29 offset1:30
	ds_read2_b32 v[154:155], v250 offset0:15 offset1:16
	ds_read2_b32 v[156:157], v250 offset0:13 offset1:14
	s_setprio 1
	s_waitcnt lgkmcnt(11)
	v_mfma_f32_16x16x32_bf16 v[98:101], v[36:39], v[0:3], 0
	v_mfma_f32_16x16x32_bf16 v[36:39], v[36:39], v[8:11], 0
	s_waitcnt lgkmcnt(10)
	v_mfma_f32_16x16x32_bf16 v[106:109], v[40:43], v[8:11], 0
	v_mfma_f32_16x16x32_bf16 v[102:105], v[40:43], v[0:3], 0
	s_waitcnt lgkmcnt(9)
	v_mfma_f32_16x16x32_bf16 v[40:43], v[44:47], v[12:15], v[36:39]
	s_waitcnt lgkmcnt(8)
	v_mfma_f32_16x16x32_bf16 v[36:39], v[84:87], v[12:15], v[106:109]
	v_mfma_f32_16x16x32_bf16 v[98:101], v[44:47], v[4:7], v[98:101]
	v_mfma_f32_16x16x32_bf16 v[102:105], v[84:87], v[4:7], v[102:105]
	s_setprio 0
	v_cndmask_b32_e64 v232, v230, v228, s[36:37]
	s_waitcnt lgkmcnt(4)
	v_sub_f32_e32 v139, v139, v232
	v_sub_f32_e32 v138, v138, v232
	v_sub_f32_e32 v141, v141, v232
	v_sub_f32_e32 v140, v140, v232
	v_sub_f32_e32 v143, v143, v232
	v_sub_f32_e32 v142, v142, v232
	v_sub_f32_e32 v149, v149, v232
	v_sub_f32_e32 v148, v148, v232
	v_cndmask_b32_e64 v232, v231, v228, s[36:37]
	s_waitcnt lgkmcnt(0)
	v_sub_f32_e32 v151, v151, v232
	v_sub_f32_e32 v150, v150, v232
	v_sub_f32_e32 v153, v153, v232
	v_sub_f32_e32 v152, v152, v232
	v_sub_f32_e32 v155, v155, v232
	v_sub_f32_e32 v154, v154, v232
	v_sub_f32_e32 v157, v157, v232
	v_sub_f32_e32 v156, v156, v232
	s_waitcnt lgkmcnt(7)
	s_nop 4
	v_fmamk_f32 v91, v98, 0x3e38aa3b, v139
	v_fmamk_f32 v84, v99, 0x3e38aa3b, v138
	s_waitcnt lgkmcnt(6)
	v_fmamk_f32 v85, v100, 0x3e38aa3b, v141
	v_fmamk_f32 v46, v101, 0x3e38aa3b, v140
	s_waitcnt lgkmcnt(5)
	v_fmamk_f32 v45, v102, 0x3e38aa3b, v143
	v_fmamk_f32 v44, v103, 0x3e38aa3b, v142
	v_max3_f32 v47, v91, v84, v85
	s_waitcnt lgkmcnt(4)
	v_fmamk_f32 v92, v104, 0x3e38aa3b, v149
	v_fmamk_f32 v86, v105, 0x3e38aa3b, v148
	v_max3_f32 v87, v46, v45, v44
	v_max_f32_e32 v88, v92, v86
	v_max3_f32 v47, v88, v47, v87
	v_cndmask_b32_e64 v47, v47, v225, s[36:37]
	v_sub_f32_e32 v87, v188, v230
	v_add_f32_e32 v87, 0x41000000, v87
	v_cmp_gt_f32_e32 vcc, v47, v87
	s_cbranch_vccz .LBB0_444
; template <int MODE>
; __device__ __forceinline__ void nsa_compute(int cur, int buf, int t, int hl, u64 mymask, const bf16x8 (&Qf)[2][2], f32x4 (&O)[4][2], float (&m)[2], float (&l)[2],
;                                             const float (&inv)[2], float* impw, char* lds) {
;     ...
;         if (__any(mx > m[r] + 8.0f)) {
;           mx = fmaxf(mx, __shfl_xor(mx, 16)); mx = fmaxf(mx, __shfl_xor(mx, 32));
;           const float mn = fmaxf(m[r], mx), al = __builtin_amdgcn_exp2f(m[r] - mn);
;           m[r] = mn; l[r] *= al;
;           if (MODE != 0) {
; #pragma unroll
;             for (int df = 0; df < 4; ++df) O[df][r] *= al;
;           }
;         }
;         const float me = (MODE == 2) ? (selok ? m[r] : __builtin_inff()) : m[r];
;         float ps = 0.f;
; #pragma unroll
;         for (int kk = 0; kk < 2; ++kk)
; #pragma unroll
;           for (int e = 0; e < 4; ++e) { pv[kk][e] = __builtin_amdgcn_exp2f(sv[kk][e] - me); ps += pv[kk][e]; }
;         l[r] += ps;
	v_add_f32_e32 v47, v47, v230
	ds_bpermute_b32 v87, v233, v47
	v_max_f32_e32 v47, v47, v47
	v_mov_b32_e32 v89, v189
	s_waitcnt lgkmcnt(0)
	v_max_f32_e32 v87, v87, v87
	v_max_f32_e32 v47, v47, v87
	ds_bpermute_b32 v87, v234, v47
	s_waitcnt lgkmcnt(0)
	v_max3_f32 v88, v188, v47, v87
	v_sub_f32_e32 v47, v188, v88
	v_exp_f32_e32 v98, v47
	v_mov_b64_e32 v[188:189], v[88:89]
	v_mul_f32_e32 v190, v190, v98
	v_pk_mul_f32 v[74:75], v[74:75], v[98:99] op_sel_hi:[1,0]
	v_pk_mul_f32 v[72:73], v[72:73], v[98:99] op_sel_hi:[1,0]
	v_pk_mul_f32 v[26:27], v[26:27], v[98:99] op_sel_hi:[1,0]
	v_pk_mul_f32 v[24:25], v[24:25], v[98:99] op_sel_hi:[1,0]
	v_pk_mul_f32 v[22:23], v[22:23], v[98:99] op_sel_hi:[1,0]
	v_pk_mul_f32 v[20:21], v[20:21], v[98:99] op_sel_hi:[1,0]
	v_pk_mul_f32 v[18:19], v[18:19], v[98:99] op_sel_hi:[1,0]
	v_pk_mul_f32 v[16:17], v[16:17], v[98:99] op_sel_hi:[1,0]
	v_cmp_lt_f32_e32 vcc, 0xefa18f08, v88
	s_nop 1
	v_cndmask_b32_e32 v232, 0, v88, vcc
	v_sub_f32_e32 v230, v232, v230
	v_sub_f32_e32 v91, v91, v230
	v_sub_f32_e32 v84, v84, v230
	v_sub_f32_e32 v85, v85, v230
	v_sub_f32_e32 v46, v46, v230
	v_sub_f32_e32 v45, v45, v230
	v_sub_f32_e32 v44, v44, v230
	v_sub_f32_e32 v92, v92, v230
	v_sub_f32_e32 v86, v86, v230
	v_mov_b32_e32 v230, v232
	s_branch .LBB0_445
.LBB0_444:
.LBB0_445:
	v_exp_f32_e32 v47, v91
	v_exp_f32_e32 v84, v84
	v_exp_f32_e32 v85, v85
	v_exp_f32_e32 v46, v46
	v_add_f32_e32 v87, 0, v47
	v_add_f32_e32 v87, v84, v87
	v_add_f32_e32 v87, v85, v87
	v_add_f32_e32 v88, v46, v87
	v_exp_f32_e32 v87, v45
	s_nop 0
	v_add_f32_e32 v45, v87, v88
	v_exp_f32_e32 v88, v44
	s_nop 0
	v_add_f32_e32 v44, v88, v45
	v_exp_f32_e32 v89, v92
	v_exp_f32_e32 v86, v86
	v_add_f32_e32 v44, v89, v44
	v_add_f32_e32 v44, v86, v44
	v_add_f32_e32 v190, v190, v44
	s_waitcnt lgkmcnt(3)
	v_fmamk_f32 v45, v40, 0x3e38aa3b, v151
	v_fmamk_f32 v44, v41, 0x3e38aa3b, v150
	s_waitcnt lgkmcnt(2)
	v_fmamk_f32 v41, v42, 0x3e38aa3b, v153
	v_fmamk_f32 v40, v43, 0x3e38aa3b, v152
	s_waitcnt lgkmcnt(1)
	v_fmamk_f32 v43, v36, 0x3e38aa3b, v155
	v_fmamk_f32 v42, v37, 0x3e38aa3b, v154
	s_waitcnt lgkmcnt(0)
	v_fmamk_f32 v90, v38, 0x3e38aa3b, v157
	v_fmamk_f32 v36, v39, 0x3e38aa3b, v156
	v_max3_f32 v37, v45, v44, v41
	v_max3_f32 v38, v40, v43, v42
	v_max_f32_e32 v39, v90, v36
	v_max3_f32 v37, v39, v37, v38
	v_cndmask_b32_e64 v37, v37, v225, s[36:37]
	v_sub_f32_e32 v38, v189, v231
	v_add_f32_e32 v38, 0x41000000, v38
	v_cmp_gt_f32_e32 vcc, v37, v38
	s_cbranch_vccz .LBB0_447
	v_add_f32_e32 v37, v37, v231
	ds_bpermute_b32 v38, v233, v37
	v_max_f32_e32 v37, v37, v37
	s_waitcnt lgkmcnt(0)
	v_max_f32_e32 v38, v38, v38
	v_max_f32_e32 v37, v37, v38
	ds_bpermute_b32 v38, v234, v37
	s_waitcnt lgkmcnt(0)
	v_max3_f32 v37, v189, v37, v38
	v_sub_f32_e32 v38, v189, v37
	v_exp_f32_e32 v38, v38
	v_mov_b32_e32 v189, v37
	v_mul_f32_e32 v191, v191, v38
	v_pk_mul_f32 v[82:83], v[82:83], v[38:39] op_sel_hi:[1,0]
	v_pk_mul_f32 v[80:81], v[80:81], v[38:39] op_sel_hi:[1,0]
	v_pk_mul_f32 v[78:79], v[78:79], v[38:39] op_sel_hi:[1,0]
	v_pk_mul_f32 v[76:77], v[76:77], v[38:39] op_sel_hi:[1,0]
	v_pk_mul_f32 v[34:35], v[34:35], v[38:39] op_sel_hi:[1,0]
	v_pk_mul_f32 v[32:33], v[32:33], v[38:39] op_sel_hi:[1,0]
	v_pk_mul_f32 v[30:31], v[30:31], v[38:39] op_sel_hi:[1,0]
	v_pk_mul_f32 v[28:29], v[28:29], v[38:39] op_sel_hi:[1,0]
	v_mov_b64_e32 v[144:145], v[190:191]
	v_cmp_lt_f32_e32 vcc, 0xefa18f08, v37
	s_nop 1
	v_cndmask_b32_e32 v232, 0, v37, vcc
	v_sub_f32_e32 v231, v232, v231
	v_sub_f32_e32 v45, v45, v231
	v_sub_f32_e32 v44, v44, v231
	v_sub_f32_e32 v41, v41, v231
	v_sub_f32_e32 v40, v40, v231
	v_sub_f32_e32 v43, v43, v231
	v_sub_f32_e32 v42, v42, v231
	v_sub_f32_e32 v90, v90, v231
	v_sub_f32_e32 v36, v36, v231
	v_mov_b32_e32 v231, v232
	s_branch .LBB0_448

; #define TIDX opaque_tid()
; __device__ __forceinline__ unsigned pk2(float lo, float hi) { const f32x2v v = {lo, hi}; const bf16x2v r = __builtin_convertvector(v, bf16x2v); return __builtin_bit_cast(unsigned, r); }
; __device__ __forceinline__ void kv_lwrite(const KVRegs& r, char* lds, int buf) {
;   const int tid = TIDX, row = tid >> 3, cq = tid & 7;
;   char* kt = lds + NSA_KT + buf * 8192 + row * 128;
;   *(u32x4*)(kt + ((cq ^ (row & 7)) << 4)) = r.k0;
;   bf16_t* vt = (bf16_t*)(lds + NSA_VT + buf * 8704) + (cq * 8) * 68 + row;
; #pragma unroll
;   for (int i = 0; i < 4; ++i) { vt[(2 * i) * 68] = (bf16_t)(r.v0[i] & 0xffffu); vt[(2 * i + 1) * 68] = (bf16_t)(r.v0[i] >> 16); }
; }
; template <int MODE>
; __device__ __forceinline__ void nsa_compute(int cur, int buf, int t, int hl, u64 mymask, const bf16x8 (&Qf)[2][2], f32x4 (&O)[4][2], float (&m)[2], float (&l)[2],
;                                             const float (&inv)[2], float* impw, char* lds) {
;     ...
;         const float me = (MODE == 2) ? (selok ? m[r] : __builtin_inff()) : m[r];
;         float ps = 0.f;
; #pragma unroll
;         for (int kk = 0; kk < 2; ++kk)
; #pragma unroll
;           for (int e = 0; e < 4; ++e) { pv[kk][e] = __builtin_amdgcn_exp2f(sv[kk][e] - me); ps += pv[kk][e]; }
;         l[r] += ps;
;       }
;       if (MODE != 0) {
;         const unsigned w0 = pk2(pv[0][0], pv[0][1]), w1 = pk2(pv[0][2], pv[0][3]), w2 = pk2(pv[1][0], pv[1][1]), w3 = pk2(pv[1][2], pv[1][3]);
;         u32x4 pw; pw.x = w0; pw.y = w1; pw.z = w2; pw.w = w3;
;         Pf[r] = __builtin_bit_cast(bf16x8, pw);
;       }
;     }
;     if (MODE != 0) {
;       bf16x8 vfr[4];
; #pragma unroll
;       for (int df = 0; df < 4; ++df) {
;         const bf16x4 va = *(const bf16x4*)(vt + (df * 16 + fr) * 68 + 32 * s2 + 4 * fq);
;         const bf16x4 vb = *(const bf16x4*)(vt + (df * 16 + fr) * 68 + 32 * s2 + 16 + 4 * fq);
;         bf16x8 vf; vf[0] = va[0]; vf[1] = va[1]; vf[2] = va[2]; vf[3] = va[3]; vf[4] = vb[0]; vf[5] = vb[1]; vf[6] = vb[2]; vf[7] = vb[3];
;         vfr[df] = vf;
;       }
;       __builtin_amdgcn_s_setprio(1);
; #pragma unroll
;       for (int df = 0; df < 4; ++df)
; #pragma unroll
;         for (int r = 0; r < 2; ++r) O[df][r] = mfma16(vfr[df], Pf[r], O[df][r]);
;       __builtin_amdgcn_s_setprio(0);
.LBB0_448:
	v_cvt_pk_bf16_f32 v104, v47, v84
	v_cvt_pk_bf16_f32 v105, v85, v46
	v_cvt_pk_bf16_f32 v106, v87, v88
	v_cvt_pk_bf16_f32 v107, v89, v86
	v_mov_b32_e32 v37, v45
	v_mov_b32_e32 v38, v44
	ds_read2_b64 v[44:47], v94 offset0:8 offset1:12
	ds_read2_b64 v[84:87], v95 offset0:24 offset1:28
	ds_read2_b64 v[108:111], v96 offset0:40 offset1:44
	ds_read2_b64 v[112:115], v97 offset0:56 offset1:60
	v_exp_f32_e32 v37, v37
	v_exp_f32_e32 v38, v38
	v_exp_f32_e32 v39, v41
	v_exp_f32_e32 v40, v40
	v_exp_f32_e32 v41, v43
	v_exp_f32_e32 v42, v42
	v_exp_f32_e32 v43, v90
	v_exp_f32_e32 v36, v36
	v_cvt_pk_bf16_f32 v116, v37, v38
	v_cvt_pk_bf16_f32 v117, v39, v40
	v_cvt_pk_bf16_f32 v118, v41, v42
	v_cvt_pk_bf16_f32 v119, v43, v36
	s_setprio 1
	s_waitcnt lgkmcnt(3)
	v_mfma_f32_16x16x32_bf16 v[88:91], v[44:47], v[104:107], v[72:75]
	v_mfma_f32_16x16x32_bf16 v[96:99], v[44:47], v[116:119], v[80:83]
	s_waitcnt lgkmcnt(2)
	v_mfma_f32_16x16x32_bf16 v[100:103], v[84:87], v[104:107], v[24:27]
	v_mfma_f32_16x16x32_bf16 v[84:87], v[84:87], v[116:119], v[76:79]
	s_waitcnt lgkmcnt(1)
	v_mfma_f32_16x16x32_bf16 v[92:95], v[108:111], v[104:107], v[20:23]
	v_mfma_f32_16x16x32_bf16 v[76:79], v[108:111], v[116:119], v[32:35]
	s_waitcnt lgkmcnt(0)
	v_mfma_f32_16x16x32_bf16 v[80:83], v[112:115], v[104:107], v[16:19]
	v_mfma_f32_16x16x32_bf16 v[72:75], v[112:115], v[116:119], v[28:31]
	s_setprio 0
	s_xor_b32 s74, s74, 1
	s_cmp_lt_i32 s16, 0
	s_cbranch_scc1 .LBB0_450
	v_mov_b32 v16, v179
	s_lshl_b32 s17, s74, 13
	v_ashrrev_i32_e32 v17, 3, v16
	v_xor_b32_e32 v19, v17, v16
	v_lshl_add_u32 v18, v17, 7, s17
	v_lshlrev_b32_e32 v19, 4, v19
	s_movk_i32 s30, 0x70
	v_lshlrev_b32_e32 v16, 3, v16
	v_and_or_b32 v18, v19, s30, v18
	s_lshl_b32 s30, s74, 9
	v_and_b32_e32 v16, 56, v16
	s_add_i32 s17, s17, s30
	v_mul_u32_u24_e32 v16, 0x88, v16
	v_lshlrev_b32_e32 v17, 1, v17
	v_add3_u32 v16, s17, v16, v17
	s_waitcnt vmcnt(1)
	ds_write_b128 v18, v[56:59]
	s_waitcnt vmcnt(0)
	ds_write_b16 v16, v60 offset:16384
	ds_write_b16_d16_hi v16, v60 offset:16520
	ds_write_b16 v16, v61 offset:16656
	ds_write_b16_d16_hi v16, v61 offset:16792
	ds_write_b16 v16, v62 offset:16928
	ds_write_b16_d16_hi v16, v62 offset:17064
	ds_write_b16 v16, v63 offset:17200
	ds_write_b16_d16_hi v16, v63 offset:17336

; template <int MODE>
; __device__ __forceinline__ void nsa_compute(int cur, int buf, int t, int hl, u64 mymask, const bf16x8 (&Qf)[2][2], f32x4 (&O)[4][2], float (&m)[2], float (&l)[2],
;                                             const float (&inv)[2], float* impw, char* lds) {
;     ...
;   const bool selok = (MODE == 2) ? (((mymask >> cur) & 1ull) != 0ull) : true;
;   const float* tb = (MODE == 3) ? (const float*)(lds + NSA_TW) + hl * 640 : (const float*)(lds + NSA_T) + hl * 4160;
;   constexpr int TS = (MODE == 3) ? 640 : 4160;
;   const int base = (MODE <= 1) ? (t - 31 - 16 * (cur * 64 + 4 * fq) + 64) : (t - cur * 64 - 4 * fq + 64);
; #pragma unroll
;   for (int s2 = 0; s2 < 2; ++s2) {
;     f32x4 S[2][2] = {};
;     bf16x8 kfr[2][2];
; #pragma unroll
;     for (int ks = 0; ks < 2; ++ks)
; #pragma unroll
;       for (int kk = 0; kk < 2; ++kk) kfr[ks][kk] = *(const bf16x8*)(kt + (32 * s2 + 16 * kk + fr) * 128 + (((ks * 4 + fq) ^ (fr & 7)) << 4));
;     __builtin_amdgcn_s_setprio(1);
; #pragma unroll
;     for (int ks = 0; ks < 2; ++ks)
; #pragma unroll
;       for (int kk = 0; kk < 2; ++kk)
; #pragma unroll
;         for (int r = 0; r < 2; ++r) S[kk][r] = mfma16(kfr[ks][kk], Qf[r][ks], S[kk][r]);
;     __builtin_amdgcn_s_setprio(0);
;     bf16x8 Pf[2];
;     float g1s[2] = {0.f, 0.f}, p3s[2] = {0.f, 0.f};
; #pragma unroll
;     for (int r = 0; r < 2; ++r) {
;       float sv[2][4];
; #pragma unroll
;       for (int kk = 0; kk < 2; ++kk)
; #pragma unroll
;         for (int e = 0; e < 4; ++e) {
;           const int off = 32 * s2 + 16 * kk + e;
;           int idx;
;           if (MODE <= 1) { idx = base - 16 * off; idx = idx > 0 ? idx : 0; } else idx = base - off;
;           sv[kk][e] = S[kk][r][e] * (0.125f * LOG2E) + tb[r * TS + idx];
;         }
;       float pv[2][4];
;       if (MODE == 1) {
; #pragma unroll
;         for (int kk = 0; kk < 2; ++kk)
; #pragma unroll
;           for (int e = 0; e < 4; ++e) pv[kk][e] = __builtin_amdgcn_exp2f(sv[kk][e] - m[r]) * inv[r];
; #pragma unroll
;         for (int kk = 0; kk < 2; ++kk) { g1s[kk] += pv[kk][0] + pv[kk][1] + pv[kk][2] + 0.5f * pv[kk][3]; p3s[kk] += 0.5f * pv[kk][3]; }
;       } else {
;         const float mxa = fmaxf(fmaxf(sv[0][0], sv[0][1]), sv[0][2]), mxb = fmaxf(fmaxf(sv[0][3], sv[1][0]), sv[1][1]);
;         float mx = fmaxf(fmaxf(fmaxf(sv[1][2], sv[1][3]), mxa), mxb);
.LBB0_452:
	v_add_f32_e32 v16, 0, v37
	v_add_f32_e32 v16, v38, v16
	v_add_f32_e32 v16, v39, v16
	v_add_f32_e32 v16, v40, v16
	v_add_f32_e32 v16, v41, v16
	v_add_f32_e32 v16, v42, v16
	v_add_f32_e32 v16, v43, v16
	v_add_f32_e32 v16, v36, v16
	s_cmp_lt_i32 s16, 0
	v_add_f32_e32 v145, v145, v16
	s_cbranch_scc1 .LBB0_435
	s_lshl_b64 s[30:31], 1, s16
	v_mov_b32 v18, v179
	v_and_b32_e32 v17, s31, v187
	v_lshrrev_b32_e32 v19, 4, v18
	v_bfe_u32 v24, v18, 4, 2
	v_and_b32_e32 v16, s30, v186
	v_and_b32_e32 v25, 7, v18
	v_and_b32_e32 v117, 15, v18
	s_lshl_b32 s72, s74, 13
	v_cmp_eq_u64_e64 s[36:37], 0, v[16:17]
	v_lshlrev_b32_e32 v118, 2, v24
	v_bitop3_b32 v16, v19, v25, 3 bitop3:0x6c
	v_bitop3_b32 v24, v24, v25, 4 bitop3:0x36
	v_lshlrev_b32_e32 v114, 7, v117
	v_lshl_or_b32 v115, v16, 4, s72
	v_lshl_or_b32 v116, v24, 4, s72
	v_or_b32_e32 v20, v115, v114
	v_or_b32_e32 v28, v116, v114
	ds_read_b128 v[16:19], v20
	ds_read_b128 v[20:23], v20 offset:2048
	ds_read_b128 v[24:27], v28
	ds_read_b128 v[28:31], v28 offset:2048
	v_sub_u32_e32 v251, v180, v118
	v_lshl_add_u32 v251, v251, 2, v181
	s_lshl_b32 s16, s16, 8
	v_subrev_u32_e32 v250, s16, v251
	v_add_u32_e32 v249, 0x8400, v250
	v_add_u32_e32 v248, 0xc500, v250
	ds_read2_b32 v[148:149], v249 offset0:63 offset1:64
	ds_read2_b32 v[150:151], v249 offset0:61 offset1:62
	ds_read2_b32 v[152:153], v249 offset0:47 offset1:48
	ds_read2_b32 v[154:155], v249 offset0:45 offset1:46
	ds_read2_b32 v[156:157], v248 offset0:63 offset1:64
	ds_read2_b32 v[168:169], v248 offset0:61 offset1:62
	ds_read2_b32 v[170:171], v248 offset0:47 offset1:48
	ds_read2_b32 v[172:173], v248 offset0:45 offset1:46
	s_setprio 1
	s_waitcnt lgkmcnt(11)
	v_mfma_f32_16x16x32_bf16 v[32:35], v[16:19], v[0:3], 0
	v_mfma_f32_16x16x32_bf16 v[16:19], v[16:19], v[8:11], 0
	s_waitcnt lgkmcnt(10)
	v_mfma_f32_16x16x32_bf16 v[40:43], v[20:23], v[0:3], 0
	v_mfma_f32_16x16x32_bf16 v[20:23], v[20:23], v[8:11], 0
	s_waitcnt lgkmcnt(9)
	v_mfma_f32_16x16x32_bf16 v[36:39], v[24:27], v[12:15], v[16:19]
	s_waitcnt lgkmcnt(8)
	v_mfma_f32_16x16x32_bf16 v[16:19], v[28:31], v[4:7], v[40:43]
	v_mfma_f32_16x16x32_bf16 v[28:31], v[28:31], v[12:15], v[20:23]
	v_mfma_f32_16x16x32_bf16 v[32:35], v[24:27], v[4:7], v[32:35]
	s_setprio 0
	v_cndmask_b32_e64 v232, v230, v228, s[36:37]
	s_waitcnt lgkmcnt(4)
	v_sub_f32_e32 v149, v149, v232
	v_sub_f32_e32 v148, v148, v232
	v_sub_f32_e32 v151, v151, v232
	v_sub_f32_e32 v150, v150, v232
	v_sub_f32_e32 v153, v153, v232
	v_sub_f32_e32 v152, v152, v232
	v_sub_f32_e32 v155, v155, v232
	v_sub_f32_e32 v154, v154, v232
	v_cndmask_b32_e64 v232, v231, v228, s[36:37]
	s_waitcnt lgkmcnt(0)
	v_sub_f32_e32 v157, v157, v232
	v_sub_f32_e32 v156, v156, v232
	v_sub_f32_e32 v169, v169, v232
	v_sub_f32_e32 v168, v168, v232
	v_sub_f32_e32 v171, v171, v232
	v_sub_f32_e32 v170, v170, v232
	v_sub_f32_e32 v173, v173, v232
	v_sub_f32_e32 v172, v172, v232
	s_nop 0
	v_sub_u32_e32 v20, v180, v118
	v_lshl_add_u32 v20, v20, 2, v181
	v_subrev_u32_e32 v122, s16, v20
	s_waitcnt lgkmcnt(7)
	s_nop 1
	v_fmamk_f32 v47, v32, 0x3e38aa3b, v149
	v_fmamk_f32 v46, v33, 0x3e38aa3b, v148
	s_waitcnt lgkmcnt(6)
	v_fmamk_f32 v43, v34, 0x3e38aa3b, v151
	v_fmamk_f32 v42, v35, 0x3e38aa3b, v150
	s_waitcnt lgkmcnt(5)
	v_fmamk_f32 v41, v16, 0x3e38aa3b, v153
	v_fmamk_f32 v40, v17, 0x3e38aa3b, v152
	v_max3_f32 v16, v47, v46, v43
	v_max3_f32 v17, v42, v41, v40
	s_waitcnt lgkmcnt(4)
	v_fmamk_f32 v45, v18, 0x3e38aa3b, v155
	v_fmamk_f32 v44, v19, 0x3e38aa3b, v154
	v_max_f32_e32 v18, v45, v44
	v_max3_f32 v16, v18, v16, v17
	v_cndmask_b32_e64 v16, v16, v225, s[36:37]
	v_sub_f32_e32 v17, v188, v230
	v_add_f32_e32 v17, 0x41000000, v17
	v_cmp_gt_f32_e32 vcc, v16, v17
	s_cbranch_vccz .LBB0_455
	v_add_f32_e32 v16, v16, v230
	ds_bpermute_b32 v17, v233, v16
	v_max_f32_e32 v16, v16, v16
	v_mov_b32_e32 v105, v189
	v_mov_b32_e32 v147, v145
	s_waitcnt lgkmcnt(0)
	v_max_f32_e32 v17, v17, v17
	v_max_f32_e32 v16, v16, v17
	ds_bpermute_b32 v17, v234, v16
	s_waitcnt lgkmcnt(0)
	v_max3_f32 v104, v188, v16, v17
	v_sub_f32_e32 v16, v188, v104
	v_exp_f32_e32 v32, v16
	v_mov_b64_e32 v[188:189], v[104:105]
	v_mul_f32_e32 v146, v144, v32
	v_pk_mul_f32 v[26:27], v[90:91], v[32:33] op_sel_hi:[1,0]
	v_pk_mul_f32 v[24:25], v[88:89], v[32:33] op_sel_hi:[1,0]
	v_pk_mul_f32 v[18:19], v[102:103], v[32:33] op_sel_hi:[1,0]
	v_pk_mul_f32 v[16:17], v[100:101], v[32:33] op_sel_hi:[1,0]
	v_pk_mul_f32 v[22:23], v[94:95], v[32:33] op_sel_hi:[1,0]
	v_pk_mul_f32 v[20:21], v[92:93], v[32:33] op_sel_hi:[1,0]
	v_pk_mul_f32 v[34:35], v[82:83], v[32:33] op_sel_hi:[1,0]
	v_pk_mul_f32 v[32:33], v[80:81], v[32:33] op_sel_hi:[1,0]
	v_cmp_lt_f32_e32 vcc, 0xefa18f08, v104
	s_nop 1
	v_cndmask_b32_e32 v232, 0, v104, vcc
	v_sub_f32_e32 v230, v232, v230
	v_sub_f32_e32 v47, v47, v230
	v_sub_f32_e32 v46, v46, v230
	v_sub_f32_e32 v43, v43, v230
	v_sub_f32_e32 v42, v42, v230
	v_sub_f32_e32 v41, v41, v230
	v_sub_f32_e32 v40, v40, v230
	v_sub_f32_e32 v45, v45, v230
	v_sub_f32_e32 v44, v44, v230
	v_mov_b32_e32 v230, v232
	s_branch .LBB0_456

; template <int MODE>
; __device__ __forceinline__ void nsa_compute(int cur, int buf, int t, int hl, u64 mymask, const bf16x8 (&Qf)[2][2], f32x4 (&O)[4][2], float (&m)[2], float (&l)[2],
;                                             const float (&inv)[2], float* impw, char* lds) {
;     ...
;         const float mxa = fmaxf(fmaxf(sv[0][0], sv[0][1]), sv[0][2]), mxb = fmaxf(fmaxf(sv[0][3], sv[1][0]), sv[1][1]);
;         float mx = fmaxf(fmaxf(fmaxf(sv[1][2], sv[1][3]), mxa), mxb);
;         if (MODE == 2) mx = selok ? mx : -__builtin_inff();
;         if (__any(mx > m[r] + 8.0f)) {
;           mx = fmaxf(mx, __shfl_xor(mx, 16)); mx = fmaxf(mx, __shfl_xor(mx, 32));
;           const float mn = fmaxf(m[r], mx), al = __builtin_amdgcn_exp2f(m[r] - mn);
;           m[r] = mn; l[r] *= al;
;           if (MODE != 0) {
; #pragma unroll
;             for (int df = 0; df < 4; ++df) O[df][r] *= al;
;           }
;         }
;         const float me = (MODE == 2) ? (selok ? m[r] : __builtin_inff()) : m[r];
;         float ps = 0.f;
; #pragma unroll
;         for (int kk = 0; kk < 2; ++kk)
; #pragma unroll
;           for (int e = 0; e < 4; ++e) { pv[kk][e] = __builtin_amdgcn_exp2f(sv[kk][e] - me); ps += pv[kk][e]; }
;         l[r] += ps;
.LBB0_456:
	v_exp_f32_e32 v119, v47
	v_exp_f32_e32 v120, v46
	v_exp_f32_e32 v121, v43
	v_exp_f32_e32 v123, v42
	v_add_f32_e32 v47, 0, v119
	v_exp_f32_e32 v124, v41
	v_add_f32_e32 v46, v120, v47
	v_exp_f32_e32 v125, v40
	v_add_f32_e32 v43, v121, v46
	v_add_f32_e32 v42, v123, v43
	v_add_f32_e32 v41, v124, v42
	v_add_f32_e32 v40, v125, v41
	v_exp_f32_e32 v126, v45
	v_exp_f32_e32 v127, v44
	v_add_f32_e32 v40, v126, v40
	v_add_f32_e32 v40, v127, v40
	v_add_f32_e32 v146, v146, v40
	s_waitcnt lgkmcnt(3)
	v_fmamk_f32 v47, v36, 0x3e38aa3b, v157
	v_fmamk_f32 v46, v37, 0x3e38aa3b, v156
	s_waitcnt lgkmcnt(2)
	v_fmamk_f32 v113, v38, 0x3e38aa3b, v169
	v_fmamk_f32 v112, v39, 0x3e38aa3b, v168
	s_waitcnt lgkmcnt(1)
	v_fmamk_f32 v45, v28, 0x3e38aa3b, v171
	v_fmamk_f32 v44, v29, 0x3e38aa3b, v170
	s_waitcnt lgkmcnt(0)
	v_fmamk_f32 v29, v30, 0x3e38aa3b, v173
	v_fmamk_f32 v28, v31, 0x3e38aa3b, v172
	v_max3_f32 v30, v47, v46, v113
	v_max3_f32 v31, v112, v45, v44
	v_max_f32_e32 v36, v29, v28
	v_max3_f32 v30, v36, v30, v31
	v_cndmask_b32_e64 v30, v30, v225, s[36:37]
	v_sub_f32_e32 v31, v189, v231
	v_add_f32_e32 v31, 0x41000000, v31
	v_cmp_gt_f32_e32 vcc, v30, v31
	s_cbranch_vccz .LBB0_458
	v_add_f32_e32 v30, v30, v231
	ds_bpermute_b32 v31, v233, v30
	v_max_f32_e32 v30, v30, v30
	s_waitcnt lgkmcnt(0)
	v_max_f32_e32 v31, v31, v31
	v_max_f32_e32 v30, v30, v31
	ds_bpermute_b32 v31, v234, v30
	s_waitcnt lgkmcnt(0)
	v_max3_f32 v30, v189, v30, v31
	v_sub_f32_e32 v31, v189, v30
	v_exp_f32_e32 v108, v31
	v_mov_b32_e32 v189, v30
	v_mul_f32_e32 v147, v147, v108
	v_pk_mul_f32 v[38:39], v[98:99], v[108:109] op_sel_hi:[1,0]
	v_pk_mul_f32 v[36:37], v[96:97], v[108:109] op_sel_hi:[1,0]
	v_pk_mul_f32 v[42:43], v[86:87], v[108:109] op_sel_hi:[1,0]
	v_pk_mul_f32 v[40:41], v[84:85], v[108:109] op_sel_hi:[1,0]
	v_pk_mul_f32 v[106:107], v[78:79], v[108:109] op_sel_hi:[1,0]
	v_pk_mul_f32 v[104:105], v[76:77], v[108:109] op_sel_hi:[1,0]
	v_pk_mul_f32 v[110:111], v[74:75], v[108:109] op_sel_hi:[1,0]
	v_pk_mul_f32 v[108:109], v[72:73], v[108:109] op_sel_hi:[1,0]
	v_cmp_lt_f32_e32 vcc, 0xefa18f08, v30
	s_nop 1
	v_cndmask_b32_e32 v232, 0, v30, vcc
	v_sub_f32_e32 v231, v232, v231
	v_sub_f32_e32 v47, v47, v231
	v_sub_f32_e32 v46, v46, v231
	v_sub_f32_e32 v113, v113, v231
	v_sub_f32_e32 v112, v112, v231
	v_sub_f32_e32 v45, v45, v231
	v_sub_f32_e32 v44, v44, v231
	v_sub_f32_e32 v29, v29, v231
	v_sub_f32_e32 v28, v28, v231
	v_mov_b32_e32 v231, v232
	s_branch .LBB0_459

; template <int MODE>
; __device__ __forceinline__ void nsa_compute(int cur, int buf, int t, int hl, u64 mymask, const bf16x8 (&Qf)[2][2], f32x4 (&O)[4][2], float (&m)[2], float (&l)[2],
;                                             const float (&inv)[2], float* impw, char* lds) {
;     ...
; #pragma unroll
;     for (int ks = 0; ks < 2; ++ks)
; #pragma unroll
;       for (int kk = 0; kk < 2; ++kk) kfr[ks][kk] = *(const bf16x8*)(kt + (32 * s2 + 16 * kk + fr) * 128 + (((ks * 4 + fq) ^ (fr & 7)) << 4));
;     __builtin_amdgcn_s_setprio(1);
; #pragma unroll
;     for (int ks = 0; ks < 2; ++ks)
; #pragma unroll
;       for (int kk = 0; kk < 2; ++kk)
; #pragma unroll
;         for (int r = 0; r < 2; ++r) S[kk][r] = mfma16(kfr[ks][kk], Qf[r][ks], S[kk][r]);
;     __builtin_amdgcn_s_setprio(0);
;     bf16x8 Pf[2];
;     float g1s[2] = {0.f, 0.f}, p3s[2] = {0.f, 0.f};
; #pragma unroll
;     for (int r = 0; r < 2; ++r) {
;       float sv[2][4];
; #pragma unroll
;       for (int kk = 0; kk < 2; ++kk)
; #pragma unroll
;         for (int e = 0; e < 4; ++e) {
;     ...
;         const float me = (MODE == 2) ? (selok ? m[r] : __builtin_inff()) : m[r];
;         float ps = 0.f;
; #pragma unroll
;         for (int kk = 0; kk < 2; ++kk)
; #pragma unroll
;           for (int e = 0; e < 4; ++e) { pv[kk][e] = __builtin_amdgcn_exp2f(sv[kk][e] - me); ps += pv[kk][e]; }
;         l[r] += ps;
;       }
;       if (MODE != 0) {
;         const unsigned w0 = pk2(pv[0][0], pv[0][1]), w1 = pk2(pv[0][2], pv[0][3]), w2 = pk2(pv[1][0], pv[1][1]), w3 = pk2(pv[1][2], pv[1][3]);
;         u32x4 pw; pw.x = w0; pw.y = w1; pw.z = w2; pw.w = w3;
;         Pf[r] = __builtin_bit_cast(bf16x8, pw);
;       }
;     }
;     if (MODE != 0) {
;       bf16x8 vfr[4];
; #pragma unroll
;       for (int df = 0; df < 4; ++df) {
;         const bf16x4 va = *(const bf16x4*)(vt + (df * 16 + fr) * 68 + 32 * s2 + 4 * fq);
;         const bf16x4 vb = *(const bf16x4*)(vt + (df * 16 + fr) * 68 + 32 * s2 + 16 + 4 * fq);
;         bf16x8 vf; vf[0] = va[0]; vf[1] = va[1]; vf[2] = va[2]; vf[3] = va[3]; vf[4] = vb[0]; vf[5] = vb[1]; vf[6] = vb[2]; vf[7] = vb[3];
;         vfr[df] = vf;
;       }
;       __builtin_amdgcn_s_setprio(1);
; #pragma unroll
;       for (int df = 0; df < 4; ++df)
; #pragma unroll
;         for (int r = 0; r < 2; ++r) O[df][r] = mfma16(vfr[df], Pf[r], O[df][r]);
;       __builtin_amdgcn_s_setprio(0);
.LBB0_459:
	v_exp_f32_e32 v31, v47
	v_exp_f32_e32 v46, v46
	v_exp_f32_e32 v113, v113
	v_exp_f32_e32 v112, v112
	v_add_f32_e32 v47, 0, v31
	v_exp_f32_e32 v45, v45
	v_add_f32_e32 v47, v46, v47
	v_exp_f32_e32 v44, v44
	v_add_f32_e32 v47, v113, v47
	v_exp_f32_e32 v29, v29
	v_add_f32_e32 v47, v112, v47
	v_exp_f32_e32 v28, v28
	v_add_f32_e32 v47, v45, v47
	v_add_f32_e32 v47, v44, v47
	v_add_f32_e32 v47, v29, v47
	s_lshl_b32 s16, s74, 9
	v_add_f32_e32 v30, v28, v47
	v_cvt_pk_bf16_f32 v135, v29, v28
	v_mul_u32_u24_e32 v28, 0x44, v117
	s_add_i32 s73, s72, s16
	v_lshlrev_b32_e32 v28, 1, v28
	v_lshlrev_b32_e32 v29, 1, v118
	v_add3_u32 v28, s73, v28, v29
	v_cvt_pk_bf16_f32 v129, v121, v123
	v_cvt_pk_bf16_f32 v130, v124, v125
	v_add_u32_e32 v123, 0x4000, v28
	v_add_u32_e32 v124, 0x4800, v28
	v_cvt_pk_bf16_f32 v128, v119, v120
	v_cvt_pk_bf16_f32 v131, v126, v127
	v_cvt_pk_bf16_f32 v132, v31, v46
	v_cvt_pk_bf16_f32 v134, v45, v44
	ds_read2_b64 v[44:47], v123 offset1:4
	ds_read2_b64 v[118:121], v124 offset0:16 offset1:20
	v_add_u32_e32 v125, 0x5000, v28
	v_add_u32_e32 v126, 0x5800, v28
	ds_read2_b64 v[136:139], v125 offset0:32 offset1:36
	ds_read2_b64 v[140:143], v126 offset0:48 offset1:52
	v_add_f32_e32 v147, v147, v30
	v_cvt_pk_bf16_f32 v133, v113, v112
	s_setprio 1
	s_waitcnt lgkmcnt(3)
	v_mfma_f32_16x16x32_bf16 v[28:31], v[44:47], v[128:131], v[24:27]
	v_mfma_f32_16x16x32_bf16 v[44:47], v[44:47], v[132:135], v[36:39]
	s_waitcnt lgkmcnt(2)
	v_mfma_f32_16x16x32_bf16 v[24:27], v[118:121], v[128:131], v[16:19]
	v_mfma_f32_16x16x32_bf16 v[40:43], v[118:121], v[132:135], v[40:43]
	s_waitcnt lgkmcnt(1)
	v_mfma_f32_16x16x32_bf16 v[20:23], v[136:139], v[128:131], v[20:23]
	v_mfma_f32_16x16x32_bf16 v[36:39], v[136:139], v[132:135], v[104:107]
	s_waitcnt lgkmcnt(0)
	v_mfma_f32_16x16x32_bf16 v[16:19], v[140:143], v[128:131], v[32:35]
	v_mfma_f32_16x16x32_bf16 v[32:35], v[140:143], v[132:135], v[108:111]
	s_setprio 0
	s_nop 1
	v_add_u32_e32 v108, v115, v114
	v_add_u32_e32 v116, v116, v114
	ds_read_b128 v[104:107], v108 offset:4096
	ds_read_b128 v[108:111], v108 offset:6144
	ds_read_b128 v[112:115], v116 offset:4096
	ds_read_b128 v[116:119], v116 offset:6144
	v_add_u32_e32 v251, 0x8400, v122
	v_add_u32_e32 v250, 0xc500, v122
	ds_read2_b32 v[152:153], v251 offset0:31 offset1:32
	ds_read2_b32 v[154:155], v251 offset0:29 offset1:30
	ds_read2_b32 v[156:157], v251 offset0:15 offset1:16
	ds_read2_b32 v[168:169], v251 offset0:13 offset1:14
	ds_read2_b32 v[170:171], v250 offset0:31 offset1:32
	ds_read2_b32 v[172:173], v250 offset0:29 offset1:30
	ds_read2_b32 v[174:175], v250 offset0:15 offset1:16
	ds_read2_b32 v[192:193], v250 offset0:13 offset1:14
	s_setprio 1
	s_waitcnt lgkmcnt(11)
	v_mfma_f32_16x16x32_bf16 v[128:131], v[104:107], v[0:3], 0
	v_mfma_f32_16x16x32_bf16 v[104:107], v[104:107], v[8:11], 0
	s_waitcnt lgkmcnt(10)
	v_mfma_f32_16x16x32_bf16 v[136:139], v[108:111], v[8:11], 0
	v_mfma_f32_16x16x32_bf16 v[132:135], v[108:111], v[0:3], 0
	s_waitcnt lgkmcnt(9)
	v_mfma_f32_16x16x32_bf16 v[128:131], v[112:115], v[4:7], v[128:131]
	v_mfma_f32_16x16x32_bf16 v[108:111], v[112:115], v[12:15], v[104:107]
	s_waitcnt lgkmcnt(8)
	v_mfma_f32_16x16x32_bf16 v[104:107], v[116:119], v[12:15], v[136:139]
	v_mfma_f32_16x16x32_bf16 v[132:135], v[116:119], v[4:7], v[132:135]
	s_setprio 0
	v_cndmask_b32_e64 v232, v230, v228, s[36:37]
	s_waitcnt lgkmcnt(4)
	v_sub_f32_e32 v153, v153, v232
	v_sub_f32_e32 v152, v152, v232
	v_sub_f32_e32 v155, v155, v232
	v_sub_f32_e32 v154, v154, v232
	v_sub_f32_e32 v157, v157, v232
	v_sub_f32_e32 v156, v156, v232
	v_sub_f32_e32 v169, v169, v232
	v_sub_f32_e32 v168, v168, v232
	v_cndmask_b32_e64 v232, v231, v228, s[36:37]
	s_waitcnt lgkmcnt(0)
	v_sub_f32_e32 v171, v171, v232
	v_sub_f32_e32 v170, v170, v232
	v_sub_f32_e32 v173, v173, v232
	v_sub_f32_e32 v172, v172, v232
	v_sub_f32_e32 v175, v175, v232
	v_sub_f32_e32 v174, v174, v232
	v_sub_f32_e32 v193, v193, v232
	v_sub_f32_e32 v192, v192, v232
	s_waitcnt lgkmcnt(7)
	s_nop 1
	v_fmamk_f32 v127, v128, 0x3e38aa3b, v153
	v_fmamk_f32 v116, v129, 0x3e38aa3b, v152
	s_waitcnt lgkmcnt(6)
	v_fmamk_f32 v117, v130, 0x3e38aa3b, v155
	v_fmamk_f32 v114, v131, 0x3e38aa3b, v154
	s_waitcnt lgkmcnt(5)
	v_fmamk_f32 v113, v132, 0x3e38aa3b, v157
	v_fmamk_f32 v112, v133, 0x3e38aa3b, v156
	v_max3_f32 v115, v127, v116, v117
	s_waitcnt lgkmcnt(4)
	v_fmamk_f32 v128, v134, 0x3e38aa3b, v169
	v_fmamk_f32 v118, v135, 0x3e38aa3b, v168
	v_max3_f32 v119, v114, v113, v112
	v_max_f32_e32 v120, v128, v118
	v_max3_f32 v115, v120, v115, v119
	v_cndmask_b32_e64 v115, v115, v225, s[36:37]
	v_sub_f32_e32 v119, v188, v230
	v_add_f32_e32 v119, 0x41000000, v119
	v_cmp_gt_f32_e32 vcc, v115, v119
	s_cbranch_vccz .LBB0_461
	v_add_f32_e32 v115, v115, v230
	ds_bpermute_b32 v119, v233, v115
	v_max_f32_e32 v115, v115, v115
	v_mov_b32_e32 v121, v189
	s_waitcnt lgkmcnt(0)
	v_max_f32_e32 v119, v119, v119
	v_max_f32_e32 v115, v115, v119
	ds_bpermute_b32 v119, v234, v115
	s_waitcnt lgkmcnt(0)
	v_max3_f32 v120, v188, v115, v119
	v_sub_f32_e32 v115, v188, v120
	v_exp_f32_e32 v130, v115
	v_mov_b64_e32 v[188:189], v[120:121]
	v_mul_f32_e32 v146, v146, v130
	v_pk_mul_f32 v[30:31], v[30:31], v[130:131] op_sel_hi:[1,0]
	v_pk_mul_f32 v[28:29], v[28:29], v[130:131] op_sel_hi:[1,0]
	v_pk_mul_f32 v[26:27], v[26:27], v[130:131] op_sel_hi:[1,0]
	v_pk_mul_f32 v[24:25], v[24:25], v[130:131] op_sel_hi:[1,0]
	v_pk_mul_f32 v[22:23], v[22:23], v[130:131] op_sel_hi:[1,0]
	v_pk_mul_f32 v[20:21], v[20:21], v[130:131] op_sel_hi:[1,0]
	v_pk_mul_f32 v[18:19], v[18:19], v[130:131] op_sel_hi:[1,0]
	v_pk_mul_f32 v[16:17], v[16:17], v[130:131] op_sel_hi:[1,0]
	v_cmp_lt_f32_e32 vcc, 0xefa18f08, v120
	s_nop 1
	v_cndmask_b32_e32 v232, 0, v120, vcc
	v_sub_f32_e32 v230, v232, v230
	v_sub_f32_e32 v127, v127, v230
	v_sub_f32_e32 v116, v116, v230
	v_sub_f32_e32 v117, v117, v230
	v_sub_f32_e32 v114, v114, v230
	v_sub_f32_e32 v113, v113, v230
	v_sub_f32_e32 v112, v112, v230
	v_sub_f32_e32 v128, v128, v230
	v_sub_f32_e32 v118, v118, v230
	v_mov_b32_e32 v230, v232
	s_branch .LBB0_462
; __device__ __forceinline__ void kv_lwrite(const KVRegs& r, char* lds, int buf) {
;   const int tid = TIDX, row = tid >> 3, cq = tid & 7;
; template <int MODE>
; __device__ __forceinline__ void nsa_compute(int cur, int buf, int t, int hl, u64 mymask, const bf16x8 (&Qf)[2][2], f32x4 (&O)[4][2], float (&m)[2], float (&l)[2],
;                                             const float (&inv)[2], float* impw, char* lds) {
;     ...
;         const float mxa = fmaxf(fmaxf(sv[0][0], sv[0][1]), sv[0][2]), mxb = fmaxf(fmaxf(sv[0][3], sv[1][0]), sv[1][1]);
;         float mx = fmaxf(fmaxf(fmaxf(sv[1][2], sv[1][3]), mxa), mxb);
;         if (MODE == 2) mx = selok ? mx : -__builtin_inff();
;         if (__any(mx > m[r] + 8.0f)) {
;           mx = fmaxf(mx, __shfl_xor(mx, 16)); mx = fmaxf(mx, __shfl_xor(mx, 32));
;           const float mn = fmaxf(m[r], mx), al = __builtin_amdgcn_exp2f(m[r] - mn);
;           m[r] = mn; l[r] *= al;
;           if (MODE != 0) {
; #pragma unroll
;             for (int df = 0; df < 4; ++df) O[df][r] *= al;
;           }
;         }
;         const float me = (MODE == 2) ? (selok ? m[r] : __builtin_inff()) : m[r];
;         float ps = 0.f;
; #pragma unroll
;         for (int kk = 0; kk < 2; ++kk)
; #pragma unroll
;           for (int e = 0; e < 4; ++e) { pv[kk][e] = __builtin_amdgcn_exp2f(sv[kk][e] - me); ps += pv[kk][e]; }
;         l[r] += ps;
;       }
;       if (MODE != 0) {
;         const unsigned w0 = pk2(pv[0][0], pv[0][1]), w1 = pk2(pv[0][2], pv[0][3]), w2 = pk2(pv[1][0], pv[1][1]), w3 = pk2(pv[1][2], pv[1][3]);
;         u32x4 pw; pw.x = w0; pw.y = w1; pw.z = w2; pw.w = w3;
;         Pf[r] = __builtin_bit_cast(bf16x8, pw);
;       }
;     }
;     if (MODE != 0) {
;       bf16x8 vfr[4];
; #pragma unroll
;       for (int df = 0; df < 4; ++df) {
;         const bf16x4 va = *(const bf16x4*)(vt + (df * 16 + fr) * 68 + 32 * s2 + 4 * fq);
;         const bf16x4 vb = *(const bf16x4*)(vt + (df * 16 + fr) * 68 + 32 * s2 + 16 + 4 * fq);
;         bf16x8 vf; vf[0] = va[0]; vf[1] = va[1]; vf[2] = va[2]; vf[3] = va[3]; vf[4] = vb[0]; vf[5] = vb[1]; vf[6] = vb[2]; vf[7] = vb[3];
;         vfr[df] = vf;
;       }
;       __builtin_amdgcn_s_setprio(1);
; #pragma unroll
;       for (int df = 0; df < 4; ++df)
; #pragma unroll
;         for (int r = 0; r < 2; ++r) O[df][r] = mfma16(vfr[df], Pf[r], O[df][r]);
;       __builtin_amdgcn_s_setprio(0);
.LBB0_461:
.LBB0_462:
	v_exp_f32_e32 v115, v127
	v_exp_f32_e32 v116, v116
	v_exp_f32_e32 v117, v117
	v_exp_f32_e32 v114, v114
	v_add_f32_e32 v119, 0, v115
	v_add_f32_e32 v119, v116, v119
	v_add_f32_e32 v119, v117, v119
	v_add_f32_e32 v120, v114, v119
	v_exp_f32_e32 v119, v113
	s_nop 0
	v_add_f32_e32 v113, v119, v120
	v_exp_f32_e32 v120, v112
	s_nop 0
	v_add_f32_e32 v112, v120, v113
	v_exp_f32_e32 v121, v128
	v_exp_f32_e32 v118, v118
	v_add_f32_e32 v112, v121, v112
	v_add_f32_e32 v112, v118, v112
	v_add_f32_e32 v146, v146, v112
	s_waitcnt lgkmcnt(3)
	v_fmamk_f32 v113, v108, 0x3e38aa3b, v171
	v_fmamk_f32 v112, v109, 0x3e38aa3b, v170
	s_waitcnt lgkmcnt(2)
	v_fmamk_f32 v109, v110, 0x3e38aa3b, v173
	v_fmamk_f32 v108, v111, 0x3e38aa3b, v172
	s_waitcnt lgkmcnt(1)
	v_fmamk_f32 v111, v104, 0x3e38aa3b, v175
	v_fmamk_f32 v110, v105, 0x3e38aa3b, v174
	s_waitcnt lgkmcnt(0)
	v_fmamk_f32 v105, v106, 0x3e38aa3b, v193
	v_fmamk_f32 v104, v107, 0x3e38aa3b, v192
	v_max3_f32 v106, v113, v112, v109
	v_max3_f32 v107, v108, v111, v110
	v_max_f32_e32 v122, v105, v104
	v_max3_f32 v106, v122, v106, v107
	v_cndmask_b32_e64 v106, v106, v225, s[36:37]
	v_sub_f32_e32 v107, v189, v231
	v_add_f32_e32 v107, 0x41000000, v107
	v_cmp_gt_f32_e32 vcc, v106, v107
	s_cbranch_vccz .LBB0_464
	v_add_f32_e32 v106, v106, v231
	ds_bpermute_b32 v107, v233, v106
	v_max_f32_e32 v106, v106, v106
	s_waitcnt lgkmcnt(0)
	v_max_f32_e32 v107, v107, v107
	v_max_f32_e32 v106, v106, v107
	ds_bpermute_b32 v107, v234, v106
	s_waitcnt lgkmcnt(0)
	v_max3_f32 v106, v189, v106, v107
	v_sub_f32_e32 v107, v189, v106
	v_exp_f32_e32 v122, v107
	v_mov_b32_e32 v189, v106
	v_mul_f32_e32 v147, v147, v122
	v_pk_mul_f32 v[46:47], v[46:47], v[122:123] op_sel_hi:[1,0]
	v_pk_mul_f32 v[44:45], v[44:45], v[122:123] op_sel_hi:[1,0]
	v_pk_mul_f32 v[42:43], v[42:43], v[122:123] op_sel_hi:[1,0]
	v_pk_mul_f32 v[40:41], v[40:41], v[122:123] op_sel_hi:[1,0]
	v_pk_mul_f32 v[38:39], v[38:39], v[122:123] op_sel_hi:[1,0]
	v_pk_mul_f32 v[36:37], v[36:37], v[122:123] op_sel_hi:[1,0]
	v_pk_mul_f32 v[34:35], v[34:35], v[122:123] op_sel_hi:[1,0]
	v_pk_mul_f32 v[32:33], v[32:33], v[122:123] op_sel_hi:[1,0]
	v_cmp_lt_f32_e32 vcc, 0xefa18f08, v106
	s_nop 1
	v_cndmask_b32_e32 v232, 0, v106, vcc
	v_sub_f32_e32 v231, v232, v231
	v_sub_f32_e32 v113, v113, v231
	v_sub_f32_e32 v112, v112, v231
	v_sub_f32_e32 v109, v109, v231
	v_sub_f32_e32 v108, v108, v231
	v_sub_f32_e32 v111, v111, v231
	v_sub_f32_e32 v110, v110, v231
	v_sub_f32_e32 v105, v105, v231
	v_sub_f32_e32 v104, v104, v231
	v_mov_b32_e32 v231, v232
	s_branch .LBB0_465
.LBB0_464:
.LBB0_465:
	v_exp_f32_e32 v136, v113
	v_exp_f32_e32 v137, v112
	v_exp_f32_e32 v138, v109
	v_exp_f32_e32 v139, v108
	v_cvt_pk_bf16_f32 v132, v115, v116
	v_cvt_pk_bf16_f32 v133, v117, v114
	v_cvt_pk_bf16_f32 v134, v119, v120
	v_cvt_pk_bf16_f32 v135, v121, v118
	v_exp_f32_e32 v140, v111
	v_mov_b32_e32 v107, v110
	ds_read2_b64 v[108:111], v123 offset0:8 offset1:12
	ds_read2_b64 v[112:115], v124 offset0:24 offset1:28
	ds_read2_b64 v[116:119], v125 offset0:40 offset1:44
	ds_read2_b64 v[120:123], v126 offset0:56 offset1:60
	v_exp_f32_e32 v141, v107
	v_exp_f32_e32 v142, v105
	v_exp_f32_e32 v143, v104
	v_cvt_pk_bf16_f32 v148, v136, v137
	v_cvt_pk_bf16_f32 v149, v138, v139
	v_cvt_pk_bf16_f32 v150, v140, v141
	v_cvt_pk_bf16_f32 v151, v142, v143
	s_setprio 1
	s_waitcnt lgkmcnt(3)
	v_mfma_f32_16x16x32_bf16 v[104:107], v[108:111], v[132:135], v[28:31]
	v_mfma_f32_16x16x32_bf16 v[108:111], v[108:111], v[148:151], v[44:47]
	s_waitcnt lgkmcnt(2)
	v_mfma_f32_16x16x32_bf16 v[124:127], v[112:115], v[132:135], v[24:27]
	v_mfma_f32_16x16x32_bf16 v[112:115], v[112:115], v[148:151], v[40:43]
	s_waitcnt lgkmcnt(1)
	v_mfma_f32_16x16x32_bf16 v[128:131], v[116:119], v[132:135], v[20:23]
	v_mfma_f32_16x16x32_bf16 v[116:119], v[116:119], v[148:151], v[36:39]
	s_waitcnt lgkmcnt(0)
	v_mfma_f32_16x16x32_bf16 v[132:135], v[120:123], v[132:135], v[16:19]
	v_mfma_f32_16x16x32_bf16 v[120:123], v[120:123], v[148:151], v[32:35]
	s_setprio 0
	s_cmp_lt_i32 s62, 0
	s_cbranch_scc1 .LBB0_467
	v_mov_b32 v16, v179
	s_nop 0
	v_ashrrev_i32_e32 v17, 3, v16
	v_xor_b32_e32 v19, v17, v16
	v_lshlrev_b32_e32 v16, 3, v16
	v_lshlrev_b32_e32 v19, 4, v19
	v_and_b32_e32 v16, 56, v16
	v_lshlrev_b32_e32 v18, 7, v17
	v_and_b32_e32 v19, 0x70, v19
	v_mul_u32_u24_e32 v16, 0x88, v16
	v_lshlrev_b32_e32 v17, 1, v17
	v_add3_u32 v18, s63, v18, v19
	v_add3_u32 v16, s71, v16, v17
	s_waitcnt vmcnt(1)
	ds_write_b128 v18, v[64:67]
	s_waitcnt vmcnt(0)
	ds_write_b16 v16, v68 offset:16384
	ds_write_b16_d16_hi v16, v68 offset:16520
	ds_write_b16 v16, v69 offset:16656
	ds_write_b16_d16_hi v16, v69 offset:16792
	ds_write_b16 v16, v70 offset:16928
	ds_write_b16_d16_hi v16, v70 offset:17064
	ds_write_b16 v16, v71 offset:17200
	ds_write_b16_d16_hi v16, v71 offset:17336

; template <int MODE>
; __device__ __forceinline__ void nsa_compute(int cur, int buf, int t, int hl, u64 mymask, const bf16x8 (&Qf)[2][2], f32x4 (&O)[4][2], float (&m)[2], float (&l)[2],
;                                             const float (&inv)[2], float* impw, char* lds) {
;     ...
;   const bool selok = (MODE == 2) ? (((mymask >> cur) & 1ull) != 0ull) : true;
;   const float* tb = (MODE == 3) ? (const float*)(lds + NSA_TW) + hl * 640 : (const float*)(lds + NSA_T) + hl * 4160;
;   constexpr int TS = (MODE == 3) ? 640 : 4160;
;   const int base = (MODE <= 1) ? (t - 31 - 16 * (cur * 64 + 4 * fq) + 64) : (t - cur * 64 - 4 * fq + 64);
; #pragma unroll
;   for (int s2 = 0; s2 < 2; ++s2) {
;     f32x4 S[2][2] = {};
;     bf16x8 kfr[2][2];
; #pragma unroll
;     for (int ks = 0; ks < 2; ++ks)
; #pragma unroll
;       for (int kk = 0; kk < 2; ++kk) kfr[ks][kk] = *(const bf16x8*)(kt + (32 * s2 + 16 * kk + fr) * 128 + (((ks * 4 + fq) ^ (fr & 7)) << 4));
;     __builtin_amdgcn_s_setprio(1);
; #pragma unroll
;     for (int ks = 0; ks < 2; ++ks)
; #pragma unroll
;       for (int kk = 0; kk < 2; ++kk)
; #pragma unroll
;         for (int r = 0; r < 2; ++r) S[kk][r] = mfma16(kfr[ks][kk], Qf[r][ks], S[kk][r]);
;     __builtin_amdgcn_s_setprio(0);
;     bf16x8 Pf[2];
;     float g1s[2] = {0.f, 0.f}, p3s[2] = {0.f, 0.f};
; #pragma unroll
;     for (int r = 0; r < 2; ++r) {
;       float sv[2][4];
; #pragma unroll
;       for (int kk = 0; kk < 2; ++kk)
; #pragma unroll
;         for (int e = 0; e < 4; ++e) {
;           const int off = 32 * s2 + 16 * kk + e;
;           int idx;
;           if (MODE <= 1) { idx = base - 16 * off; idx = idx > 0 ? idx : 0; } else idx = base - off;
;           sv[kk][e] = S[kk][r][e] * (0.125f * LOG2E) + tb[r * TS + idx];
;         }
;       float pv[2][4];
;       if (MODE == 1) {
; #pragma unroll
;         for (int kk = 0; kk < 2; ++kk)
; #pragma unroll
;           for (int e = 0; e < 4; ++e) pv[kk][e] = __builtin_amdgcn_exp2f(sv[kk][e] - m[r]) * inv[r];
; #pragma unroll
;         for (int kk = 0; kk < 2; ++kk) { g1s[kk] += pv[kk][0] + pv[kk][1] + pv[kk][2] + 0.5f * pv[kk][3]; p3s[kk] += 0.5f * pv[kk][3]; }
;       } else {
;         const float mxa = fmaxf(fmaxf(sv[0][0], sv[0][1]), sv[0][2]), mxb = fmaxf(fmaxf(sv[0][3], sv[1][0]), sv[1][1]);
;         float mx = fmaxf(fmaxf(fmaxf(sv[1][2], sv[1][3]), mxa), mxb);
.LBB0_469:
	v_add_f32_e32 v16, 0, v136
	v_add_f32_e32 v16, v137, v16
	v_add_f32_e32 v16, v138, v16
	v_add_f32_e32 v16, v139, v16
	v_add_f32_e32 v16, v140, v16
	v_add_f32_e32 v16, v141, v16
	v_add_f32_e32 v16, v142, v16
	v_add_f32_e32 v16, v143, v16
	v_add_f32_e32 v147, v147, v16
	s_mov_b64 s[36:37], -1
	s_cmp_lt_i32 s62, 0
	s_mov_b64 vcc, -1
	s_cbranch_scc1 .LBB0_487
	s_lshl_b64 s[36:37], 1, s62
	v_mov_b32 v18, v179
	v_and_b32_e32 v17, s37, v187
	v_lshrrev_b32_e32 v19, 4, v18
	v_bfe_u32 v24, v18, 4, 2
	v_and_b32_e32 v16, s36, v186
	v_and_b32_e32 v25, 7, v18
	v_and_b32_e32 v150, 15, v18
	v_cmp_eq_u64_e64 s[36:37], 0, v[16:17]
	v_lshlrev_b32_e32 v151, 2, v24
	v_bitop3_b32 v16, v19, v25, 3 bitop3:0x6c
	v_bitop3_b32 v24, v24, v25, 4 bitop3:0x36
	v_lshlrev_b32_e32 v26, 7, v150
	v_lshl_add_u32 v16, v16, 4, s63
	v_lshl_add_u32 v24, v24, 4, s63
	v_add_u32_e32 v148, v16, v26
	v_add_u32_e32 v149, v24, v26
	ds_read_b128 v[16:19], v148
	ds_read_b128 v[20:23], v148 offset:2048
	ds_read_b128 v[24:27], v149
	ds_read_b128 v[32:35], v149 offset:2048
	v_sub_u32_e32 v251, v180, v151
	v_lshl_add_u32 v251, v251, 2, v181
	s_lshl_b32 s16, s62, 8
	v_subrev_u32_e32 v250, s16, v251
	v_add_u32_e32 v249, 0x8400, v250
	v_add_u32_e32 v248, 0xc500, v250
	ds_read2_b32 v[192:193], v249 offset0:63 offset1:64
	ds_read2_b32 v[194:195], v249 offset0:61 offset1:62
	ds_read2_b32 v[198:199], v249 offset0:47 offset1:48
	ds_read2_b32 v[200:201], v249 offset0:45 offset1:46
	ds_read2_b32 v[202:203], v248 offset0:63 offset1:64
	ds_read2_b32 v[204:205], v248 offset0:61 offset1:62
	ds_read2_b32 v[206:207], v248 offset0:47 offset1:48
	ds_read2_b32 v[208:209], v248 offset0:45 offset1:46
	s_setprio 1
	s_waitcnt lgkmcnt(11)
	v_mfma_f32_16x16x32_bf16 v[28:31], v[16:19], v[0:3], 0
	v_mfma_f32_16x16x32_bf16 v[16:19], v[16:19], v[8:11], 0
	s_waitcnt lgkmcnt(10)
	v_mfma_f32_16x16x32_bf16 v[36:39], v[20:23], v[0:3], 0
	v_mfma_f32_16x16x32_bf16 v[20:23], v[20:23], v[8:11], 0
	s_waitcnt lgkmcnt(9)
	v_mfma_f32_16x16x32_bf16 v[40:43], v[24:27], v[4:7], v[28:31]
	v_mfma_f32_16x16x32_bf16 v[28:31], v[24:27], v[12:15], v[16:19]
	s_waitcnt lgkmcnt(8)
	v_mfma_f32_16x16x32_bf16 v[16:19], v[32:35], v[4:7], v[36:39]
	v_mfma_f32_16x16x32_bf16 v[20:23], v[32:35], v[12:15], v[20:23]
	s_setprio 0
	v_cndmask_b32_e64 v232, v230, v228, s[36:37]
	s_waitcnt lgkmcnt(4)
	v_sub_f32_e32 v193, v193, v232
	v_sub_f32_e32 v192, v192, v232
	v_sub_f32_e32 v195, v195, v232
	v_sub_f32_e32 v194, v194, v232
	v_sub_f32_e32 v199, v199, v232
	v_sub_f32_e32 v198, v198, v232
	v_sub_f32_e32 v201, v201, v232
	v_sub_f32_e32 v200, v200, v232
	v_cndmask_b32_e64 v232, v231, v228, s[36:37]
	s_waitcnt lgkmcnt(0)
	v_sub_f32_e32 v203, v203, v232
	v_sub_f32_e32 v202, v202, v232
	v_sub_f32_e32 v205, v205, v232
	v_sub_f32_e32 v204, v204, v232
	v_sub_f32_e32 v207, v207, v232
	v_sub_f32_e32 v206, v206, v232
	v_sub_f32_e32 v209, v209, v232
	v_sub_f32_e32 v208, v208, v232
	v_sub_u32_e32 v24, v180, v151
	v_lshl_add_u32 v24, v24, 2, v181
	v_subrev_u32_e32 v158, s16, v24
	s_waitcnt lgkmcnt(7)
	v_fmamk_f32 v47, v40, 0x3e38aa3b, v193
	v_fmamk_f32 v46, v41, 0x3e38aa3b, v192
	s_waitcnt lgkmcnt(6)
	v_fmamk_f32 v39, v42, 0x3e38aa3b, v195
	v_fmamk_f32 v38, v43, 0x3e38aa3b, v194
	s_waitcnt lgkmcnt(5)
	v_fmamk_f32 v37, v16, 0x3e38aa3b, v199
	v_fmamk_f32 v36, v17, 0x3e38aa3b, v198
	v_max3_f32 v16, v47, v46, v39
	v_max3_f32 v17, v38, v37, v36
	s_waitcnt lgkmcnt(4)
	v_fmamk_f32 v45, v18, 0x3e38aa3b, v201
	v_fmamk_f32 v44, v19, 0x3e38aa3b, v200
	v_max_f32_e32 v18, v45, v44
	v_max3_f32 v16, v18, v16, v17
	v_cndmask_b32_e64 v16, v16, v225, s[36:37]
	v_sub_f32_e32 v17, v188, v230
	v_add_f32_e32 v17, 0x41000000, v17
	v_cmp_gt_f32_e32 vcc, v16, v17
	s_cbranch_vccz .LBB0_472
	v_add_f32_e32 v16, v16, v230
	ds_bpermute_b32 v17, v233, v16
	v_max_f32_e32 v16, v16, v16
	v_mov_b32_e32 v137, v189
	v_mov_b32_e32 v191, v147
	s_waitcnt lgkmcnt(0)
	v_max_f32_e32 v17, v17, v17
	v_max_f32_e32 v16, v16, v17
	ds_bpermute_b32 v17, v234, v16
	s_waitcnt lgkmcnt(0)
	v_max3_f32 v136, v188, v16, v17
	v_sub_f32_e32 v16, v188, v136
	v_exp_f32_e32 v40, v16
	v_mov_b64_e32 v[188:189], v[136:137]
	v_mul_f32_e32 v190, v146, v40
	v_pk_mul_f32 v[18:19], v[106:107], v[40:41] op_sel_hi:[1,0]
	v_pk_mul_f32 v[16:17], v[104:105], v[40:41] op_sel_hi:[1,0]
	v_pk_mul_f32 v[26:27], v[126:127], v[40:41] op_sel_hi:[1,0]
	v_pk_mul_f32 v[24:25], v[124:125], v[40:41] op_sel_hi:[1,0]
	v_pk_mul_f32 v[34:35], v[130:131], v[40:41] op_sel_hi:[1,0]
	v_pk_mul_f32 v[32:33], v[128:129], v[40:41] op_sel_hi:[1,0]
	v_pk_mul_f32 v[42:43], v[134:135], v[40:41] op_sel_hi:[1,0]
	v_pk_mul_f32 v[40:41], v[132:133], v[40:41] op_sel_hi:[1,0]
	v_cmp_lt_f32_e32 vcc, 0xefa18f08, v136
	s_nop 1
	v_cndmask_b32_e32 v232, 0, v136, vcc
	v_sub_f32_e32 v230, v232, v230
	v_sub_f32_e32 v47, v47, v230
	v_sub_f32_e32 v46, v46, v230
	v_sub_f32_e32 v39, v39, v230
	v_sub_f32_e32 v38, v38, v230
	v_sub_f32_e32 v37, v37, v230
	v_sub_f32_e32 v36, v36, v230
	v_sub_f32_e32 v45, v45, v230
	v_sub_f32_e32 v44, v44, v230
	v_mov_b32_e32 v230, v232
	s_branch .LBB0_473

; template <int MODE>
; __device__ __forceinline__ void nsa_compute(int cur, int buf, int t, int hl, u64 mymask, const bf16x8 (&Qf)[2][2], f32x4 (&O)[4][2], float (&m)[2], float (&l)[2],
;                                             const float (&inv)[2], float* impw, char* lds) {
;     ...
;         const float mxa = fmaxf(fmaxf(sv[0][0], sv[0][1]), sv[0][2]), mxb = fmaxf(fmaxf(sv[0][3], sv[1][0]), sv[1][1]);
;         float mx = fmaxf(fmaxf(fmaxf(sv[1][2], sv[1][3]), mxa), mxb);
;         if (MODE == 2) mx = selok ? mx : -__builtin_inff();
;         if (__any(mx > m[r] + 8.0f)) {
;           mx = fmaxf(mx, __shfl_xor(mx, 16)); mx = fmaxf(mx, __shfl_xor(mx, 32));
;           const float mn = fmaxf(m[r], mx), al = __builtin_amdgcn_exp2f(m[r] - mn);
;           m[r] = mn; l[r] *= al;
;           if (MODE != 0) {
; #pragma unroll
;             for (int df = 0; df < 4; ++df) O[df][r] *= al;
;           }
;         }
;         const float me = (MODE == 2) ? (selok ? m[r] : __builtin_inff()) : m[r];
;         float ps = 0.f;
; #pragma unroll
;         for (int kk = 0; kk < 2; ++kk)
; #pragma unroll
;           for (int e = 0; e < 4; ++e) { pv[kk][e] = __builtin_amdgcn_exp2f(sv[kk][e] - me); ps += pv[kk][e]; }
;         l[r] += ps;
.LBB0_473:
	v_exp_f32_e32 v152, v47
	v_exp_f32_e32 v153, v46
	v_exp_f32_e32 v154, v39
	v_exp_f32_e32 v155, v38
	v_add_f32_e32 v47, 0, v152
	v_exp_f32_e32 v156, v37
	v_add_f32_e32 v46, v153, v47
	v_exp_f32_e32 v157, v36
	v_add_f32_e32 v39, v154, v46
	v_add_f32_e32 v38, v155, v39
	v_add_f32_e32 v37, v156, v38
	v_add_f32_e32 v36, v157, v37
	v_exp_f32_e32 v159, v45
	v_exp_f32_e32 v160, v44
	v_add_f32_e32 v36, v159, v36
	v_add_f32_e32 v36, v160, v36
	v_add_f32_e32 v190, v190, v36
	s_waitcnt lgkmcnt(3)
	v_fmamk_f32 v139, v28, 0x3e38aa3b, v203
	v_fmamk_f32 v138, v29, 0x3e38aa3b, v202
	s_waitcnt lgkmcnt(2)
	v_fmamk_f32 v141, v30, 0x3e38aa3b, v205
	v_fmamk_f32 v140, v31, 0x3e38aa3b, v204
	s_waitcnt lgkmcnt(1)
	v_fmamk_f32 v137, v20, 0x3e38aa3b, v207
	v_fmamk_f32 v136, v21, 0x3e38aa3b, v206
	v_max3_f32 v20, v139, v138, v141
	v_max3_f32 v21, v140, v137, v136
	s_waitcnt lgkmcnt(0)
	v_fmamk_f32 v143, v22, 0x3e38aa3b, v209
	v_fmamk_f32 v142, v23, 0x3e38aa3b, v208
	v_max_f32_e32 v22, v143, v142
	v_max3_f32 v20, v22, v20, v21
	v_cndmask_b32_e64 v20, v20, v225, s[36:37]
	v_sub_f32_e32 v21, v189, v231
	v_add_f32_e32 v21, 0x41000000, v21
	v_cmp_gt_f32_e32 vcc, v20, v21
	s_cbranch_vccz .LBB0_475
	v_add_f32_e32 v20, v20, v231
	ds_bpermute_b32 v21, v233, v20
	v_max_f32_e32 v20, v20, v20
	s_waitcnt lgkmcnt(0)
	v_max_f32_e32 v21, v21, v21
	v_max_f32_e32 v20, v20, v21
	ds_bpermute_b32 v21, v234, v20
	s_waitcnt lgkmcnt(0)
	v_max3_f32 v161, v189, v20, v21
	v_sub_f32_e32 v20, v189, v161
	v_exp_f32_e32 v44, v20
	v_mov_b32_e32 v189, v161
	v_mul_f32_e32 v191, v191, v44
	v_pk_mul_f32 v[22:23], v[110:111], v[44:45] op_sel_hi:[1,0]
	v_pk_mul_f32 v[20:21], v[108:109], v[44:45] op_sel_hi:[1,0]
	v_pk_mul_f32 v[30:31], v[114:115], v[44:45] op_sel_hi:[1,0]
	v_pk_mul_f32 v[28:29], v[112:113], v[44:45] op_sel_hi:[1,0]
	v_pk_mul_f32 v[38:39], v[118:119], v[44:45] op_sel_hi:[1,0]
	v_pk_mul_f32 v[36:37], v[116:117], v[44:45] op_sel_hi:[1,0]
	v_pk_mul_f32 v[46:47], v[122:123], v[44:45] op_sel_hi:[1,0]
	v_pk_mul_f32 v[44:45], v[120:121], v[44:45] op_sel_hi:[1,0]
	v_cmp_lt_f32_e32 vcc, 0xefa18f08, v161
	s_nop 1
	v_cndmask_b32_e32 v232, 0, v161, vcc
	v_sub_f32_e32 v231, v232, v231
	v_sub_f32_e32 v139, v139, v231
	v_sub_f32_e32 v138, v138, v231
	v_sub_f32_e32 v141, v141, v231
	v_sub_f32_e32 v140, v140, v231
	v_sub_f32_e32 v137, v137, v231
	v_sub_f32_e32 v136, v136, v231
	v_sub_f32_e32 v143, v143, v231
	v_sub_f32_e32 v142, v142, v231
	v_mov_b32_e32 v231, v232
	s_branch .LBB0_476

; template <int MODE>
; __device__ __forceinline__ void nsa_compute(int cur, int buf, int t, int hl, u64 mymask, const bf16x8 (&Qf)[2][2], f32x4 (&O)[4][2], float (&m)[2], float (&l)[2],
;                                             const float (&inv)[2], float* impw, char* lds) {
;     ...
; #pragma unroll
;     for (int ks = 0; ks < 2; ++ks)
; #pragma unroll
;       for (int kk = 0; kk < 2; ++kk) kfr[ks][kk] = *(const bf16x8*)(kt + (32 * s2 + 16 * kk + fr) * 128 + (((ks * 4 + fq) ^ (fr & 7)) << 4));
;     __builtin_amdgcn_s_setprio(1);
; #pragma unroll
;     for (int ks = 0; ks < 2; ++ks)
; #pragma unroll
;       for (int kk = 0; kk < 2; ++kk)
; #pragma unroll
;         for (int r = 0; r < 2; ++r) S[kk][r] = mfma16(kfr[ks][kk], Qf[r][ks], S[kk][r]);
;     __builtin_amdgcn_s_setprio(0);
;     bf16x8 Pf[2];
;     float g1s[2] = {0.f, 0.f}, p3s[2] = {0.f, 0.f};
; #pragma unroll
;     for (int r = 0; r < 2; ++r) {
;       float sv[2][4];
; #pragma unroll
;       for (int kk = 0; kk < 2; ++kk)
; #pragma unroll
;         for (int e = 0; e < 4; ++e) {
;     ...
;         const float me = (MODE == 2) ? (selok ? m[r] : __builtin_inff()) : m[r];
;         float ps = 0.f;
; #pragma unroll
;         for (int kk = 0; kk < 2; ++kk)
; #pragma unroll
;           for (int e = 0; e < 4; ++e) { pv[kk][e] = __builtin_amdgcn_exp2f(sv[kk][e] - me); ps += pv[kk][e]; }
;         l[r] += ps;
;       }
;       if (MODE != 0) {
;         const unsigned w0 = pk2(pv[0][0], pv[0][1]), w1 = pk2(pv[0][2], pv[0][3]), w2 = pk2(pv[1][0], pv[1][1]), w3 = pk2(pv[1][2], pv[1][3]);
;         u32x4 pw; pw.x = w0; pw.y = w1; pw.z = w2; pw.w = w3;
;         Pf[r] = __builtin_bit_cast(bf16x8, pw);
;       }
;     }
;     if (MODE != 0) {
;       bf16x8 vfr[4];
; #pragma unroll
;       for (int df = 0; df < 4; ++df) {
;         const bf16x4 va = *(const bf16x4*)(vt + (df * 16 + fr) * 68 + 32 * s2 + 4 * fq);
;         const bf16x4 vb = *(const bf16x4*)(vt + (df * 16 + fr) * 68 + 32 * s2 + 16 + 4 * fq);
;         bf16x8 vf; vf[0] = va[0]; vf[1] = va[1]; vf[2] = va[2]; vf[3] = va[3]; vf[4] = vb[0]; vf[5] = vb[1]; vf[6] = vb[2]; vf[7] = vb[3];
;         vfr[df] = vf;
;       }
;       __builtin_amdgcn_s_setprio(1);
; #pragma unroll
;       for (int df = 0; df < 4; ++df)
; #pragma unroll
;         for (int r = 0; r < 2; ++r) O[df][r] = mfma16(vfr[df], Pf[r], O[df][r]);
;       __builtin_amdgcn_s_setprio(0);
.LBB0_476:
	v_cvt_pk_bf16_f32 v152, v152, v153
	v_cvt_pk_bf16_f32 v153, v154, v155
	v_cvt_pk_bf16_f32 v154, v156, v157
	v_exp_f32_e32 v139, v139
	v_exp_f32_e32 v138, v138
	v_exp_f32_e32 v141, v141
	v_exp_f32_e32 v140, v140
	v_cvt_pk_bf16_f32 v155, v159, v160
	v_add_f32_e32 v157, 0, v139
	v_exp_f32_e32 v159, v137
	v_add_f32_e32 v157, v138, v157
	v_add_f32_e32 v157, v141, v157
	v_add_f32_e32 v157, v140, v157
	v_add_f32_e32 v137, v159, v157
	v_exp_f32_e32 v157, v136
	s_nop 0
	v_add_f32_e32 v136, v157, v137
	v_exp_f32_e32 v143, v143
	v_exp_f32_e32 v142, v142
	v_cvt_pk_bf16_f32 v137, v141, v140
	v_mul_u32_u24_e32 v140, 0x44, v150
	v_add_f32_e32 v136, v143, v136
	v_lshlrev_b32_e32 v140, 1, v140
	v_lshlrev_b32_e32 v141, 1, v151
	v_add_f32_e32 v136, v142, v136
	v_add3_u32 v150, s71, v140, v141
	v_add_f32_e32 v191, v191, v136
	v_cvt_pk_bf16_f32 v136, v139, v138
	v_cvt_pk_bf16_f32 v138, v159, v157
	v_add_u32_e32 v159, 0x4000, v150
	v_add_u32_e32 v160, 0x4800, v150
	v_cvt_pk_bf16_f32 v139, v143, v142
	ds_read2_b64 v[140:143], v159 offset1:4
	ds_read2_b64 v[164:167], v160 offset0:16 offset1:20
	v_add_u32_e32 v161, 0x5000, v150
	v_add_u32_e32 v162, 0x5800, v150
	ds_read2_b64 v[168:171], v161 offset0:32 offset1:36
	ds_read2_b64 v[172:175], v162 offset0:48 offset1:52
	s_setprio 1
	s_waitcnt lgkmcnt(3)
	v_mfma_f32_16x16x32_bf16 v[16:19], v[140:143], v[152:155], v[16:19]
	v_mfma_f32_16x16x32_bf16 v[20:23], v[140:143], v[136:139], v[20:23]
	s_waitcnt lgkmcnt(2)
	v_mfma_f32_16x16x32_bf16 v[24:27], v[164:167], v[152:155], v[24:27]
	v_mfma_f32_16x16x32_bf16 v[28:31], v[164:167], v[136:139], v[28:31]
	s_waitcnt lgkmcnt(1)
	v_mfma_f32_16x16x32_bf16 v[32:35], v[168:171], v[152:155], v[32:35]
	v_mfma_f32_16x16x32_bf16 v[36:39], v[168:171], v[136:139], v[36:39]
	s_waitcnt lgkmcnt(0)
	v_mfma_f32_16x16x32_bf16 v[40:43], v[172:175], v[152:155], v[40:43]
	v_mfma_f32_16x16x32_bf16 v[44:47], v[172:175], v[136:139], v[44:47]
	s_setprio 0
	ds_read_b128 v[136:139], v148 offset:4096
	ds_read_b128 v[140:143], v148 offset:6144
	ds_read_b128 v[150:153], v149 offset:4096
	ds_read_b128 v[154:157], v149 offset:6144
	v_add_u32_e32 v251, 0x8400, v158
	v_add_u32_e32 v250, 0xc500, v158
	ds_read2_b32 v[192:193], v251 offset0:31 offset1:32
	ds_read2_b32 v[194:195], v251 offset0:29 offset1:30
	ds_read2_b32 v[198:199], v251 offset0:15 offset1:16
	ds_read2_b32 v[200:201], v251 offset0:13 offset1:14
	ds_read2_b32 v[202:203], v250 offset0:31 offset1:32
	ds_read2_b32 v[204:205], v250 offset0:29 offset1:30
	ds_read2_b32 v[206:207], v250 offset0:15 offset1:16
	ds_read2_b32 v[208:209], v250 offset0:13 offset1:14
	s_setprio 1
	s_waitcnt lgkmcnt(11)
	v_mfma_f32_16x16x32_bf16 v[164:167], v[136:139], v[0:3], 0
	v_mfma_f32_16x16x32_bf16 v[136:139], v[136:139], v[8:11], 0
	s_waitcnt lgkmcnt(10)
	v_mfma_f32_16x16x32_bf16 v[172:175], v[140:143], v[8:11], 0
	v_mfma_f32_16x16x32_bf16 v[168:171], v[140:143], v[0:3], 0
	s_waitcnt lgkmcnt(9)
	v_mfma_f32_16x16x32_bf16 v[164:167], v[150:153], v[4:7], v[164:167]
	v_mfma_f32_16x16x32_bf16 v[140:143], v[150:153], v[12:15], v[136:139]
	s_waitcnt lgkmcnt(8)
	v_mfma_f32_16x16x32_bf16 v[136:139], v[154:157], v[12:15], v[172:175]
	v_mfma_f32_16x16x32_bf16 v[168:171], v[154:157], v[4:7], v[168:171]
	s_setprio 0
	v_cndmask_b32_e64 v232, v230, v228, s[36:37]
	s_waitcnt lgkmcnt(4)
	v_sub_f32_e32 v193, v193, v232
	v_sub_f32_e32 v192, v192, v232
	v_sub_f32_e32 v195, v195, v232
	v_sub_f32_e32 v194, v194, v232
	v_sub_f32_e32 v199, v199, v232
	v_sub_f32_e32 v198, v198, v232
	v_sub_f32_e32 v201, v201, v232
	v_sub_f32_e32 v200, v200, v232
	v_cndmask_b32_e64 v232, v231, v228, s[36:37]
	s_waitcnt lgkmcnt(0)
	v_sub_f32_e32 v203, v203, v232
	v_sub_f32_e32 v202, v202, v232
	v_sub_f32_e32 v205, v205, v232
	v_sub_f32_e32 v204, v204, v232
	v_sub_f32_e32 v207, v207, v232
	v_sub_f32_e32 v206, v206, v232
	v_sub_f32_e32 v209, v209, v232
	v_sub_f32_e32 v208, v208, v232
	s_waitcnt lgkmcnt(7)
	s_nop 1
	v_fmamk_f32 v163, v164, 0x3e38aa3b, v193
	v_fmamk_f32 v152, v165, 0x3e38aa3b, v192
	s_waitcnt lgkmcnt(6)
	v_fmamk_f32 v153, v166, 0x3e38aa3b, v195
	v_fmamk_f32 v150, v167, 0x3e38aa3b, v194
	s_waitcnt lgkmcnt(5)
	v_fmamk_f32 v149, v168, 0x3e38aa3b, v199
	v_fmamk_f32 v148, v169, 0x3e38aa3b, v198
	v_max3_f32 v151, v163, v152, v153
	s_waitcnt lgkmcnt(4)
	v_fmamk_f32 v164, v170, 0x3e38aa3b, v201
	v_fmamk_f32 v154, v171, 0x3e38aa3b, v200
	v_max3_f32 v155, v150, v149, v148
	v_max_f32_e32 v156, v164, v154
	v_max3_f32 v151, v156, v151, v155
	v_cndmask_b32_e64 v151, v151, v225, s[36:37]
	v_sub_f32_e32 v155, v188, v230
	v_add_f32_e32 v155, 0x41000000, v155
	v_cmp_gt_f32_e32 vcc, v151, v155
	s_cbranch_vccz .LBB0_478
	v_add_f32_e32 v151, v151, v230
	ds_bpermute_b32 v155, v233, v151
	v_max_f32_e32 v151, v151, v151
	v_mov_b32_e32 v157, v189
	s_waitcnt lgkmcnt(0)
	v_max_f32_e32 v155, v155, v155
	v_max_f32_e32 v151, v151, v155
	ds_bpermute_b32 v155, v234, v151
	s_waitcnt lgkmcnt(0)
	v_max3_f32 v156, v188, v151, v155
	v_sub_f32_e32 v151, v188, v156
	v_exp_f32_e32 v166, v151
	v_mov_b64_e32 v[188:189], v[156:157]
	v_mul_f32_e32 v190, v190, v166
	v_pk_mul_f32 v[18:19], v[18:19], v[166:167] op_sel_hi:[1,0]
	v_pk_mul_f32 v[16:17], v[16:17], v[166:167] op_sel_hi:[1,0]
	v_pk_mul_f32 v[26:27], v[26:27], v[166:167] op_sel_hi:[1,0]
	v_pk_mul_f32 v[24:25], v[24:25], v[166:167] op_sel_hi:[1,0]
	v_pk_mul_f32 v[34:35], v[34:35], v[166:167] op_sel_hi:[1,0]
	v_pk_mul_f32 v[32:33], v[32:33], v[166:167] op_sel_hi:[1,0]
	v_pk_mul_f32 v[42:43], v[42:43], v[166:167] op_sel_hi:[1,0]
	v_pk_mul_f32 v[40:41], v[40:41], v[166:167] op_sel_hi:[1,0]
	v_cmp_lt_f32_e32 vcc, 0xefa18f08, v156
	s_nop 1
	v_cndmask_b32_e32 v232, 0, v156, vcc
	v_sub_f32_e32 v230, v232, v230
	v_sub_f32_e32 v163, v163, v230
	v_sub_f32_e32 v152, v152, v230
	v_sub_f32_e32 v153, v153, v230
	v_sub_f32_e32 v150, v150, v230
	v_sub_f32_e32 v149, v149, v230
	v_sub_f32_e32 v148, v148, v230
	v_sub_f32_e32 v164, v164, v230
	v_sub_f32_e32 v154, v154, v230
	v_mov_b32_e32 v230, v232
	s_branch .LBB0_479
; __device__ __forceinline__ void kv_lwrite(const KVRegs& r, char* lds, int buf) {
;   const int tid = TIDX, row = tid >> 3, cq = tid & 7;
; template <int MODE>
; __device__ __forceinline__ void nsa_compute(int cur, int buf, int t, int hl, u64 mymask, const bf16x8 (&Qf)[2][2], f32x4 (&O)[4][2], float (&m)[2], float (&l)[2],
;                                             const float (&inv)[2], float* impw, char* lds) {
;     ...
;         const float mxa = fmaxf(fmaxf(sv[0][0], sv[0][1]), sv[0][2]), mxb = fmaxf(fmaxf(sv[0][3], sv[1][0]), sv[1][1]);
;         float mx = fmaxf(fmaxf(fmaxf(sv[1][2], sv[1][3]), mxa), mxb);
;         if (MODE == 2) mx = selok ? mx : -__builtin_inff();
;         if (__any(mx > m[r] + 8.0f)) {
;           mx = fmaxf(mx, __shfl_xor(mx, 16)); mx = fmaxf(mx, __shfl_xor(mx, 32));
;           const float mn = fmaxf(m[r], mx), al = __builtin_amdgcn_exp2f(m[r] - mn);
;           m[r] = mn; l[r] *= al;
;           if (MODE != 0) {
; #pragma unroll
;             for (int df = 0; df < 4; ++df) O[df][r] *= al;
;           }
;         }
;         const float me = (MODE == 2) ? (selok ? m[r] : __builtin_inff()) : m[r];
;         float ps = 0.f;
; #pragma unroll
;         for (int kk = 0; kk < 2; ++kk)
; #pragma unroll
;           for (int e = 0; e < 4; ++e) { pv[kk][e] = __builtin_amdgcn_exp2f(sv[kk][e] - me); ps += pv[kk][e]; }
;         l[r] += ps;
;       }
;       if (MODE != 0) {
;         const unsigned w0 = pk2(pv[0][0], pv[0][1]), w1 = pk2(pv[0][2], pv[0][3]), w2 = pk2(pv[1][0], pv[1][1]), w3 = pk2(pv[1][2], pv[1][3]);
;         u32x4 pw; pw.x = w0; pw.y = w1; pw.z = w2; pw.w = w3;
;         Pf[r] = __builtin_bit_cast(bf16x8, pw);
;       }
;     }
;     if (MODE != 0) {
;       bf16x8 vfr[4];
; #pragma unroll
;       for (int df = 0; df < 4; ++df) {
;         const bf16x4 va = *(const bf16x4*)(vt + (df * 16 + fr) * 68 + 32 * s2 + 4 * fq);
;         const bf16x4 vb = *(const bf16x4*)(vt + (df * 16 + fr) * 68 + 32 * s2 + 16 + 4 * fq);
;         bf16x8 vf; vf[0] = va[0]; vf[1] = va[1]; vf[2] = va[2]; vf[3] = va[3]; vf[4] = vb[0]; vf[5] = vb[1]; vf[6] = vb[2]; vf[7] = vb[3];
;         vfr[df] = vf;
;       }
;       __builtin_amdgcn_s_setprio(1);
; #pragma unroll
;       for (int df = 0; df < 4; ++df)
; #pragma unroll
;         for (int r = 0; r < 2; ++r) O[df][r] = mfma16(vfr[df], Pf[r], O[df][r]);
;       __builtin_amdgcn_s_setprio(0);
.LBB0_478:
.LBB0_479:
	v_exp_f32_e32 v151, v163
	v_exp_f32_e32 v152, v152
	v_exp_f32_e32 v153, v153
	v_exp_f32_e32 v150, v150
	v_add_f32_e32 v155, 0, v151
	v_add_f32_e32 v155, v152, v155
	v_add_f32_e32 v155, v153, v155
	v_add_f32_e32 v156, v150, v155
	v_exp_f32_e32 v155, v149
	s_nop 0
	v_add_f32_e32 v149, v155, v156
	v_exp_f32_e32 v156, v148
	s_nop 0
	v_add_f32_e32 v148, v156, v149
	v_exp_f32_e32 v157, v164
	v_exp_f32_e32 v154, v154
	v_add_f32_e32 v148, v157, v148
	v_add_f32_e32 v148, v154, v148
	v_add_f32_e32 v190, v190, v148
	s_waitcnt lgkmcnt(3)
	v_fmamk_f32 v149, v140, 0x3e38aa3b, v203
	v_fmamk_f32 v148, v141, 0x3e38aa3b, v202
	s_waitcnt lgkmcnt(2)
	v_fmamk_f32 v141, v142, 0x3e38aa3b, v205
	v_fmamk_f32 v140, v143, 0x3e38aa3b, v204
	s_waitcnt lgkmcnt(1)
	v_fmamk_f32 v143, v136, 0x3e38aa3b, v207
	v_fmamk_f32 v142, v137, 0x3e38aa3b, v206
	s_waitcnt lgkmcnt(0)
	v_fmamk_f32 v158, v138, 0x3e38aa3b, v209
	v_fmamk_f32 v136, v139, 0x3e38aa3b, v208
	v_max3_f32 v137, v149, v148, v141
	v_max3_f32 v138, v140, v143, v142
	v_max_f32_e32 v139, v158, v136
	v_max3_f32 v137, v139, v137, v138
	v_cndmask_b32_e64 v137, v137, v225, s[36:37]
	v_sub_f32_e32 v138, v189, v231
	v_add_f32_e32 v138, 0x41000000, v138
	v_cmp_gt_f32_e32 vcc, v137, v138
	s_cbranch_vccz .LBB0_481
	v_add_f32_e32 v137, v137, v231
	ds_bpermute_b32 v138, v233, v137
	v_max_f32_e32 v137, v137, v137
	s_waitcnt lgkmcnt(0)
	v_max_f32_e32 v138, v138, v138
	v_max_f32_e32 v137, v137, v138
	ds_bpermute_b32 v138, v234, v137
	s_waitcnt lgkmcnt(0)
	v_max3_f32 v137, v189, v137, v138
	v_sub_f32_e32 v138, v189, v137
	v_exp_f32_e32 v138, v138
	v_mov_b32_e32 v189, v137
	v_mul_f32_e32 v191, v191, v138
	v_pk_mul_f32 v[22:23], v[22:23], v[138:139] op_sel_hi:[1,0]
	v_pk_mul_f32 v[20:21], v[20:21], v[138:139] op_sel_hi:[1,0]
	v_pk_mul_f32 v[30:31], v[30:31], v[138:139] op_sel_hi:[1,0]
	v_pk_mul_f32 v[28:29], v[28:29], v[138:139] op_sel_hi:[1,0]
	v_pk_mul_f32 v[38:39], v[38:39], v[138:139] op_sel_hi:[1,0]
	v_pk_mul_f32 v[36:37], v[36:37], v[138:139] op_sel_hi:[1,0]
	v_pk_mul_f32 v[46:47], v[46:47], v[138:139] op_sel_hi:[1,0]
	v_pk_mul_f32 v[44:45], v[44:45], v[138:139] op_sel_hi:[1,0]
	v_cmp_lt_f32_e32 vcc, 0xefa18f08, v137
	s_nop 1
	v_cndmask_b32_e32 v232, 0, v137, vcc
	v_sub_f32_e32 v231, v232, v231
	v_sub_f32_e32 v149, v149, v231
	v_sub_f32_e32 v148, v148, v231
	v_sub_f32_e32 v141, v141, v231
	v_sub_f32_e32 v140, v140, v231
	v_sub_f32_e32 v143, v143, v231
	v_sub_f32_e32 v142, v142, v231
	v_sub_f32_e32 v158, v158, v231
	v_sub_f32_e32 v136, v136, v231
	v_mov_b32_e32 v231, v232
	s_branch .LBB0_482
.LBB0_481:
.LBB0_482:
	v_cvt_pk_bf16_f32 v164, v151, v152
	v_cvt_pk_bf16_f32 v165, v153, v150
	v_cvt_pk_bf16_f32 v166, v155, v156
	v_cvt_pk_bf16_f32 v167, v157, v154
	v_mov_b32_e32 v137, v149
	v_mov_b32_e32 v138, v148
	v_mov_b32_e32 v143, v158
	ds_read2_b64 v[148:151], v159 offset0:8 offset1:12
	ds_read2_b64 v[152:155], v160 offset0:24 offset1:28
	ds_read2_b64 v[156:159], v161 offset0:40 offset1:44
	ds_read2_b64 v[160:163], v162 offset0:56 offset1:60
	v_exp_f32_e32 v137, v137
	v_exp_f32_e32 v138, v138
	v_exp_f32_e32 v139, v141
	v_exp_f32_e32 v140, v140
	v_exp_f32_e32 v141, v143
	v_exp_f32_e32 v142, v142
	v_exp_f32_e32 v143, v143
	v_exp_f32_e32 v136, v136
	v_cvt_pk_bf16_f32 v168, v137, v138
	v_cvt_pk_bf16_f32 v169, v139, v140
	v_cvt_pk_bf16_f32 v170, v141, v142
	v_cvt_pk_bf16_f32 v171, v143, v136
	s_setprio 1
	s_waitcnt lgkmcnt(3)
	v_mfma_f32_16x16x32_bf16 v[16:19], v[148:151], v[164:167], v[16:19]
	v_mfma_f32_16x16x32_bf16 v[20:23], v[148:151], v[168:171], v[20:23]
	s_waitcnt lgkmcnt(2)
	v_mfma_f32_16x16x32_bf16 v[24:27], v[152:155], v[164:167], v[24:27]
	v_mfma_f32_16x16x32_bf16 v[28:31], v[152:155], v[168:171], v[28:31]
	s_waitcnt lgkmcnt(1)
	v_mfma_f32_16x16x32_bf16 v[32:35], v[156:159], v[164:167], v[32:35]
	v_mfma_f32_16x16x32_bf16 v[36:39], v[156:159], v[168:171], v[36:39]
	s_waitcnt lgkmcnt(0)
	v_mfma_f32_16x16x32_bf16 v[40:43], v[160:163], v[164:167], v[40:43]
	v_mfma_f32_16x16x32_bf16 v[44:47], v[160:163], v[168:171], v[44:47]
	s_setprio 0
	s_cmp_lt_i32 s75, 0
	s_cbranch_scc1 .LBB0_484
	v_mov_b32 v148, v179
	s_nop 0
	v_ashrrev_i32_e32 v149, 3, v148
	v_xor_b32_e32 v151, v149, v148
	v_lshlrev_b32_e32 v148, 3, v148
	v_lshlrev_b32_e32 v151, 4, v151
	v_and_b32_e32 v148, 56, v148
	v_lshlrev_b32_e32 v150, 7, v149
	v_and_b32_e32 v151, 0x70, v151
	v_mul_u32_u24_e32 v148, 0x88, v148
	v_lshlrev_b32_e32 v149, 1, v149
	v_add3_u32 v150, s72, v150, v151
	v_add3_u32 v148, s73, v148, v149
	s_waitcnt vmcnt(1)
	ds_write_b128 v150, v[48:51]
	s_waitcnt vmcnt(0)
	ds_write_b16 v148, v52 offset:16384
	ds_write_b16_d16_hi v148, v52 offset:16520
	ds_write_b16 v148, v53 offset:16656
	ds_write_b16_d16_hi v148, v53 offset:16792
	ds_write_b16 v148, v54 offset:16928
	ds_write_b16_d16_hi v148, v54 offset:17064
	ds_write_b16 v148, v55 offset:17200
	ds_write_b16_d16_hi v148, v55 offset:17336
